# fused GEMM epilogues: xor-16/32 lane exchanges on the VALU (v_permlane16/32_swap) instead of ds_bpermute round trips
# baseline (speedup 1.0000x reference)
.LBB0_295:
	v_and_b32_e32 v147, 64, v197
	v_xor_b32_e32 v146, 16, v197
	v_add_u32_e32 v147, 64, v147
	s_bfe_u32 s7, s0, 0x10006
	v_cmp_lt_i32_e32 vcc, v146, v147
	s_lshl_b32 s5, s7, 10
	s_add_i32 s5, s5, s19
	v_cndmask_b32_e32 v146, v197, v146, vcc
	v_lshlrev_b32_e32 v166, 2, v146
	v_xor_b32_e32 v146, 32, v197
	v_cmp_lt_i32_e32 vcc, v146, v147
	s_add_i32 s5, s5, 0
	v_add_u32_e32 v167, s5, v167
	v_cndmask_b32_e32 v146, v197, v146, vcc
	s_lshl_b32 s5, s18, 13
	v_and_b32_e32 v144, 63, v165
	v_lshlrev_b32_e32 v165, 2, v146
	v_lshlrev_b64 v[146:147], 11, v[158:159]
	s_and_b32 s6, s5, 0x4000
	v_lshl_add_u64 v[146:147], s[60:61], 0, v[146:147]
	s_or_b32 s10, s6, 0x10000
	v_lshl_add_u64 v[160:161], v[156:157], 1, v[146:147]
	v_add_u32_e32 v146, s10, v167
	ds_read_b128 v[168:171], v146
	s_lshl_b32 s4, s18, 2
	s_add_i32 s4, s4, 0
	s_add_i32 s4, s4, 0x20000
	v_cmp_gt_u32_e32 vcc, 16, v144
	s_waitcnt lgkmcnt(0)
	v_lshlrev_b32_e32 v146, 16, v168
	v_and_b32_e32 v147, 0xffff0000, v168
	v_lshlrev_b32_e32 v154, 16, v169
	v_and_b32_e32 v155, 0xffff0000, v169
	v_pk_fma_f32 v[138:139], v[138:139], 0.5, v[154:155] op_sel_hi:[1,0,1]
	v_pk_fma_f32 v[136:137], v[136:137], 0.5, v[146:147] op_sel_hi:[1,0,1]
	v_lshlrev_b32_e32 v146, 16, v170
	v_and_b32_e32 v147, 0xffff0000, v170
	v_lshlrev_b32_e32 v154, 16, v171
	v_and_b32_e32 v155, 0xffff0000, v171
	v_pk_fma_f32 v[154:155], v[134:135], 0.5, v[154:155] op_sel_hi:[1,0,1]
	v_pk_fma_f32 v[146:147], v[132:133], 0.5, v[146:147] op_sel_hi:[1,0,1]
	v_cvt_pk_bf16_f32 v132, v136, v137
	v_cvt_pk_bf16_f32 v133, v138, v139
	v_cvt_pk_bf16_f32 v134, v146, v147
	v_cvt_pk_bf16_f32 v135, v154, v155
	global_store_dwordx4 v[160:161], v[132:135], off
	s_nop 1
	v_mul_f32_e32 v132, v137, v137
	v_mul_f32_e32 v133, v139, v139
	v_fmac_f32_e32 v132, v136, v136
	v_fmac_f32_e32 v133, v138, v138
	v_add_f32_e32 v132, v132, v133
	v_mul_f32_e32 v133, v147, v147
	v_mul_f32_e32 v134, v155, v155
	v_fmac_f32_e32 v133, v146, v146
	v_fmac_f32_e32 v134, v154, v154
	v_add_f32_e32 v133, v133, v134
	v_add_f32_e32 v138, v132, v133
	v_add_u32_e32 v132, s6, v167
	ds_read_b128 v[132:135], v132
	s_waitcnt lgkmcnt(0)
	v_lshlrev_b32_e32 v136, 16, v132
	v_and_b32_e32 v137, 0xffff0000, v132
	v_lshlrev_b32_e32 v132, 16, v133
	v_and_b32_e32 v133, 0xffff0000, v133
	v_pk_fma_f32 v[126:127], v[126:127], 0.5, v[132:133] op_sel_hi:[1,0,1]
	v_lshlrev_b32_e32 v132, 16, v134
	v_and_b32_e32 v133, 0xffff0000, v134
	v_lshlrev_b32_e32 v134, 16, v135
	v_and_b32_e32 v135, 0xffff0000, v135
	v_pk_fma_f32 v[124:125], v[124:125], 0.5, v[136:137] op_sel_hi:[1,0,1]
	v_pk_fma_f32 v[134:135], v[122:123], 0.5, v[134:135] op_sel_hi:[1,0,1]
	v_pk_fma_f32 v[132:133], v[120:121], 0.5, v[132:133] op_sel_hi:[1,0,1]
	v_cvt_pk_bf16_f32 v120, v124, v125
	v_cvt_pk_bf16_f32 v121, v126, v127
	v_cvt_pk_bf16_f32 v122, v132, v133
	v_cvt_pk_bf16_f32 v123, v134, v135
	global_store_dwordx4 v[160:161], v[120:123], off offset:256
	s_nop 1
	v_mul_f32_e32 v120, v125, v125
	v_mul_f32_e32 v121, v127, v127
	v_fmac_f32_e32 v120, v124, v124
	v_fmac_f32_e32 v121, v126, v126
	v_add_f32_e32 v120, v120, v121
	v_mul_f32_e32 v121, v133, v133
	v_mul_f32_e32 v122, v135, v135
	v_fmac_f32_e32 v121, v132, v132
	v_fmac_f32_e32 v122, v134, v134
	v_add_f32_e32 v121, v121, v122
	v_add_f32_e32 v120, v120, v121
	v_add_f32_e32 v120, v138, v120
	v_mov_b32_e32 v121, v120
	s_nop 1
	v_permlane16_swap_b32_e32 v120, v121
	v_lshl_add_u32 v122, v164, 4, s4
	s_waitcnt lgkmcnt(0)
	v_add_f32_e32 v120, v120, v121
	v_mov_b32_e32 v121, v120
	s_nop 1
	v_permlane32_swap_b32_e32 v120, v121
	s_and_saveexec_b64 s[4:5], vcc
	s_cbranch_execz .LBB0_297
	s_waitcnt lgkmcnt(0)
	v_add_f32_e32 v120, v120, v121
	ds_write_b32 v122, v120
.LBB0_297:
	s_or_b64 exec, exec, s[4:5]
	s_or_b32 s4, s13, 16
	v_or_b32_e32 v123, s4, v162
	s_lshr_b32 s4, s4, 3
	s_or_b32 s4, s4, s7
	v_lshlrev_b32_e32 v124, 6, v123
	s_movk_i32 s5, 0x3c0
	s_lshl_b32 s4, s4, 10
	v_lshlrev_b32_e32 v123, 2, v123
	v_and_or_b32 v124, v124, s5, v163
	v_and_b32_e32 v123, 32, v123
	s_add_i32 s4, s4, 0
	v_xad_u32 v123, v124, v123, s4
	v_add_u32_e32 v124, s10, v123
	ds_read_b128 v[124:127], v124
	v_or_b32_e32 v120, 16, v158
	s_waitcnt lgkmcnt(0)
	v_ashrrev_i32_e32 v121, 31, v120
	v_lshlrev_b64 v[120:121], 11, v[120:121]
	v_lshl_add_u64 v[120:121], s[60:61], 0, v[120:121]
	v_lshlrev_b32_e32 v132, 16, v124
	v_and_b32_e32 v133, 0xffff0000, v124
	v_lshlrev_b32_e32 v124, 16, v125
	v_and_b32_e32 v125, 0xffff0000, v125
	v_pk_fma_f32 v[118:119], v[118:119], 0.5, v[124:125] op_sel_hi:[1,0,1]
	v_lshlrev_b32_e32 v124, 16, v126
	v_and_b32_e32 v125, 0xffff0000, v126
	v_lshlrev_b32_e32 v126, 16, v127
	v_and_b32_e32 v127, 0xffff0000, v127
	v_pk_fma_f32 v[116:117], v[116:117], 0.5, v[132:133] op_sel_hi:[1,0,1]
	v_pk_fma_f32 v[126:127], v[114:115], 0.5, v[126:127] op_sel_hi:[1,0,1]
	v_pk_fma_f32 v[124:125], v[112:113], 0.5, v[124:125] op_sel_hi:[1,0,1]
	v_lshl_add_u64 v[120:121], v[156:157], 1, v[120:121]
	v_cvt_pk_bf16_f32 v112, v116, v117
	v_cvt_pk_bf16_f32 v113, v118, v119
	v_cvt_pk_bf16_f32 v114, v124, v125
	v_cvt_pk_bf16_f32 v115, v126, v127
	global_store_dwordx4 v[120:121], v[112:115], off
	s_nop 1
	v_mul_f32_e32 v112, v117, v117
	v_mul_f32_e32 v113, v119, v119
	v_fmac_f32_e32 v112, v116, v116
	v_fmac_f32_e32 v113, v118, v118
	v_add_f32_e32 v112, v112, v113
	v_mul_f32_e32 v113, v125, v125
	v_mul_f32_e32 v114, v127, v127
	v_fmac_f32_e32 v113, v124, v124
	v_fmac_f32_e32 v114, v126, v126
	v_add_f32_e32 v113, v113, v114
	v_add_f32_e32 v118, v112, v113
	v_add_u32_e32 v112, s6, v123
	ds_read_b128 v[112:115], v112
	s_waitcnt lgkmcnt(0)
	v_lshlrev_b32_e32 v116, 16, v112
	v_and_b32_e32 v117, 0xffff0000, v112
	v_lshlrev_b32_e32 v112, 16, v113
	v_and_b32_e32 v113, 0xffff0000, v113
	v_pk_fma_f32 v[106:107], v[106:107], 0.5, v[112:113] op_sel_hi:[1,0,1]
	v_lshlrev_b32_e32 v112, 16, v114
	v_and_b32_e32 v113, 0xffff0000, v114
	v_lshlrev_b32_e32 v114, 16, v115
	v_and_b32_e32 v115, 0xffff0000, v115
	v_pk_fma_f32 v[104:105], v[104:105], 0.5, v[116:117] op_sel_hi:[1,0,1]
	v_pk_fma_f32 v[114:115], v[102:103], 0.5, v[114:115] op_sel_hi:[1,0,1]
	v_pk_fma_f32 v[112:113], v[100:101], 0.5, v[112:113] op_sel_hi:[1,0,1]
	v_cvt_pk_bf16_f32 v100, v104, v105
	v_cvt_pk_bf16_f32 v101, v106, v107
	v_cvt_pk_bf16_f32 v102, v112, v113
	v_cvt_pk_bf16_f32 v103, v114, v115
	global_store_dwordx4 v[120:121], v[100:103], off offset:256
	s_nop 1
	v_mul_f32_e32 v100, v105, v105
	v_mul_f32_e32 v101, v107, v107
	v_fmac_f32_e32 v100, v104, v104
	v_fmac_f32_e32 v101, v106, v106
	v_add_f32_e32 v100, v100, v101
	v_mul_f32_e32 v101, v113, v113
	v_mul_f32_e32 v102, v115, v115
	v_fmac_f32_e32 v101, v112, v112
	v_fmac_f32_e32 v102, v114, v114
	v_add_f32_e32 v101, v101, v102
	v_add_f32_e32 v100, v100, v101
	v_add_f32_e32 v100, v118, v100
	v_mov_b32_e32 v101, v100
	s_nop 1
	v_permlane16_swap_b32_e32 v100, v101
	s_waitcnt lgkmcnt(0)
	v_add_f32_e32 v100, v100, v101
	v_mov_b32_e32 v101, v100
	s_nop 1
	v_permlane32_swap_b32_e32 v100, v101
	s_and_saveexec_b64 s[4:5], vcc
	s_cbranch_execz .LBB0_299
	s_waitcnt lgkmcnt(0)
	v_add_f32_e32 v100, v100, v101
	ds_write_b32 v122, v100 offset:256
.LBB0_299:
	s_or_b64 exec, exec, s[4:5]
	s_or_b32 s4, s13, 32
	v_or_b32_e32 v102, s4, v162
	s_lshr_b32 s4, s4, 3
	s_or_b32 s4, s4, s7
	v_lshlrev_b32_e32 v103, 6, v102
	s_movk_i32 s5, 0x3c0
	s_lshl_b32 s4, s4, 10
	v_lshlrev_b32_e32 v102, 2, v102
	v_and_or_b32 v103, v103, s5, v163
	v_and_b32_e32 v102, 32, v102
	s_add_i32 s4, s4, 0
	v_xad_u32 v102, v103, v102, s4
	v_add_u32_e32 v103, s10, v102
	ds_read_b128 v[104:107], v103
	v_or_b32_e32 v100, 32, v158
	s_waitcnt lgkmcnt(0)
	v_ashrrev_i32_e32 v101, 31, v100
	v_lshlrev_b64 v[100:101], 11, v[100:101]
	v_lshl_add_u64 v[100:101], s[60:61], 0, v[100:101]
	v_lshlrev_b32_e32 v112, 16, v104
	v_and_b32_e32 v113, 0xffff0000, v104
	v_lshlrev_b32_e32 v104, 16, v105
	v_and_b32_e32 v105, 0xffff0000, v105
	v_pk_fma_f32 v[98:99], v[98:99], 0.5, v[104:105] op_sel_hi:[1,0,1]
	v_lshlrev_b32_e32 v104, 16, v106
	v_and_b32_e32 v105, 0xffff0000, v106
	v_lshlrev_b32_e32 v106, 16, v107
	v_and_b32_e32 v107, 0xffff0000, v107
	v_pk_fma_f32 v[96:97], v[96:97], 0.5, v[112:113] op_sel_hi:[1,0,1]
	v_pk_fma_f32 v[106:107], v[94:95], 0.5, v[106:107] op_sel_hi:[1,0,1]
	v_pk_fma_f32 v[104:105], v[92:93], 0.5, v[104:105] op_sel_hi:[1,0,1]
	v_lshl_add_u64 v[100:101], v[156:157], 1, v[100:101]
	v_cvt_pk_bf16_f32 v92, v96, v97
	v_cvt_pk_bf16_f32 v93, v98, v99
	v_cvt_pk_bf16_f32 v94, v104, v105
	v_cvt_pk_bf16_f32 v95, v106, v107
	global_store_dwordx4 v[100:101], v[92:95], off
	s_nop 1
	v_mul_f32_e32 v92, v97, v97
	v_mul_f32_e32 v93, v99, v99
	v_fmac_f32_e32 v92, v96, v96
	v_fmac_f32_e32 v93, v98, v98
	v_add_f32_e32 v92, v92, v93
	v_mul_f32_e32 v93, v105, v105
	v_mul_f32_e32 v94, v107, v107
	v_fmac_f32_e32 v93, v104, v104
	v_fmac_f32_e32 v94, v106, v106
	v_add_f32_e32 v93, v93, v94
	v_add_f32_e32 v98, v92, v93
	v_add_u32_e32 v92, s6, v102
	ds_read_b128 v[92:95], v92
	s_waitcnt lgkmcnt(0)
	v_lshlrev_b32_e32 v96, 16, v92
	v_and_b32_e32 v97, 0xffff0000, v92
	v_lshlrev_b32_e32 v92, 16, v93
	v_and_b32_e32 v93, 0xffff0000, v93
	v_pk_fma_f32 v[86:87], v[86:87], 0.5, v[92:93] op_sel_hi:[1,0,1]
	v_lshlrev_b32_e32 v92, 16, v94
	v_and_b32_e32 v93, 0xffff0000, v94
	v_lshlrev_b32_e32 v94, 16, v95
	v_and_b32_e32 v95, 0xffff0000, v95
	v_pk_fma_f32 v[84:85], v[84:85], 0.5, v[96:97] op_sel_hi:[1,0,1]
	v_pk_fma_f32 v[94:95], v[82:83], 0.5, v[94:95] op_sel_hi:[1,0,1]
	v_pk_fma_f32 v[92:93], v[80:81], 0.5, v[92:93] op_sel_hi:[1,0,1]
	v_cvt_pk_bf16_f32 v80, v84, v85
	v_cvt_pk_bf16_f32 v81, v86, v87
	v_cvt_pk_bf16_f32 v82, v92, v93
	v_cvt_pk_bf16_f32 v83, v94, v95
	global_store_dwordx4 v[100:101], v[80:83], off offset:256
	s_nop 1
	v_mul_f32_e32 v80, v85, v85
	v_mul_f32_e32 v81, v87, v87
	v_fmac_f32_e32 v80, v84, v84
	v_fmac_f32_e32 v81, v86, v86
	v_add_f32_e32 v80, v80, v81
	v_mul_f32_e32 v81, v93, v93
	v_mul_f32_e32 v82, v95, v95
	v_fmac_f32_e32 v81, v92, v92
	v_fmac_f32_e32 v82, v94, v94
	v_add_f32_e32 v81, v81, v82
	v_add_f32_e32 v80, v80, v81
	v_add_f32_e32 v80, v98, v80
	v_mov_b32_e32 v81, v80
	s_nop 1
	v_permlane16_swap_b32_e32 v80, v81
	s_waitcnt lgkmcnt(0)
	v_add_f32_e32 v80, v80, v81
	v_mov_b32_e32 v81, v80
	s_nop 1
	v_permlane32_swap_b32_e32 v80, v81
	s_and_saveexec_b64 s[4:5], vcc
	s_cbranch_execz .LBB0_301
	s_waitcnt lgkmcnt(0)
	v_add_f32_e32 v80, v80, v81
	ds_write_b32 v122, v80 offset:512
.LBB0_301:
	s_or_b64 exec, exec, s[4:5]
	s_or_b32 s4, s13, 48
	v_or_b32_e32 v82, s4, v162
	s_lshr_b32 s4, s4, 3
	s_or_b32 s4, s4, s7
	v_lshlrev_b32_e32 v83, 6, v82
	s_movk_i32 s5, 0x3c0
	s_lshl_b32 s4, s4, 10
	v_lshlrev_b32_e32 v82, 2, v82
	v_and_or_b32 v83, v83, s5, v163
	v_and_b32_e32 v82, 32, v82
	s_add_i32 s4, s4, 0
	v_xad_u32 v82, v83, v82, s4
	v_add_u32_e32 v83, s10, v82
	ds_read_b128 v[84:87], v83
	v_or_b32_e32 v80, 48, v158
	s_waitcnt lgkmcnt(0)
	v_ashrrev_i32_e32 v81, 31, v80
	v_lshlrev_b64 v[80:81], 11, v[80:81]
	v_lshl_add_u64 v[80:81], s[60:61], 0, v[80:81]
	v_lshlrev_b32_e32 v92, 16, v84
	v_and_b32_e32 v93, 0xffff0000, v84
	v_lshlrev_b32_e32 v84, 16, v85
	v_and_b32_e32 v85, 0xffff0000, v85
	v_pk_fma_f32 v[78:79], v[78:79], 0.5, v[84:85] op_sel_hi:[1,0,1]
	v_lshlrev_b32_e32 v84, 16, v86
	v_and_b32_e32 v85, 0xffff0000, v86
	v_lshlrev_b32_e32 v86, 16, v87
	v_and_b32_e32 v87, 0xffff0000, v87
	v_pk_fma_f32 v[76:77], v[76:77], 0.5, v[92:93] op_sel_hi:[1,0,1]
	v_pk_fma_f32 v[86:87], v[74:75], 0.5, v[86:87] op_sel_hi:[1,0,1]
	v_pk_fma_f32 v[84:85], v[72:73], 0.5, v[84:85] op_sel_hi:[1,0,1]
	v_lshl_add_u64 v[80:81], v[156:157], 1, v[80:81]
	v_cvt_pk_bf16_f32 v72, v76, v77
	v_cvt_pk_bf16_f32 v73, v78, v79
	v_cvt_pk_bf16_f32 v74, v84, v85
	v_cvt_pk_bf16_f32 v75, v86, v87
	global_store_dwordx4 v[80:81], v[72:75], off
	s_nop 1
	v_mul_f32_e32 v72, v77, v77
	v_mul_f32_e32 v73, v79, v79
	v_fmac_f32_e32 v72, v76, v76
	v_fmac_f32_e32 v73, v78, v78
	v_add_f32_e32 v72, v72, v73
	v_mul_f32_e32 v73, v85, v85
	v_mul_f32_e32 v74, v87, v87
	v_fmac_f32_e32 v73, v84, v84
	v_fmac_f32_e32 v74, v86, v86
	v_add_f32_e32 v73, v73, v74
	v_add_f32_e32 v78, v72, v73
	v_add_u32_e32 v72, s6, v82
	ds_read_b128 v[72:75], v72
	s_waitcnt lgkmcnt(0)
	v_lshlrev_b32_e32 v76, 16, v72
	v_and_b32_e32 v77, 0xffff0000, v72
	v_lshlrev_b32_e32 v72, 16, v73
	v_and_b32_e32 v73, 0xffff0000, v73
	v_pk_fma_f32 v[70:71], v[70:71], 0.5, v[72:73] op_sel_hi:[1,0,1]
	v_lshlrev_b32_e32 v72, 16, v74
	v_and_b32_e32 v73, 0xffff0000, v74
	v_lshlrev_b32_e32 v74, 16, v75
	v_and_b32_e32 v75, 0xffff0000, v75
	v_pk_fma_f32 v[68:69], v[68:69], 0.5, v[76:77] op_sel_hi:[1,0,1]
	v_pk_fma_f32 v[74:75], v[66:67], 0.5, v[74:75] op_sel_hi:[1,0,1]
	v_pk_fma_f32 v[72:73], v[64:65], 0.5, v[72:73] op_sel_hi:[1,0,1]
	v_cvt_pk_bf16_f32 v64, v68, v69
	v_cvt_pk_bf16_f32 v65, v70, v71
	v_cvt_pk_bf16_f32 v66, v72, v73
	v_cvt_pk_bf16_f32 v67, v74, v75
	global_store_dwordx4 v[80:81], v[64:67], off offset:256
	s_nop 1
	v_mul_f32_e32 v64, v69, v69
	v_mul_f32_e32 v65, v71, v71
	v_fmac_f32_e32 v64, v68, v68
	v_fmac_f32_e32 v65, v70, v70
	v_add_f32_e32 v64, v64, v65
	v_mul_f32_e32 v65, v73, v73
	v_mul_f32_e32 v66, v75, v75
	v_fmac_f32_e32 v65, v72, v72
	v_fmac_f32_e32 v66, v74, v74
	v_add_f32_e32 v65, v65, v66
	v_add_f32_e32 v64, v64, v65
	v_add_f32_e32 v64, v78, v64
	v_mov_b32_e32 v65, v64
	s_nop 1
	v_permlane16_swap_b32_e32 v64, v65
	s_waitcnt lgkmcnt(0)
	v_add_f32_e32 v64, v64, v65
	v_mov_b32_e32 v65, v64
	s_nop 1
	v_permlane32_swap_b32_e32 v64, v65
	s_and_saveexec_b64 s[4:5], vcc
	s_cbranch_execz .LBB0_303
	s_waitcnt lgkmcnt(0)
	v_add_f32_e32 v64, v64, v65
	ds_write_b32 v122, v64 offset:768
.LBB0_303:
	s_or_b64 exec, exec, s[4:5]
	s_or_b32 s6, s6, 0x18000
	v_add_u32_e32 v68, s6, v167
	ds_read_b128 v[68:71], v68
	s_waitcnt lgkmcnt(0)
	v_lshlrev_b64 v[64:65], 11, v[158:159]
	v_lshl_add_u64 v[64:65], s[60:61], 0, v[64:65]
	v_lshl_add_u64 v[64:65], v[156:157], 1, v[64:65]
	s_mov_b32 s4, 0x40000
	v_lshlrev_b32_e32 v72, 16, v68
	v_and_b32_e32 v73, 0xffff0000, v68
	v_lshlrev_b32_e32 v68, 16, v69
	v_and_b32_e32 v69, 0xffff0000, v69
	v_pk_fma_f32 v[62:63], v[62:63], 0.5, v[68:69] op_sel_hi:[1,0,1]
	v_lshlrev_b32_e32 v68, 16, v70
	v_and_b32_e32 v69, 0xffff0000, v70
	v_lshlrev_b32_e32 v70, 16, v71
	v_and_b32_e32 v71, 0xffff0000, v71
	v_pk_fma_f32 v[60:61], v[60:61], 0.5, v[72:73] op_sel_hi:[1,0,1]
	v_pk_fma_f32 v[70:71], v[58:59], 0.5, v[70:71] op_sel_hi:[1,0,1]
	v_pk_fma_f32 v[68:69], v[56:57], 0.5, v[68:69] op_sel_hi:[1,0,1]
	v_add_co_u32_e64 v72, s[38:39], s4, v64
	v_cvt_pk_bf16_f32 v56, v60, v61
	v_cvt_pk_bf16_f32 v57, v62, v63
	v_cvt_pk_bf16_f32 v58, v68, v69
	v_cvt_pk_bf16_f32 v59, v70, v71
	v_addc_co_u32_e64 v73, s[38:39], 0, v65, s[38:39]
	global_store_dwordx4 v[72:73], v[56:59], off
	v_lshl_add_u64 v[66:67], v[64:65], 0, s[62:63]
	s_nop 0
	v_mul_f32_e32 v56, v61, v61
	v_mul_f32_e32 v57, v63, v63
	v_fmac_f32_e32 v56, v60, v60
	v_fmac_f32_e32 v57, v62, v62
	v_add_f32_e32 v56, v56, v57
	v_mul_f32_e32 v57, v69, v69
	v_mul_f32_e32 v58, v71, v71
	v_fmac_f32_e32 v57, v68, v68
	v_fmac_f32_e32 v58, v70, v70
	v_add_f32_e32 v57, v57, v58
	v_add_f32_e32 v60, v56, v57
	ds_read_b128 v[56:59], v167 offset:32768
	s_waitcnt vmcnt(0) lgkmcnt(0)
	v_cndmask_b32_e64 v61, v59, v143, s[36:37]
	v_cndmask_b32_e64 v59, v57, v141, s[36:37]
	v_cndmask_b32_e64 v57, v56, v140, s[36:37]
	v_cndmask_b32_e64 v62, v58, v142, s[36:37]
	v_lshlrev_b32_e32 v56, 16, v57
	v_and_b32_e32 v57, 0xffff0000, v57
	v_lshlrev_b32_e32 v58, 16, v59
	v_and_b32_e32 v59, 0xffff0000, v59
	v_pk_fma_f32 v[54:55], v[54:55], 0.5, v[58:59] op_sel_hi:[1,0,1]
	v_pk_fma_f32 v[52:53], v[52:53], 0.5, v[56:57] op_sel_hi:[1,0,1]
	v_lshlrev_b32_e32 v56, 16, v62
	v_and_b32_e32 v57, 0xffff0000, v62
	v_lshlrev_b32_e32 v58, 16, v61
	v_and_b32_e32 v59, 0xffff0000, v61
	v_pk_fma_f32 v[58:59], v[50:51], 0.5, v[58:59] op_sel_hi:[1,0,1]
	v_pk_fma_f32 v[56:57], v[48:49], 0.5, v[56:57] op_sel_hi:[1,0,1]
	v_cvt_pk_bf16_f32 v48, v52, v53
	v_cvt_pk_bf16_f32 v49, v54, v55
	v_cvt_pk_bf16_f32 v50, v56, v57
	v_cvt_pk_bf16_f32 v51, v58, v59
	global_store_dwordx4 v[66:67], v[48:51], off offset:256
	s_nop 1
	v_mul_f32_e32 v48, v53, v53
	v_mul_f32_e32 v49, v55, v55
	v_fmac_f32_e32 v48, v52, v52
	v_fmac_f32_e32 v49, v54, v54
	v_add_f32_e32 v48, v48, v49
	v_mul_f32_e32 v49, v57, v57
	v_mul_f32_e32 v50, v59, v59
	v_fmac_f32_e32 v49, v56, v56
	v_fmac_f32_e32 v50, v58, v58
	v_add_f32_e32 v49, v49, v50
	v_add_f32_e32 v48, v48, v49
	v_add_f32_e32 v48, v60, v48
	v_mov_b32_e32 v49, v48
	s_nop 1
	v_permlane16_swap_b32_e32 v48, v49
	s_waitcnt lgkmcnt(0)
	v_add_f32_e32 v48, v48, v49
	v_mov_b32_e32 v49, v48
	s_nop 1
	v_permlane32_swap_b32_e32 v48, v49
	s_and_saveexec_b64 s[4:5], vcc
	s_cbranch_execz .LBB0_305
	s_waitcnt lgkmcnt(0)
	v_add_f32_e32 v48, v48, v49
	ds_write_b32 v122, v48 offset:2048
.LBB0_305:
	s_or_b64 exec, exec, s[4:5]
	v_add_u32_e32 v50, s6, v123
	ds_read_b128 v[50:53], v50
	s_mov_b32 s4, 0x48000
	s_waitcnt lgkmcnt(0)
	v_lshl_add_u64 v[48:49], v[64:65], 0, s[76:77]
	s_waitcnt lgkmcnt(0)
	v_lshlrev_b32_e32 v54, 16, v50
	v_and_b32_e32 v55, 0xffff0000, v50
	v_lshlrev_b32_e32 v50, 16, v51
	v_and_b32_e32 v51, 0xffff0000, v51
	v_pk_fma_f32 v[46:47], v[46:47], 0.5, v[50:51] op_sel_hi:[1,0,1]
	v_lshlrev_b32_e32 v50, 16, v52
	v_and_b32_e32 v51, 0xffff0000, v52
	v_lshlrev_b32_e32 v52, 16, v53
	v_and_b32_e32 v53, 0xffff0000, v53
	v_pk_fma_f32 v[44:45], v[44:45], 0.5, v[54:55] op_sel_hi:[1,0,1]
	v_pk_fma_f32 v[52:53], v[42:43], 0.5, v[52:53] op_sel_hi:[1,0,1]
	v_pk_fma_f32 v[50:51], v[40:41], 0.5, v[50:51] op_sel_hi:[1,0,1]
	v_add_co_u32_e64 v54, s[38:39], s4, v64
	v_cvt_pk_bf16_f32 v40, v44, v45
	v_cvt_pk_bf16_f32 v41, v46, v47
	v_cvt_pk_bf16_f32 v42, v50, v51
	v_cvt_pk_bf16_f32 v43, v52, v53
	v_addc_co_u32_e64 v55, s[38:39], 0, v65, s[38:39]
	global_store_dwordx4 v[54:55], v[40:43], off
	s_nop 1
	v_mul_f32_e32 v40, v45, v45
	v_mul_f32_e32 v41, v47, v47
	v_fmac_f32_e32 v40, v44, v44
	v_fmac_f32_e32 v41, v46, v46
	v_add_f32_e32 v40, v40, v41
	v_mul_f32_e32 v41, v51, v51
	v_mul_f32_e32 v42, v53, v53
	v_fmac_f32_e32 v41, v50, v50
	v_fmac_f32_e32 v42, v52, v52
	v_add_f32_e32 v41, v41, v42
	v_add_f32_e32 v44, v40, v41
	ds_read_b128 v[40:43], v123 offset:32768
	s_waitcnt lgkmcnt(0)
	v_cndmask_b32_e64 v45, v43, v131, s[36:37]
	v_cndmask_b32_e64 v43, v41, v129, s[36:37]
	v_cndmask_b32_e64 v41, v40, v128, s[36:37]
	v_cndmask_b32_e64 v46, v42, v130, s[36:37]
	v_lshlrev_b32_e32 v40, 16, v41
	v_and_b32_e32 v41, 0xffff0000, v41
	v_lshlrev_b32_e32 v42, 16, v43
	v_and_b32_e32 v43, 0xffff0000, v43
	v_pk_fma_f32 v[38:39], v[38:39], 0.5, v[42:43] op_sel_hi:[1,0,1]
	v_pk_fma_f32 v[36:37], v[36:37], 0.5, v[40:41] op_sel_hi:[1,0,1]
	v_lshlrev_b32_e32 v40, 16, v46
	v_and_b32_e32 v41, 0xffff0000, v46
	v_lshlrev_b32_e32 v42, 16, v45
	v_and_b32_e32 v43, 0xffff0000, v45
	v_pk_fma_f32 v[42:43], v[34:35], 0.5, v[42:43] op_sel_hi:[1,0,1]
	v_pk_fma_f32 v[40:41], v[32:33], 0.5, v[40:41] op_sel_hi:[1,0,1]
	v_cvt_pk_bf16_f32 v32, v36, v37
	v_cvt_pk_bf16_f32 v33, v38, v39
	v_cvt_pk_bf16_f32 v34, v40, v41
	v_cvt_pk_bf16_f32 v35, v42, v43
	global_store_dwordx4 v[48:49], v[32:35], off offset:256
	s_nop 1
	v_mul_f32_e32 v32, v37, v37
	v_mul_f32_e32 v33, v39, v39
	v_fmac_f32_e32 v32, v36, v36
	v_fmac_f32_e32 v33, v38, v38
	v_add_f32_e32 v32, v32, v33
	v_mul_f32_e32 v33, v41, v41
	v_mul_f32_e32 v34, v43, v43
	v_fmac_f32_e32 v33, v40, v40
	v_fmac_f32_e32 v34, v42, v42
	v_add_f32_e32 v33, v33, v34
	v_add_f32_e32 v32, v32, v33
	v_add_f32_e32 v32, v44, v32
	v_mov_b32_e32 v33, v32
	s_nop 1
	v_permlane16_swap_b32_e32 v32, v33
	s_waitcnt lgkmcnt(0)
	v_add_f32_e32 v32, v32, v33
	v_mov_b32_e32 v33, v32
	s_nop 1
	v_permlane32_swap_b32_e32 v32, v33
	s_and_saveexec_b64 s[4:5], vcc
	s_cbranch_execz .LBB0_307
	s_waitcnt lgkmcnt(0)
	v_add_f32_e32 v32, v32, v33
	ds_write_b32 v122, v32 offset:2304
.LBB0_307:
	s_or_b64 exec, exec, s[4:5]
	v_add_u32_e32 v36, s6, v102
	ds_read_b128 v[36:39], v36
	s_waitcnt lgkmcnt(0)
	v_lshlrev_b64 v[32:33], 11, v[158:159]
	v_lshl_add_u64 v[32:33], s[60:61], 0, v[32:33]
	v_lshl_add_u64 v[32:33], v[156:157], 1, v[32:33]
	s_mov_b32 s4, 0x50000
	s_waitcnt lgkmcnt(0)
	v_lshlrev_b32_e32 v40, 16, v36
	v_and_b32_e32 v41, 0xffff0000, v36
	v_lshlrev_b32_e32 v36, 16, v37
	v_and_b32_e32 v37, 0xffff0000, v37
	v_pk_fma_f32 v[30:31], v[30:31], 0.5, v[36:37] op_sel_hi:[1,0,1]
	v_lshlrev_b32_e32 v36, 16, v38
	v_and_b32_e32 v37, 0xffff0000, v38
	v_lshlrev_b32_e32 v38, 16, v39
	v_and_b32_e32 v39, 0xffff0000, v39
	v_pk_fma_f32 v[28:29], v[28:29], 0.5, v[40:41] op_sel_hi:[1,0,1]
	v_pk_fma_f32 v[38:39], v[26:27], 0.5, v[38:39] op_sel_hi:[1,0,1]
	v_pk_fma_f32 v[36:37], v[24:25], 0.5, v[36:37] op_sel_hi:[1,0,1]
	v_add_co_u32_e64 v40, s[38:39], s4, v32
	v_cvt_pk_bf16_f32 v24, v28, v29
	v_cvt_pk_bf16_f32 v25, v30, v31
	v_cvt_pk_bf16_f32 v26, v36, v37
	v_cvt_pk_bf16_f32 v27, v38, v39
	v_addc_co_u32_e64 v41, s[38:39], 0, v33, s[38:39]
	global_store_dwordx4 v[40:41], v[24:27], off
	v_lshl_add_u64 v[34:35], v[32:33], 0, s[78:79]
	s_nop 0
	v_mul_f32_e32 v24, v29, v29
	v_mul_f32_e32 v25, v31, v31
	v_fmac_f32_e32 v24, v28, v28
	v_fmac_f32_e32 v25, v30, v30
	v_add_f32_e32 v24, v24, v25
	v_mul_f32_e32 v25, v37, v37
	v_mul_f32_e32 v26, v39, v39
	v_fmac_f32_e32 v25, v36, v36
	v_fmac_f32_e32 v26, v38, v38
	v_add_f32_e32 v25, v25, v26
	v_add_f32_e32 v28, v24, v25
	ds_read_b128 v[24:27], v102 offset:32768
	s_waitcnt lgkmcnt(0)
	v_cndmask_b32_e64 v29, v27, v111, s[36:37]
	v_cndmask_b32_e64 v27, v25, v109, s[36:37]
	v_cndmask_b32_e64 v25, v24, v108, s[36:37]
	v_cndmask_b32_e64 v30, v26, v110, s[36:37]
	v_lshlrev_b32_e32 v24, 16, v25
	v_and_b32_e32 v25, 0xffff0000, v25
	v_lshlrev_b32_e32 v26, 16, v27
	v_and_b32_e32 v27, 0xffff0000, v27
	v_pk_fma_f32 v[14:15], v[14:15], 0.5, v[26:27] op_sel_hi:[1,0,1]
	v_pk_fma_f32 v[12:13], v[12:13], 0.5, v[24:25] op_sel_hi:[1,0,1]
	v_lshlrev_b32_e32 v24, 16, v30
	v_and_b32_e32 v25, 0xffff0000, v30
	v_lshlrev_b32_e32 v26, 16, v29
	v_and_b32_e32 v27, 0xffff0000, v29
	v_pk_fma_f32 v[26:27], v[10:11], 0.5, v[26:27] op_sel_hi:[1,0,1]
	v_pk_fma_f32 v[24:25], v[8:9], 0.5, v[24:25] op_sel_hi:[1,0,1]
	v_cvt_pk_bf16_f32 v8, v12, v13
	v_cvt_pk_bf16_f32 v9, v14, v15
	v_cvt_pk_bf16_f32 v10, v24, v25
	v_cvt_pk_bf16_f32 v11, v26, v27
	global_store_dwordx4 v[34:35], v[8:11], off offset:256
	s_nop 1
	v_mul_f32_e32 v8, v13, v13
	v_mul_f32_e32 v9, v15, v15
	v_fmac_f32_e32 v8, v12, v12
	v_fmac_f32_e32 v9, v14, v14
	v_add_f32_e32 v8, v8, v9
	v_mul_f32_e32 v9, v25, v25
	v_mul_f32_e32 v10, v27, v27
	v_fmac_f32_e32 v9, v24, v24
	v_fmac_f32_e32 v10, v26, v26
	v_add_f32_e32 v9, v9, v10
	v_add_f32_e32 v8, v8, v9
	v_add_f32_e32 v8, v28, v8
	v_mov_b32_e32 v9, v8
	s_nop 1
	v_permlane16_swap_b32_e32 v8, v9
	s_waitcnt lgkmcnt(0)
	v_add_f32_e32 v8, v8, v9
	v_mov_b32_e32 v9, v8
	s_nop 1
	v_permlane32_swap_b32_e32 v8, v9
	s_and_saveexec_b64 s[4:5], vcc
	s_cbranch_execz .LBB0_309
	s_waitcnt lgkmcnt(0)
	v_add_f32_e32 v8, v8, v9
	ds_write_b32 v122, v8 offset:2560
.LBB0_309:
	s_or_b64 exec, exec, s[4:5]
	v_add_u32_e32 v8, s6, v82
	s_waitcnt lgkmcnt(0)
	ds_read_b128 v[8:11], v8
	ds_read_b128 v[12:15], v82 offset:32768
	v_lshl_add_u64 v[24:25], v[32:33], 0, s[80:81]
	s_waitcnt lgkmcnt(0)
	v_lshlrev_b32_e32 v26, 16, v8
	v_and_b32_e32 v27, 0xffff0000, v8
	v_lshlrev_b32_e32 v8, 16, v9
	v_and_b32_e32 v9, 0xffff0000, v9
	v_pk_fma_f32 v[6:7], v[6:7], 0.5, v[8:9] op_sel_hi:[1,0,1]
	v_pk_fma_f32 v[4:5], v[4:5], 0.5, v[26:27] op_sel_hi:[1,0,1]
	v_lshlrev_b32_e32 v8, 16, v10
	v_and_b32_e32 v9, 0xffff0000, v10
	v_pk_fma_f32 v[8:9], v[0:1], 0.5, v[8:9] op_sel_hi:[1,0,1]
	v_cvt_pk_bf16_f32 v0, v4, v5
	v_mul_f32_e32 v5, v5, v5
	v_lshlrev_b32_e32 v10, 16, v11
	v_and_b32_e32 v11, 0xffff0000, v11
	v_fmac_f32_e32 v5, v4, v4
	v_mul_f32_e32 v4, v7, v7
	v_pk_fma_f32 v[10:11], v[2:3], 0.5, v[10:11] op_sel_hi:[1,0,1]
	v_fmac_f32_e32 v4, v6, v6
	v_cvt_pk_bf16_f32 v1, v6, v7
	v_add_f32_e32 v4, v5, v4
	v_mul_f32_e32 v5, v9, v9
	v_mul_f32_e32 v6, v11, v11
	v_fmac_f32_e32 v5, v8, v8
	v_fmac_f32_e32 v6, v10, v10
	v_add_f32_e32 v5, v5, v6
	v_add_f32_e32 v26, v4, v5
	s_waitcnt lgkmcnt(0)
	v_cndmask_b32_e64 v7, v13, v89, s[36:37]
	v_cndmask_b32_e64 v5, v12, v88, s[36:37]
	v_lshlrev_b32_e32 v4, 16, v5
	v_and_b32_e32 v5, 0xffff0000, v5
	v_lshlrev_b32_e32 v6, 16, v7
	v_and_b32_e32 v7, 0xffff0000, v7
	v_cvt_pk_bf16_f32 v2, v8, v9
	v_cvt_pk_bf16_f32 v3, v10, v11
	v_cndmask_b32_e64 v11, v15, v91, s[36:37]
	v_cndmask_b32_e64 v9, v14, v90, s[36:37]
	v_pk_fma_f32 v[6:7], v[22:23], 0.5, v[6:7] op_sel_hi:[1,0,1]
	v_pk_fma_f32 v[4:5], v[20:21], 0.5, v[4:5] op_sel_hi:[1,0,1]
	v_lshlrev_b32_e32 v8, 16, v9
	v_and_b32_e32 v9, 0xffff0000, v9
	v_lshlrev_b32_e32 v10, 16, v11
	v_and_b32_e32 v11, 0xffff0000, v11
	v_mul_f32_e32 v12, v5, v5
	v_mul_f32_e32 v13, v7, v7
	v_pk_fma_f32 v[10:11], v[18:19], 0.5, v[10:11] op_sel_hi:[1,0,1]
	v_pk_fma_f32 v[8:9], v[16:17], 0.5, v[8:9] op_sel_hi:[1,0,1]
	v_fmac_f32_e32 v12, v4, v4
	v_fmac_f32_e32 v13, v6, v6
	v_add_f32_e32 v12, v12, v13
	v_mul_f32_e32 v13, v9, v9
	v_mul_f32_e32 v14, v11, v11
	v_fmac_f32_e32 v13, v8, v8
	v_fmac_f32_e32 v14, v10, v10
	v_add_f32_e32 v13, v13, v14
	v_add_f32_e32 v12, v12, v13
	v_add_f32_e32 v14, v26, v12
	v_mov_b32_e32 v15, v14
	s_nop 1
	v_permlane16_swap_b32_e32 v14, v15
	v_add_co_u32_e64 v12, s[36:37], s55, v32
	s_nop 1
	v_addc_co_u32_e64 v13, s[36:37], 0, v33, s[36:37]
	global_store_dwordx4 v[12:13], v[0:3], off
	s_waitcnt lgkmcnt(0)
	s_nop 0
	v_add_f32_e32 v0, v14, v15
	v_mov_b32_e32 v1, v0
	s_nop 1
	v_permlane32_swap_b32_e32 v0, v1
	v_cvt_pk_bf16_f32 v2, v4, v5
	v_cvt_pk_bf16_f32 v3, v6, v7
	v_cvt_pk_bf16_f32 v4, v8, v9
	v_cvt_pk_bf16_f32 v5, v10, v11
	global_store_dwordx4 v[24:25], v[2:5], off offset:256
	s_and_saveexec_b64 s[4:5], vcc
	s_cbranch_execz .LBB0_311
	s_waitcnt lgkmcnt(0)
	v_add_f32_e32 v0, v0, v1
	ds_write_b32 v122, v0 offset:2816

.LBB0_627:
	v_and_b32_e32 v147, 64, v197
	v_xor_b32_e32 v146, 16, v197
	v_add_u32_e32 v147, 64, v147
	s_bfe_u32 s7, s0, 0x10006
	v_cmp_lt_i32_e32 vcc, v146, v147
	s_lshl_b32 s5, s7, 10
	s_add_i32 s5, s5, s24
	v_cndmask_b32_e32 v146, v197, v146, vcc
	v_lshlrev_b32_e32 v166, 2, v146
	v_xor_b32_e32 v146, 32, v197
	v_cmp_lt_i32_e32 vcc, v146, v147
	s_add_i32 s5, s5, 0
	v_add_u32_e32 v167, s5, v167
	v_cndmask_b32_e32 v146, v197, v146, vcc
	s_lshl_b32 s5, s19, 13
	v_and_b32_e32 v144, 63, v165
	v_lshlrev_b32_e32 v165, 2, v146
	v_lshlrev_b64 v[146:147], 11, v[158:159]
	s_and_b32 s6, s5, 0x4000
	v_lshl_add_u64 v[146:147], s[60:61], 0, v[146:147]
	s_or_b32 s10, s6, 0x10000
	v_lshl_add_u64 v[160:161], v[156:157], 1, v[146:147]
	v_add_u32_e32 v146, s10, v167
	ds_read_b128 v[168:171], v146
	s_lshl_b32 s4, s19, 2
	s_add_i32 s4, s4, 0
	s_add_i32 s4, s4, 0x20000
	v_cmp_gt_u32_e32 vcc, 16, v144
	s_waitcnt lgkmcnt(0)
	v_lshlrev_b32_e32 v146, 16, v168
	v_and_b32_e32 v147, 0xffff0000, v168
	v_lshlrev_b32_e32 v154, 16, v169
	v_and_b32_e32 v155, 0xffff0000, v169
	v_pk_add_f32 v[138:139], v[138:139], v[154:155]
	v_pk_add_f32 v[136:137], v[136:137], v[146:147]
	v_lshlrev_b32_e32 v146, 16, v170
	v_and_b32_e32 v147, 0xffff0000, v170
	v_lshlrev_b32_e32 v154, 16, v171
	v_and_b32_e32 v155, 0xffff0000, v171
	v_pk_add_f32 v[154:155], v[134:135], v[154:155]
	v_pk_add_f32 v[146:147], v[132:133], v[146:147]
	v_cvt_pk_bf16_f32 v132, v136, v137
	v_cvt_pk_bf16_f32 v133, v138, v139
	v_cvt_pk_bf16_f32 v134, v146, v147
	v_cvt_pk_bf16_f32 v135, v154, v155
	global_store_dwordx4 v[160:161], v[132:135], off
	s_nop 1
	v_mul_f32_e32 v132, v137, v137
	v_mul_f32_e32 v133, v139, v139
	v_fmac_f32_e32 v132, v136, v136
	v_fmac_f32_e32 v133, v138, v138
	v_add_f32_e32 v132, v132, v133
	v_mul_f32_e32 v133, v147, v147
	v_mul_f32_e32 v134, v155, v155
	v_fmac_f32_e32 v133, v146, v146
	v_fmac_f32_e32 v134, v154, v154
	v_add_f32_e32 v133, v133, v134
	v_add_f32_e32 v138, v132, v133
	v_add_u32_e32 v132, s6, v167
	ds_read_b128 v[132:135], v132
	s_waitcnt lgkmcnt(0)
	v_lshlrev_b32_e32 v136, 16, v132
	v_and_b32_e32 v137, 0xffff0000, v132
	v_lshlrev_b32_e32 v132, 16, v133
	v_and_b32_e32 v133, 0xffff0000, v133
	v_pk_add_f32 v[126:127], v[126:127], v[132:133]
	v_lshlrev_b32_e32 v132, 16, v134
	v_and_b32_e32 v133, 0xffff0000, v134
	v_lshlrev_b32_e32 v134, 16, v135
	v_and_b32_e32 v135, 0xffff0000, v135
	v_pk_add_f32 v[124:125], v[124:125], v[136:137]
	v_pk_add_f32 v[134:135], v[122:123], v[134:135]
	v_pk_add_f32 v[132:133], v[120:121], v[132:133]
	v_cvt_pk_bf16_f32 v120, v124, v125
	v_cvt_pk_bf16_f32 v121, v126, v127
	v_cvt_pk_bf16_f32 v122, v132, v133
	v_cvt_pk_bf16_f32 v123, v134, v135
	global_store_dwordx4 v[160:161], v[120:123], off offset:256
	s_nop 1
	v_mul_f32_e32 v120, v125, v125
	v_mul_f32_e32 v121, v127, v127
	v_fmac_f32_e32 v120, v124, v124
	v_fmac_f32_e32 v121, v126, v126
	v_add_f32_e32 v120, v120, v121
	v_mul_f32_e32 v121, v133, v133
	v_mul_f32_e32 v122, v135, v135
	v_fmac_f32_e32 v121, v132, v132
	v_fmac_f32_e32 v122, v134, v134
	v_add_f32_e32 v121, v121, v122
	v_add_f32_e32 v120, v120, v121
	v_add_f32_e32 v120, v138, v120
	v_mov_b32_e32 v121, v120
	s_nop 1
	v_permlane16_swap_b32_e32 v120, v121
	v_lshl_add_u32 v122, v164, 4, s4
	s_waitcnt lgkmcnt(0)
	v_add_f32_e32 v120, v120, v121
	v_mov_b32_e32 v121, v120
	s_nop 1
	v_permlane32_swap_b32_e32 v120, v121
	s_and_saveexec_b64 s[4:5], vcc
	s_cbranch_execz .LBB0_629
	s_waitcnt lgkmcnt(0)
	v_add_f32_e32 v120, v120, v121
	ds_write_b32 v122, v120
.LBB0_629:
	s_or_b64 exec, exec, s[4:5]
	s_or_b32 s4, s18, 16
	v_or_b32_e32 v123, s4, v162
	s_lshr_b32 s4, s4, 3
	s_or_b32 s4, s4, s7
	v_lshlrev_b32_e32 v124, 6, v123
	s_movk_i32 s5, 0x3c0
	s_lshl_b32 s4, s4, 10
	v_lshlrev_b32_e32 v123, 2, v123
	v_and_or_b32 v124, v124, s5, v163
	v_and_b32_e32 v123, 32, v123
	s_add_i32 s4, s4, 0
	v_xad_u32 v123, v124, v123, s4
	v_add_u32_e32 v124, s10, v123
	ds_read_b128 v[124:127], v124
	v_or_b32_e32 v120, 16, v158
	s_waitcnt lgkmcnt(0)
	v_ashrrev_i32_e32 v121, 31, v120
	v_lshlrev_b64 v[120:121], 11, v[120:121]
	v_lshl_add_u64 v[120:121], s[60:61], 0, v[120:121]
	v_lshlrev_b32_e32 v132, 16, v124
	v_and_b32_e32 v133, 0xffff0000, v124
	v_lshlrev_b32_e32 v124, 16, v125
	v_and_b32_e32 v125, 0xffff0000, v125
	v_pk_add_f32 v[118:119], v[118:119], v[124:125]
	v_lshlrev_b32_e32 v124, 16, v126
	v_and_b32_e32 v125, 0xffff0000, v126
	v_lshlrev_b32_e32 v126, 16, v127
	v_and_b32_e32 v127, 0xffff0000, v127
	v_pk_add_f32 v[116:117], v[116:117], v[132:133]
	v_pk_add_f32 v[126:127], v[114:115], v[126:127]
	v_pk_add_f32 v[124:125], v[112:113], v[124:125]
	v_lshl_add_u64 v[120:121], v[156:157], 1, v[120:121]
	v_cvt_pk_bf16_f32 v112, v116, v117
	v_cvt_pk_bf16_f32 v113, v118, v119
	v_cvt_pk_bf16_f32 v114, v124, v125
	v_cvt_pk_bf16_f32 v115, v126, v127
	global_store_dwordx4 v[120:121], v[112:115], off
	s_nop 1
	v_mul_f32_e32 v112, v117, v117
	v_mul_f32_e32 v113, v119, v119
	v_fmac_f32_e32 v112, v116, v116
	v_fmac_f32_e32 v113, v118, v118
	v_add_f32_e32 v112, v112, v113
	v_mul_f32_e32 v113, v125, v125
	v_mul_f32_e32 v114, v127, v127
	v_fmac_f32_e32 v113, v124, v124
	v_fmac_f32_e32 v114, v126, v126
	v_add_f32_e32 v113, v113, v114
	v_add_f32_e32 v118, v112, v113
	v_add_u32_e32 v112, s6, v123
	ds_read_b128 v[112:115], v112
	s_waitcnt lgkmcnt(0)
	v_lshlrev_b32_e32 v116, 16, v112
	v_and_b32_e32 v117, 0xffff0000, v112
	v_lshlrev_b32_e32 v112, 16, v113
	v_and_b32_e32 v113, 0xffff0000, v113
	v_pk_add_f32 v[106:107], v[106:107], v[112:113]
	v_lshlrev_b32_e32 v112, 16, v114
	v_and_b32_e32 v113, 0xffff0000, v114
	v_lshlrev_b32_e32 v114, 16, v115
	v_and_b32_e32 v115, 0xffff0000, v115
	v_pk_add_f32 v[104:105], v[104:105], v[116:117]
	v_pk_add_f32 v[114:115], v[102:103], v[114:115]
	v_pk_add_f32 v[112:113], v[100:101], v[112:113]
	v_cvt_pk_bf16_f32 v100, v104, v105
	v_cvt_pk_bf16_f32 v101, v106, v107
	v_cvt_pk_bf16_f32 v102, v112, v113
	v_cvt_pk_bf16_f32 v103, v114, v115
	global_store_dwordx4 v[120:121], v[100:103], off offset:256
	s_nop 1
	v_mul_f32_e32 v100, v105, v105
	v_mul_f32_e32 v101, v107, v107
	v_fmac_f32_e32 v100, v104, v104
	v_fmac_f32_e32 v101, v106, v106
	v_add_f32_e32 v100, v100, v101
	v_mul_f32_e32 v101, v113, v113
	v_mul_f32_e32 v102, v115, v115
	v_fmac_f32_e32 v101, v112, v112
	v_fmac_f32_e32 v102, v114, v114
	v_add_f32_e32 v101, v101, v102
	v_add_f32_e32 v100, v100, v101
	v_add_f32_e32 v100, v118, v100
	v_mov_b32_e32 v101, v100
	s_nop 1
	v_permlane16_swap_b32_e32 v100, v101
	s_waitcnt lgkmcnt(0)
	v_add_f32_e32 v100, v100, v101
	v_mov_b32_e32 v101, v100
	s_nop 1
	v_permlane32_swap_b32_e32 v100, v101
	s_and_saveexec_b64 s[4:5], vcc
	s_cbranch_execz .LBB0_631
	s_waitcnt lgkmcnt(0)
	v_add_f32_e32 v100, v100, v101
	ds_write_b32 v122, v100 offset:256
.LBB0_631:
	s_or_b64 exec, exec, s[4:5]
	s_or_b32 s4, s18, 32
	v_or_b32_e32 v102, s4, v162
	s_lshr_b32 s4, s4, 3
	s_or_b32 s4, s4, s7
	v_lshlrev_b32_e32 v103, 6, v102
	s_movk_i32 s5, 0x3c0
	s_lshl_b32 s4, s4, 10
	v_lshlrev_b32_e32 v102, 2, v102
	v_and_or_b32 v103, v103, s5, v163
	v_and_b32_e32 v102, 32, v102
	s_add_i32 s4, s4, 0
	v_xad_u32 v102, v103, v102, s4
	v_add_u32_e32 v103, s10, v102
	ds_read_b128 v[104:107], v103
	v_or_b32_e32 v100, 32, v158
	s_waitcnt lgkmcnt(0)
	v_ashrrev_i32_e32 v101, 31, v100
	v_lshlrev_b64 v[100:101], 11, v[100:101]
	v_lshl_add_u64 v[100:101], s[60:61], 0, v[100:101]
	v_lshlrev_b32_e32 v112, 16, v104
	v_and_b32_e32 v113, 0xffff0000, v104
	v_lshlrev_b32_e32 v104, 16, v105
	v_and_b32_e32 v105, 0xffff0000, v105
	v_pk_add_f32 v[98:99], v[98:99], v[104:105]
	v_lshlrev_b32_e32 v104, 16, v106
	v_and_b32_e32 v105, 0xffff0000, v106
	v_lshlrev_b32_e32 v106, 16, v107
	v_and_b32_e32 v107, 0xffff0000, v107
	v_pk_add_f32 v[96:97], v[96:97], v[112:113]
	v_pk_add_f32 v[106:107], v[94:95], v[106:107]
	v_pk_add_f32 v[104:105], v[92:93], v[104:105]
	v_lshl_add_u64 v[100:101], v[156:157], 1, v[100:101]
	v_cvt_pk_bf16_f32 v92, v96, v97
	v_cvt_pk_bf16_f32 v93, v98, v99
	v_cvt_pk_bf16_f32 v94, v104, v105
	v_cvt_pk_bf16_f32 v95, v106, v107
	global_store_dwordx4 v[100:101], v[92:95], off
	s_nop 1
	v_mul_f32_e32 v92, v97, v97
	v_mul_f32_e32 v93, v99, v99
	v_fmac_f32_e32 v92, v96, v96
	v_fmac_f32_e32 v93, v98, v98
	v_add_f32_e32 v92, v92, v93
	v_mul_f32_e32 v93, v105, v105
	v_mul_f32_e32 v94, v107, v107
	v_fmac_f32_e32 v93, v104, v104
	v_fmac_f32_e32 v94, v106, v106
	v_add_f32_e32 v93, v93, v94
	v_add_f32_e32 v98, v92, v93
	v_add_u32_e32 v92, s6, v102
	ds_read_b128 v[92:95], v92
	s_waitcnt lgkmcnt(0)
	v_lshlrev_b32_e32 v96, 16, v92
	v_and_b32_e32 v97, 0xffff0000, v92
	v_lshlrev_b32_e32 v92, 16, v93
	v_and_b32_e32 v93, 0xffff0000, v93
	v_pk_add_f32 v[86:87], v[86:87], v[92:93]
	v_lshlrev_b32_e32 v92, 16, v94
	v_and_b32_e32 v93, 0xffff0000, v94
	v_lshlrev_b32_e32 v94, 16, v95
	v_and_b32_e32 v95, 0xffff0000, v95
	v_pk_add_f32 v[84:85], v[84:85], v[96:97]
	v_pk_add_f32 v[94:95], v[82:83], v[94:95]
	v_pk_add_f32 v[92:93], v[80:81], v[92:93]
	v_cvt_pk_bf16_f32 v80, v84, v85
	v_cvt_pk_bf16_f32 v81, v86, v87
	v_cvt_pk_bf16_f32 v82, v92, v93
	v_cvt_pk_bf16_f32 v83, v94, v95
	global_store_dwordx4 v[100:101], v[80:83], off offset:256
	s_nop 1
	v_mul_f32_e32 v80, v85, v85
	v_mul_f32_e32 v81, v87, v87
	v_fmac_f32_e32 v80, v84, v84
	v_fmac_f32_e32 v81, v86, v86
	v_add_f32_e32 v80, v80, v81
	v_mul_f32_e32 v81, v93, v93
	v_mul_f32_e32 v82, v95, v95
	v_fmac_f32_e32 v81, v92, v92
	v_fmac_f32_e32 v82, v94, v94
	v_add_f32_e32 v81, v81, v82
	v_add_f32_e32 v80, v80, v81
	v_add_f32_e32 v80, v98, v80
	v_mov_b32_e32 v81, v80
	s_nop 1
	v_permlane16_swap_b32_e32 v80, v81
	s_waitcnt lgkmcnt(0)
	v_add_f32_e32 v80, v80, v81
	v_mov_b32_e32 v81, v80
	s_nop 1
	v_permlane32_swap_b32_e32 v80, v81
	s_and_saveexec_b64 s[4:5], vcc
	s_cbranch_execz .LBB0_633
	s_waitcnt lgkmcnt(0)
	v_add_f32_e32 v80, v80, v81
	ds_write_b32 v122, v80 offset:512
.LBB0_633:
	s_or_b64 exec, exec, s[4:5]
	s_or_b32 s4, s18, 48
	v_or_b32_e32 v82, s4, v162
	s_lshr_b32 s4, s4, 3
	s_or_b32 s4, s4, s7
	v_lshlrev_b32_e32 v83, 6, v82
	s_movk_i32 s5, 0x3c0
	s_lshl_b32 s4, s4, 10
	v_lshlrev_b32_e32 v82, 2, v82
	v_and_or_b32 v83, v83, s5, v163
	v_and_b32_e32 v82, 32, v82
	s_add_i32 s4, s4, 0
	v_xad_u32 v82, v83, v82, s4
	v_add_u32_e32 v83, s10, v82
	ds_read_b128 v[84:87], v83
	v_or_b32_e32 v80, 48, v158
	s_waitcnt lgkmcnt(0)
	v_ashrrev_i32_e32 v81, 31, v80
	v_lshlrev_b64 v[80:81], 11, v[80:81]
	v_lshl_add_u64 v[80:81], s[60:61], 0, v[80:81]
	v_lshlrev_b32_e32 v92, 16, v84
	v_and_b32_e32 v93, 0xffff0000, v84
	v_lshlrev_b32_e32 v84, 16, v85
	v_and_b32_e32 v85, 0xffff0000, v85
	v_pk_add_f32 v[78:79], v[78:79], v[84:85]
	v_lshlrev_b32_e32 v84, 16, v86
	v_and_b32_e32 v85, 0xffff0000, v86
	v_lshlrev_b32_e32 v86, 16, v87
	v_and_b32_e32 v87, 0xffff0000, v87
	v_pk_add_f32 v[76:77], v[76:77], v[92:93]
	v_pk_add_f32 v[86:87], v[74:75], v[86:87]
	v_pk_add_f32 v[84:85], v[72:73], v[84:85]
	v_lshl_add_u64 v[80:81], v[156:157], 1, v[80:81]
	v_cvt_pk_bf16_f32 v72, v76, v77
	v_cvt_pk_bf16_f32 v73, v78, v79
	v_cvt_pk_bf16_f32 v74, v84, v85
	v_cvt_pk_bf16_f32 v75, v86, v87
	global_store_dwordx4 v[80:81], v[72:75], off
	s_nop 1
	v_mul_f32_e32 v72, v77, v77
	v_mul_f32_e32 v73, v79, v79
	v_fmac_f32_e32 v72, v76, v76
	v_fmac_f32_e32 v73, v78, v78
	v_add_f32_e32 v72, v72, v73
	v_mul_f32_e32 v73, v85, v85
	v_mul_f32_e32 v74, v87, v87
	v_fmac_f32_e32 v73, v84, v84
	v_fmac_f32_e32 v74, v86, v86
	v_add_f32_e32 v73, v73, v74
	v_add_f32_e32 v78, v72, v73
	v_add_u32_e32 v72, s6, v82
	ds_read_b128 v[72:75], v72
	s_waitcnt lgkmcnt(0)
	v_lshlrev_b32_e32 v76, 16, v72
	v_and_b32_e32 v77, 0xffff0000, v72
	v_lshlrev_b32_e32 v72, 16, v73
	v_and_b32_e32 v73, 0xffff0000, v73
	v_pk_add_f32 v[70:71], v[70:71], v[72:73]
	v_lshlrev_b32_e32 v72, 16, v74
	v_and_b32_e32 v73, 0xffff0000, v74
	v_lshlrev_b32_e32 v74, 16, v75
	v_and_b32_e32 v75, 0xffff0000, v75
	v_pk_add_f32 v[68:69], v[68:69], v[76:77]
	v_pk_add_f32 v[74:75], v[66:67], v[74:75]
	v_pk_add_f32 v[72:73], v[64:65], v[72:73]
	v_cvt_pk_bf16_f32 v64, v68, v69
	v_cvt_pk_bf16_f32 v65, v70, v71
	v_cvt_pk_bf16_f32 v66, v72, v73
	v_cvt_pk_bf16_f32 v67, v74, v75
	global_store_dwordx4 v[80:81], v[64:67], off offset:256
	s_nop 1
	v_mul_f32_e32 v64, v69, v69
	v_mul_f32_e32 v65, v71, v71
	v_fmac_f32_e32 v64, v68, v68
	v_fmac_f32_e32 v65, v70, v70
	v_add_f32_e32 v64, v64, v65
	v_mul_f32_e32 v65, v73, v73
	v_mul_f32_e32 v66, v75, v75
	v_fmac_f32_e32 v65, v72, v72
	v_fmac_f32_e32 v66, v74, v74
	v_add_f32_e32 v65, v65, v66
	v_add_f32_e32 v64, v64, v65
	v_add_f32_e32 v64, v78, v64
	v_mov_b32_e32 v65, v64
	s_nop 1
	v_permlane16_swap_b32_e32 v64, v65
	s_waitcnt lgkmcnt(0)
	v_add_f32_e32 v64, v64, v65
	v_mov_b32_e32 v65, v64
	s_nop 1
	v_permlane32_swap_b32_e32 v64, v65
	s_and_saveexec_b64 s[4:5], vcc
	s_cbranch_execz .LBB0_635
	s_waitcnt lgkmcnt(0)
	v_add_f32_e32 v64, v64, v65
	ds_write_b32 v122, v64 offset:768
.LBB0_635:
	s_or_b64 exec, exec, s[4:5]
	s_or_b32 s6, s6, 0x18000
	v_add_u32_e32 v68, s6, v167
	ds_read_b128 v[68:71], v68
	s_waitcnt lgkmcnt(0)
	v_lshlrev_b64 v[64:65], 11, v[158:159]
	v_lshl_add_u64 v[64:65], s[60:61], 0, v[64:65]
	v_lshl_add_u64 v[64:65], v[156:157], 1, v[64:65]
	s_mov_b32 s4, 0x40000
	v_lshlrev_b32_e32 v72, 16, v68
	v_and_b32_e32 v73, 0xffff0000, v68
	v_lshlrev_b32_e32 v68, 16, v69
	v_and_b32_e32 v69, 0xffff0000, v69
	v_pk_add_f32 v[62:63], v[62:63], v[68:69]
	v_lshlrev_b32_e32 v68, 16, v70
	v_and_b32_e32 v69, 0xffff0000, v70
	v_lshlrev_b32_e32 v70, 16, v71
	v_and_b32_e32 v71, 0xffff0000, v71
	v_pk_add_f32 v[60:61], v[60:61], v[72:73]
	v_pk_add_f32 v[70:71], v[58:59], v[70:71]
	v_pk_add_f32 v[68:69], v[56:57], v[68:69]
	v_add_co_u32_e64 v72, s[38:39], s4, v64
	v_cvt_pk_bf16_f32 v56, v60, v61
	v_cvt_pk_bf16_f32 v57, v62, v63
	v_cvt_pk_bf16_f32 v58, v68, v69
	v_cvt_pk_bf16_f32 v59, v70, v71
	v_addc_co_u32_e64 v73, s[38:39], 0, v65, s[38:39]
	global_store_dwordx4 v[72:73], v[56:59], off
	v_lshl_add_u64 v[66:67], v[64:65], 0, s[62:63]
	s_nop 0
	v_mul_f32_e32 v56, v61, v61
	v_mul_f32_e32 v57, v63, v63
	v_fmac_f32_e32 v56, v60, v60
	v_fmac_f32_e32 v57, v62, v62
	v_add_f32_e32 v56, v56, v57
	v_mul_f32_e32 v57, v69, v69
	v_mul_f32_e32 v58, v71, v71
	v_fmac_f32_e32 v57, v68, v68
	v_fmac_f32_e32 v58, v70, v70
	v_add_f32_e32 v57, v57, v58
	v_add_f32_e32 v60, v56, v57
	ds_read_b128 v[56:59], v167 offset:32768
	s_waitcnt vmcnt(0) lgkmcnt(0)
	v_cndmask_b32_e64 v61, v59, v143, s[36:37]
	v_cndmask_b32_e64 v59, v57, v141, s[36:37]
	v_cndmask_b32_e64 v57, v56, v140, s[36:37]
	v_cndmask_b32_e64 v62, v58, v142, s[36:37]
	v_lshlrev_b32_e32 v56, 16, v57
	v_and_b32_e32 v57, 0xffff0000, v57
	v_lshlrev_b32_e32 v58, 16, v59
	v_and_b32_e32 v59, 0xffff0000, v59
	v_pk_add_f32 v[54:55], v[54:55], v[58:59]
	v_pk_add_f32 v[52:53], v[52:53], v[56:57]
	v_lshlrev_b32_e32 v56, 16, v62
	v_and_b32_e32 v57, 0xffff0000, v62
	v_lshlrev_b32_e32 v58, 16, v61
	v_and_b32_e32 v59, 0xffff0000, v61
	v_pk_add_f32 v[58:59], v[50:51], v[58:59]
	v_pk_add_f32 v[56:57], v[48:49], v[56:57]
	v_cvt_pk_bf16_f32 v48, v52, v53
	v_cvt_pk_bf16_f32 v49, v54, v55
	v_cvt_pk_bf16_f32 v50, v56, v57
	v_cvt_pk_bf16_f32 v51, v58, v59
	global_store_dwordx4 v[66:67], v[48:51], off offset:256
	s_nop 1
	v_mul_f32_e32 v48, v53, v53
	v_mul_f32_e32 v49, v55, v55
	v_fmac_f32_e32 v48, v52, v52
	v_fmac_f32_e32 v49, v54, v54
	v_add_f32_e32 v48, v48, v49
	v_mul_f32_e32 v49, v57, v57
	v_mul_f32_e32 v50, v59, v59
	v_fmac_f32_e32 v49, v56, v56
	v_fmac_f32_e32 v50, v58, v58
	v_add_f32_e32 v49, v49, v50
	v_add_f32_e32 v48, v48, v49
	v_add_f32_e32 v48, v60, v48
	v_mov_b32_e32 v49, v48
	s_nop 1
	v_permlane16_swap_b32_e32 v48, v49
	s_waitcnt lgkmcnt(0)
	v_add_f32_e32 v48, v48, v49
	v_mov_b32_e32 v49, v48
	s_nop 1
	v_permlane32_swap_b32_e32 v48, v49
	s_and_saveexec_b64 s[4:5], vcc
	s_cbranch_execz .LBB0_637
	s_waitcnt lgkmcnt(0)
	v_add_f32_e32 v48, v48, v49
	ds_write_b32 v122, v48 offset:2048
.LBB0_637:
	s_or_b64 exec, exec, s[4:5]
	v_add_u32_e32 v50, s6, v123
	ds_read_b128 v[50:53], v50
	s_mov_b32 s4, 0x48000
	s_waitcnt lgkmcnt(0)
	v_lshl_add_u64 v[48:49], v[64:65], 0, s[76:77]
	s_waitcnt lgkmcnt(0)
	v_lshlrev_b32_e32 v54, 16, v50
	v_and_b32_e32 v55, 0xffff0000, v50
	v_lshlrev_b32_e32 v50, 16, v51
	v_and_b32_e32 v51, 0xffff0000, v51
	v_pk_add_f32 v[46:47], v[46:47], v[50:51]
	v_lshlrev_b32_e32 v50, 16, v52
	v_and_b32_e32 v51, 0xffff0000, v52
	v_lshlrev_b32_e32 v52, 16, v53
	v_and_b32_e32 v53, 0xffff0000, v53
	v_pk_add_f32 v[44:45], v[44:45], v[54:55]
	v_pk_add_f32 v[52:53], v[42:43], v[52:53]
	v_pk_add_f32 v[50:51], v[40:41], v[50:51]
	v_add_co_u32_e64 v54, s[38:39], s4, v64
	v_cvt_pk_bf16_f32 v40, v44, v45
	v_cvt_pk_bf16_f32 v41, v46, v47
	v_cvt_pk_bf16_f32 v42, v50, v51
	v_cvt_pk_bf16_f32 v43, v52, v53
	v_addc_co_u32_e64 v55, s[38:39], 0, v65, s[38:39]
	global_store_dwordx4 v[54:55], v[40:43], off
	s_nop 1
	v_mul_f32_e32 v40, v45, v45
	v_mul_f32_e32 v41, v47, v47
	v_fmac_f32_e32 v40, v44, v44
	v_fmac_f32_e32 v41, v46, v46
	v_add_f32_e32 v40, v40, v41
	v_mul_f32_e32 v41, v51, v51
	v_mul_f32_e32 v42, v53, v53
	v_fmac_f32_e32 v41, v50, v50
	v_fmac_f32_e32 v42, v52, v52
	v_add_f32_e32 v41, v41, v42
	v_add_f32_e32 v44, v40, v41
	ds_read_b128 v[40:43], v123 offset:32768
	s_waitcnt lgkmcnt(0)
	v_cndmask_b32_e64 v45, v43, v131, s[36:37]
	v_cndmask_b32_e64 v43, v41, v129, s[36:37]
	v_cndmask_b32_e64 v41, v40, v128, s[36:37]
	v_cndmask_b32_e64 v46, v42, v130, s[36:37]
	v_lshlrev_b32_e32 v40, 16, v41
	v_and_b32_e32 v41, 0xffff0000, v41
	v_lshlrev_b32_e32 v42, 16, v43
	v_and_b32_e32 v43, 0xffff0000, v43
	v_pk_add_f32 v[38:39], v[38:39], v[42:43]
	v_pk_add_f32 v[36:37], v[36:37], v[40:41]
	v_lshlrev_b32_e32 v40, 16, v46
	v_and_b32_e32 v41, 0xffff0000, v46
	v_lshlrev_b32_e32 v42, 16, v45
	v_and_b32_e32 v43, 0xffff0000, v45
	v_pk_add_f32 v[42:43], v[34:35], v[42:43]
	v_pk_add_f32 v[40:41], v[32:33], v[40:41]
	v_cvt_pk_bf16_f32 v32, v36, v37
	v_cvt_pk_bf16_f32 v33, v38, v39
	v_cvt_pk_bf16_f32 v34, v40, v41
	v_cvt_pk_bf16_f32 v35, v42, v43
	global_store_dwordx4 v[48:49], v[32:35], off offset:256
	s_nop 1
	v_mul_f32_e32 v32, v37, v37
	v_mul_f32_e32 v33, v39, v39
	v_fmac_f32_e32 v32, v36, v36
	v_fmac_f32_e32 v33, v38, v38
	v_add_f32_e32 v32, v32, v33
	v_mul_f32_e32 v33, v41, v41
	v_mul_f32_e32 v34, v43, v43
	v_fmac_f32_e32 v33, v40, v40
	v_fmac_f32_e32 v34, v42, v42
	v_add_f32_e32 v33, v33, v34
	v_add_f32_e32 v32, v32, v33
	v_add_f32_e32 v32, v44, v32
	v_mov_b32_e32 v33, v32
	s_nop 1
	v_permlane16_swap_b32_e32 v32, v33
	s_waitcnt lgkmcnt(0)
	v_add_f32_e32 v32, v32, v33
	v_mov_b32_e32 v33, v32
	s_nop 1
	v_permlane32_swap_b32_e32 v32, v33
	s_and_saveexec_b64 s[4:5], vcc
	s_cbranch_execz .LBB0_639
	s_waitcnt lgkmcnt(0)
	v_add_f32_e32 v32, v32, v33
	ds_write_b32 v122, v32 offset:2304
.LBB0_639:
	s_or_b64 exec, exec, s[4:5]
	v_add_u32_e32 v36, s6, v102
	ds_read_b128 v[36:39], v36
	s_waitcnt lgkmcnt(0)
	v_lshlrev_b64 v[32:33], 11, v[158:159]
	v_lshl_add_u64 v[32:33], s[60:61], 0, v[32:33]
	v_lshl_add_u64 v[32:33], v[156:157], 1, v[32:33]
	s_mov_b32 s4, 0x50000
	s_waitcnt lgkmcnt(0)
	v_lshlrev_b32_e32 v40, 16, v36
	v_and_b32_e32 v41, 0xffff0000, v36
	v_lshlrev_b32_e32 v36, 16, v37
	v_and_b32_e32 v37, 0xffff0000, v37
	v_pk_add_f32 v[30:31], v[30:31], v[36:37]
	v_lshlrev_b32_e32 v36, 16, v38
	v_and_b32_e32 v37, 0xffff0000, v38
	v_lshlrev_b32_e32 v38, 16, v39
	v_and_b32_e32 v39, 0xffff0000, v39
	v_pk_add_f32 v[28:29], v[28:29], v[40:41]
	v_pk_add_f32 v[38:39], v[26:27], v[38:39]
	v_pk_add_f32 v[36:37], v[24:25], v[36:37]
	v_add_co_u32_e64 v40, s[38:39], s4, v32
	v_cvt_pk_bf16_f32 v24, v28, v29
	v_cvt_pk_bf16_f32 v25, v30, v31
	v_cvt_pk_bf16_f32 v26, v36, v37
	v_cvt_pk_bf16_f32 v27, v38, v39
	v_addc_co_u32_e64 v41, s[38:39], 0, v33, s[38:39]
	global_store_dwordx4 v[40:41], v[24:27], off
	v_lshl_add_u64 v[34:35], v[32:33], 0, s[78:79]
	s_nop 0
	v_mul_f32_e32 v24, v29, v29
	v_mul_f32_e32 v25, v31, v31
	v_fmac_f32_e32 v24, v28, v28
	v_fmac_f32_e32 v25, v30, v30
	v_add_f32_e32 v24, v24, v25
	v_mul_f32_e32 v25, v37, v37
	v_mul_f32_e32 v26, v39, v39
	v_fmac_f32_e32 v25, v36, v36
	v_fmac_f32_e32 v26, v38, v38
	v_add_f32_e32 v25, v25, v26
	v_add_f32_e32 v28, v24, v25
	ds_read_b128 v[24:27], v102 offset:32768
	s_waitcnt lgkmcnt(0)
	v_cndmask_b32_e64 v29, v27, v111, s[36:37]
	v_cndmask_b32_e64 v27, v25, v109, s[36:37]
	v_cndmask_b32_e64 v25, v24, v108, s[36:37]
	v_cndmask_b32_e64 v30, v26, v110, s[36:37]
	v_lshlrev_b32_e32 v24, 16, v25
	v_and_b32_e32 v25, 0xffff0000, v25
	v_lshlrev_b32_e32 v26, 16, v27
	v_and_b32_e32 v27, 0xffff0000, v27
	v_pk_add_f32 v[14:15], v[14:15], v[26:27]
	v_pk_add_f32 v[12:13], v[12:13], v[24:25]
	v_lshlrev_b32_e32 v24, 16, v30
	v_and_b32_e32 v25, 0xffff0000, v30
	v_lshlrev_b32_e32 v26, 16, v29
	v_and_b32_e32 v27, 0xffff0000, v29
	v_pk_add_f32 v[26:27], v[10:11], v[26:27]
	v_pk_add_f32 v[24:25], v[8:9], v[24:25]
	v_cvt_pk_bf16_f32 v8, v12, v13
	v_cvt_pk_bf16_f32 v9, v14, v15
	v_cvt_pk_bf16_f32 v10, v24, v25
	v_cvt_pk_bf16_f32 v11, v26, v27
	global_store_dwordx4 v[34:35], v[8:11], off offset:256
	s_nop 1
	v_mul_f32_e32 v8, v13, v13
	v_mul_f32_e32 v9, v15, v15
	v_fmac_f32_e32 v8, v12, v12
	v_fmac_f32_e32 v9, v14, v14
	v_add_f32_e32 v8, v8, v9
	v_mul_f32_e32 v9, v25, v25
	v_mul_f32_e32 v10, v27, v27
	v_fmac_f32_e32 v9, v24, v24
	v_fmac_f32_e32 v10, v26, v26
	v_add_f32_e32 v9, v9, v10
	v_add_f32_e32 v8, v8, v9
	v_add_f32_e32 v8, v28, v8
	v_mov_b32_e32 v9, v8
	s_nop 1
	v_permlane16_swap_b32_e32 v8, v9
	s_waitcnt lgkmcnt(0)
	v_add_f32_e32 v8, v8, v9
	v_mov_b32_e32 v9, v8
	s_nop 1
	v_permlane32_swap_b32_e32 v8, v9
	s_and_saveexec_b64 s[4:5], vcc
	s_cbranch_execz .LBB0_641
	s_waitcnt lgkmcnt(0)
	v_add_f32_e32 v8, v8, v9
	ds_write_b32 v122, v8 offset:2560
.LBB0_641:
	s_or_b64 exec, exec, s[4:5]
	v_add_u32_e32 v8, s6, v82
	s_waitcnt lgkmcnt(0)
	ds_read_b128 v[8:11], v8
	ds_read_b128 v[12:15], v82 offset:32768
	v_lshl_add_u64 v[24:25], v[32:33], 0, s[80:81]
	s_waitcnt lgkmcnt(0)
	v_lshlrev_b32_e32 v26, 16, v8
	v_and_b32_e32 v27, 0xffff0000, v8
	v_lshlrev_b32_e32 v8, 16, v9
	v_and_b32_e32 v9, 0xffff0000, v9
	v_pk_add_f32 v[6:7], v[6:7], v[8:9]
	v_pk_add_f32 v[4:5], v[4:5], v[26:27]
	v_lshlrev_b32_e32 v8, 16, v10
	v_and_b32_e32 v9, 0xffff0000, v10
	v_pk_add_f32 v[8:9], v[0:1], v[8:9]
	v_cvt_pk_bf16_f32 v0, v4, v5
	v_mul_f32_e32 v5, v5, v5
	v_lshlrev_b32_e32 v10, 16, v11
	v_and_b32_e32 v11, 0xffff0000, v11
	v_fmac_f32_e32 v5, v4, v4
	v_mul_f32_e32 v4, v7, v7
	v_pk_add_f32 v[10:11], v[2:3], v[10:11]
	v_fmac_f32_e32 v4, v6, v6
	v_cvt_pk_bf16_f32 v1, v6, v7
	v_add_f32_e32 v4, v5, v4
	v_mul_f32_e32 v5, v9, v9
	v_mul_f32_e32 v6, v11, v11
	v_fmac_f32_e32 v5, v8, v8
	v_fmac_f32_e32 v6, v10, v10
	v_add_f32_e32 v5, v5, v6
	v_add_f32_e32 v26, v4, v5
	s_waitcnt lgkmcnt(0)
	v_cndmask_b32_e64 v7, v13, v89, s[36:37]
	v_cndmask_b32_e64 v5, v12, v88, s[36:37]
	v_lshlrev_b32_e32 v4, 16, v5
	v_and_b32_e32 v5, 0xffff0000, v5
	v_lshlrev_b32_e32 v6, 16, v7
	v_and_b32_e32 v7, 0xffff0000, v7
	v_cvt_pk_bf16_f32 v2, v8, v9
	v_cvt_pk_bf16_f32 v3, v10, v11
	v_cndmask_b32_e64 v11, v15, v91, s[36:37]
	v_cndmask_b32_e64 v9, v14, v90, s[36:37]
	v_pk_add_f32 v[6:7], v[22:23], v[6:7]
	v_pk_add_f32 v[4:5], v[20:21], v[4:5]
	v_lshlrev_b32_e32 v8, 16, v9
	v_and_b32_e32 v9, 0xffff0000, v9
	v_lshlrev_b32_e32 v10, 16, v11
	v_and_b32_e32 v11, 0xffff0000, v11
	v_mul_f32_e32 v12, v5, v5
	v_mul_f32_e32 v13, v7, v7
	v_pk_add_f32 v[10:11], v[18:19], v[10:11]
	v_pk_add_f32 v[8:9], v[16:17], v[8:9]
	v_fmac_f32_e32 v12, v4, v4
	v_fmac_f32_e32 v13, v6, v6
	v_add_f32_e32 v12, v12, v13
	v_mul_f32_e32 v13, v9, v9
	v_mul_f32_e32 v14, v11, v11
	v_fmac_f32_e32 v13, v8, v8
	v_fmac_f32_e32 v14, v10, v10
	v_add_f32_e32 v13, v13, v14
	v_add_f32_e32 v12, v12, v13
	v_add_f32_e32 v14, v26, v12
	v_mov_b32_e32 v15, v14
	s_nop 1
	v_permlane16_swap_b32_e32 v14, v15
	v_add_co_u32_e64 v12, s[36:37], s55, v32
	s_nop 1
	v_addc_co_u32_e64 v13, s[36:37], 0, v33, s[36:37]
	global_store_dwordx4 v[12:13], v[0:3], off
	s_waitcnt lgkmcnt(0)
	s_nop 0
	v_add_f32_e32 v0, v14, v15
	v_mov_b32_e32 v1, v0
	s_nop 1
	v_permlane32_swap_b32_e32 v0, v1
	v_cvt_pk_bf16_f32 v2, v4, v5
	v_cvt_pk_bf16_f32 v3, v6, v7
	v_cvt_pk_bf16_f32 v4, v8, v9
	v_cvt_pk_bf16_f32 v5, v10, v11
	global_store_dwordx4 v[24:25], v[2:5], off offset:256
	s_and_saveexec_b64 s[4:5], vcc
	s_cbranch_execz .LBB0_643
	s_waitcnt lgkmcnt(0)
	v_add_f32_e32 v0, v0, v1
	ds_write_b32 v122, v0 offset:2816

.LBB0_746:
	s_and_b32 s4, s49, 0xffffff00
	s_add_i32 s2, s4, 0
	v_lshl_add_u32 v128, v201, 2, s2
	v_add_u32_e32 v136, 0x21000, v128
	s_barrier
	ds_read2_b32 v[134:135], v136 offset1:16
	s_mov_b32 s2, 0xff61b1e6
	s_waitcnt lgkmcnt(0)
	v_mul_f32_e32 v128, 0x3db8aa3b, v134
	v_pk_mul_f32 v[184:185], v[126:127], v[128:129] op_sel_hi:[1,0]
	v_pk_mul_f32 v[188:189], v[124:125], v[128:129] op_sel_hi:[1,0]
	v_pk_mul_f32 v[122:123], v[122:123], v[128:129] op_sel_hi:[1,0]
	v_pk_mul_f32 v[120:121], v[120:121], v[128:129] op_sel_hi:[1,0]
	v_pk_mul_f32 v[126:127], v[118:119], v[128:129] op_sel_hi:[1,0]
	v_pk_mul_f32 v[124:125], v[116:117], v[128:129] op_sel_hi:[1,0]
	v_pk_mul_f32 v[130:131], v[114:115], v[128:129] op_sel_hi:[1,0]
	v_pk_mul_f32 v[128:129], v[112:113], v[128:129] op_sel_hi:[1,0]
	v_and_b32_e32 v113, 64, v197
	v_xor_b32_e32 v112, 16, v197
	v_add_u32_e32 v113, 64, v113
	v_cmp_lt_i32_e32 vcc, v112, v113
	v_max_f32_e32 v114, v122, v123
	v_max3_f32 v114, v120, v121, v114
	v_cndmask_b32_e32 v112, v197, v112, vcc
	v_lshlrev_b32_e32 v144, 2, v112
	v_max_f32_e32 v112, v184, v185
	v_max3_f32 v112, v188, v189, v112
	v_max3_f32 v112, v112, s2, v114
	v_max_f32_e32 v114, v126, v127
	v_max_f32_e32 v115, v130, v131
	v_max3_f32 v114, v124, v125, v114
	v_max3_f32 v115, v128, v129, v115
	v_max3_f32 v112, v112, v114, v115
	v_mov_b32_e32 v114, v112
	s_nop 1
	v_permlane16_swap_b32_e32 v112, v114
	v_xor_b32_e32 v115, 32, v197
	v_cmp_lt_i32_e32 vcc, v115, v113
	ds_read2_b32 v[132:133], v136 offset0:32 offset1:48
	ds_read2_b32 v[118:119], v136 offset0:128 offset1:144
	ds_read2_b32 v[116:117], v136 offset0:160 offset1:176
	v_cndmask_b32_e32 v113, v197, v115, vcc
	v_lshlrev_b32_e32 v202, 2, v113
	s_waitcnt lgkmcnt(0)
	v_max_f32_e32 v113, v114, v114
	v_max_f32_e32 v112, v112, v113
	v_mov_b32_e32 v113, v112
	s_nop 1
	v_permlane32_swap_b32_e32 v112, v113
	s_lshl_b32 s2, s0, 2
	v_cmp_eq_u32_e32 vcc, 0, v199
	s_add_i32 s5, s2, 0
	s_and_saveexec_b64 s[2:3], vcc
	s_cbranch_execz .LBB0_748
	s_lshl_b32 s6, s48, 10
	s_waitcnt lgkmcnt(0)
	v_max_f32_e32 v113, v113, v113
	v_max_f32_e32 v112, v112, v112
	s_add_i32 s6, s5, s6
	v_max_f32_e32 v112, v112, v113
	v_lshl_add_u32 v113, v201, 4, s6
	ds_write_b32 v113, v112
.LBB0_748:
	s_or_b64 exec, exec, s[2:3]
	v_mul_f32_e32 v112, 0x3db8aa3b, v135
	s_waitcnt lgkmcnt(0)
	v_pk_mul_f32 v[186:187], v[110:111], v[112:113] op_sel_hi:[1,0]
	v_pk_mul_f32 v[182:183], v[106:107], v[112:113] op_sel_hi:[1,0]
	v_pk_mul_f32 v[190:191], v[108:109], v[112:113] op_sel_hi:[1,0]
	v_pk_mul_f32 v[104:105], v[104:105], v[112:113] op_sel_hi:[1,0]
	v_pk_mul_f32 v[108:109], v[88:89], v[112:113] op_sel_hi:[1,0]
	v_max_f32_e32 v88, v186, v187
	v_max_f32_e32 v89, v182, v183
	v_pk_mul_f32 v[110:111], v[98:99], v[112:113] op_sel_hi:[1,0]
	v_pk_mul_f32 v[90:91], v[90:91], v[112:113] op_sel_hi:[1,0]
	v_max3_f32 v88, v190, v191, v88
	v_max3_f32 v89, v104, v105, v89
	s_mov_b32 s2, 0xff61b1e6
	v_pk_mul_f32 v[180:181], v[96:97], v[112:113] op_sel_hi:[1,0]
	v_max3_f32 v88, v88, s2, v89
	v_max_f32_e32 v89, v110, v111
	v_max_f32_e32 v96, v90, v91
	v_max3_f32 v89, v180, v181, v89
	v_max3_f32 v96, v108, v109, v96
	v_max3_f32 v88, v88, v89, v96
	v_mov_b32_e32 v89, v88
	s_nop 1
	v_permlane16_swap_b32_e32 v88, v89
	s_waitcnt lgkmcnt(0)
	v_max_f32_e32 v89, v89, v89
	v_max_f32_e32 v88, v88, v89
	v_mov_b32_e32 v89, v88
	s_nop 1
	v_permlane32_swap_b32_e32 v88, v89
	s_and_saveexec_b64 s[2:3], vcc
	s_cbranch_execz .LBB0_750
	s_lshl_b32 s6, s48, 10
	s_waitcnt lgkmcnt(0)
	v_max_f32_e32 v89, v89, v89
	v_max_f32_e32 v88, v88, v88
	s_add_i32 s6, s5, s6
	v_max_f32_e32 v88, v88, v89
	v_lshl_add_u32 v89, v201, 4, s6
	ds_write_b32 v89, v88 offset:256
.LBB0_750:
	s_or_b64 exec, exec, s[2:3]
	v_mul_f32_e32 v88, 0x3db8aa3b, v132
	s_waitcnt lgkmcnt(0)
	v_pk_mul_f32 v[174:175], v[102:103], v[88:89] op_sel_hi:[1,0]
	v_pk_mul_f32 v[98:99], v[94:95], v[88:89] op_sel_hi:[1,0]
	v_pk_mul_f32 v[178:179], v[100:101], v[88:89] op_sel_hi:[1,0]
	v_pk_mul_f32 v[176:177], v[92:93], v[88:89] op_sel_hi:[1,0]
	v_pk_mul_f32 v[112:113], v[72:73], v[88:89] op_sel_hi:[1,0]
	v_max_f32_e32 v72, v174, v175
	v_max_f32_e32 v73, v98, v99
	v_pk_mul_f32 v[106:107], v[82:83], v[88:89] op_sel_hi:[1,0]
	v_pk_mul_f32 v[114:115], v[74:75], v[88:89] op_sel_hi:[1,0]
	v_max3_f32 v72, v178, v179, v72
	v_max3_f32 v73, v176, v177, v73
	s_mov_b32 s2, 0xff61b1e6
	v_pk_mul_f32 v[100:101], v[80:81], v[88:89] op_sel_hi:[1,0]
	v_max3_f32 v72, v72, s2, v73
	v_max_f32_e32 v73, v106, v107
	v_max_f32_e32 v74, v114, v115
	v_max3_f32 v73, v100, v101, v73
	v_max3_f32 v74, v112, v113, v74
	v_max3_f32 v72, v72, v73, v74
	v_mov_b32_e32 v73, v72
	s_nop 1
	v_permlane16_swap_b32_e32 v72, v73
	s_waitcnt lgkmcnt(0)
	v_max_f32_e32 v73, v73, v73
	v_max_f32_e32 v72, v72, v73
	v_mov_b32_e32 v73, v72
	s_nop 1
	v_permlane32_swap_b32_e32 v72, v73
	s_and_saveexec_b64 s[2:3], vcc
	s_cbranch_execz .LBB0_752
	s_lshl_b32 s6, s48, 10
	s_waitcnt lgkmcnt(0)
	v_max_f32_e32 v73, v73, v73
	v_max_f32_e32 v72, v72, v72
	s_add_i32 s6, s5, s6
	v_max_f32_e32 v72, v72, v73
	v_lshl_add_u32 v73, v201, 4, s6
	ds_write_b32 v73, v72 offset:512
.LBB0_752:
	s_or_b64 exec, exec, s[2:3]
	v_mul_f32_e32 v74, 0x3db8aa3b, v133
	v_pk_mul_f32 v[168:169], v[86:87], v[74:75] op_sel_hi:[1,0]
	s_waitcnt lgkmcnt(0)
	v_pk_mul_f32 v[72:73], v[78:79], v[74:75] op_sel_hi:[1,0]
	v_pk_mul_f32 v[172:173], v[84:85], v[74:75] op_sel_hi:[1,0]
	v_pk_mul_f32 v[170:171], v[76:77], v[74:75] op_sel_hi:[1,0]
	v_pk_mul_f32 v[76:77], v[64:65], v[74:75] op_sel_hi:[1,0]
	v_max_f32_e32 v64, v168, v169
	v_max_f32_e32 v65, v72, v73
	v_pk_mul_f32 v[70:71], v[70:71], v[74:75] op_sel_hi:[1,0]
	v_pk_mul_f32 v[78:79], v[66:67], v[74:75] op_sel_hi:[1,0]
	v_max3_f32 v64, v172, v173, v64
	v_max3_f32 v65, v170, v171, v65
	s_mov_b32 s2, 0xff61b1e6
	v_pk_mul_f32 v[166:167], v[68:69], v[74:75] op_sel_hi:[1,0]
	v_max3_f32 v64, v64, s2, v65
	v_max_f32_e32 v65, v70, v71
	v_max_f32_e32 v66, v78, v79
	v_max3_f32 v65, v166, v167, v65
	v_max3_f32 v66, v76, v77, v66
	v_max3_f32 v64, v64, v65, v66
	v_mov_b32_e32 v65, v64
	s_nop 1
	v_permlane16_swap_b32_e32 v64, v65
	s_waitcnt lgkmcnt(0)
	v_max_f32_e32 v65, v65, v65
	v_max_f32_e32 v64, v64, v65
	v_mov_b32_e32 v65, v64
	s_nop 1
	v_permlane32_swap_b32_e32 v64, v65
	s_and_saveexec_b64 s[2:3], vcc
	s_cbranch_execz .LBB0_754
	s_lshl_b32 s6, s48, 10
	s_waitcnt lgkmcnt(0)
	v_max_f32_e32 v65, v65, v65
	v_max_f32_e32 v64, v64, v64
	s_add_i32 s6, s5, s6
	v_max_f32_e32 v64, v64, v65
	v_lshl_add_u32 v65, v201, 4, s6
	ds_write_b32 v65, v64 offset:768
.LBB0_754:
	s_or_b64 exec, exec, s[2:3]
	v_mul_f32_e32 v64, 0x3db8aa3b, v118
	s_waitcnt lgkmcnt(0)
	v_pk_mul_f32 v[162:163], v[62:63], v[64:65] op_sel_hi:[1,0]
	v_pk_mul_f32 v[66:67], v[58:59], v[64:65] op_sel_hi:[1,0]
	v_pk_mul_f32 v[164:165], v[60:61], v[64:65] op_sel_hi:[1,0]
	v_pk_mul_f32 v[58:59], v[56:57], v[64:65] op_sel_hi:[1,0]
	v_pk_mul_f32 v[80:81], v[40:41], v[64:65] op_sel_hi:[1,0]
	v_max_f32_e32 v40, v162, v163
	v_max_f32_e32 v41, v66, v67
	v_pk_mul_f32 v[74:75], v[50:51], v[64:65] op_sel_hi:[1,0]
	v_pk_mul_f32 v[82:83], v[42:43], v[64:65] op_sel_hi:[1,0]
	v_max3_f32 v40, v164, v165, v40
	v_max3_f32 v41, v58, v59, v41
	s_mov_b32 s2, 0xff61b1e6
	v_pk_mul_f32 v[68:69], v[48:49], v[64:65] op_sel_hi:[1,0]
	v_max3_f32 v40, v40, s2, v41
	v_max_f32_e32 v41, v74, v75
	v_max_f32_e32 v42, v82, v83
	v_max3_f32 v41, v68, v69, v41
	v_max3_f32 v42, v80, v81, v42
	v_max3_f32 v40, v40, v41, v42
	v_mov_b32_e32 v41, v40
	s_nop 1
	v_permlane16_swap_b32_e32 v40, v41
	s_waitcnt lgkmcnt(0)
	v_max_f32_e32 v41, v41, v41
	v_max_f32_e32 v40, v40, v41
	v_mov_b32_e32 v41, v40
	s_nop 1
	v_permlane32_swap_b32_e32 v40, v41
	s_and_saveexec_b64 s[2:3], vcc
	s_cbranch_execz .LBB0_756
	s_lshl_b32 s6, s48, 10
	s_waitcnt lgkmcnt(0)
	v_max_f32_e32 v41, v41, v41
	v_max_f32_e32 v40, v40, v40
	s_add_i32 s6, s5, s6
	v_max_f32_e32 v40, v40, v41
	v_lshl_add_u32 v41, v201, 4, s6
	ds_write_b32 v41, v40 offset:2048
.LBB0_756:
	s_or_b64 exec, exec, s[2:3]
	v_mul_f32_e32 v42, 0x3db8aa3b, v119
	v_pk_mul_f32 v[156:157], v[54:55], v[42:43] op_sel_hi:[1,0]
	s_waitcnt lgkmcnt(0)
	v_pk_mul_f32 v[40:41], v[46:47], v[42:43] op_sel_hi:[1,0]
	v_pk_mul_f32 v[160:161], v[52:53], v[42:43] op_sel_hi:[1,0]
	v_pk_mul_f32 v[158:159], v[44:45], v[42:43] op_sel_hi:[1,0]
	v_pk_mul_f32 v[44:45], v[24:25], v[42:43] op_sel_hi:[1,0]
	v_max_f32_e32 v24, v156, v157
	v_max_f32_e32 v25, v40, v41
	v_pk_mul_f32 v[46:47], v[34:35], v[42:43] op_sel_hi:[1,0]
	v_pk_mul_f32 v[26:27], v[26:27], v[42:43] op_sel_hi:[1,0]
	v_max3_f32 v24, v160, v161, v24
	v_max3_f32 v25, v158, v159, v25
	s_mov_b32 s2, 0xff61b1e6
	v_pk_mul_f32 v[142:143], v[32:33], v[42:43] op_sel_hi:[1,0]
	v_max3_f32 v24, v24, s2, v25
	v_max_f32_e32 v25, v46, v47
	v_max_f32_e32 v32, v26, v27
	v_max3_f32 v25, v142, v143, v25
	v_max3_f32 v32, v44, v45, v32
	v_max3_f32 v24, v24, v25, v32
	v_mov_b32_e32 v25, v24
	s_nop 1
	v_permlane16_swap_b32_e32 v24, v25
	s_waitcnt lgkmcnt(0)
	v_max_f32_e32 v25, v25, v25
	v_max_f32_e32 v24, v24, v25
	v_mov_b32_e32 v25, v24
	s_nop 1
	v_permlane32_swap_b32_e32 v24, v25
	s_and_saveexec_b64 s[2:3], vcc
	s_cbranch_execz .LBB0_758
	s_lshl_b32 s6, s48, 10
	s_waitcnt lgkmcnt(0)
	v_max_f32_e32 v25, v25, v25
	v_max_f32_e32 v24, v24, v24
	s_add_i32 s6, s5, s6
	v_max_f32_e32 v24, v24, v25
	v_lshl_add_u32 v25, v201, 4, s6
	ds_write_b32 v25, v24 offset:2304
.LBB0_758:
	s_or_b64 exec, exec, s[2:3]
	v_mul_f32_e32 v24, 0x3db8aa3b, v116
	s_waitcnt lgkmcnt(0)
	v_pk_mul_f32 v[136:137], v[38:39], v[24:25] op_sel_hi:[1,0]
	v_pk_mul_f32 v[34:35], v[30:31], v[24:25] op_sel_hi:[1,0]
	v_pk_mul_f32 v[140:141], v[36:37], v[24:25] op_sel_hi:[1,0]
	v_pk_mul_f32 v[138:139], v[28:29], v[24:25] op_sel_hi:[1,0]
	v_pk_mul_f32 v[48:49], v[8:9], v[24:25] op_sel_hi:[1,0]
	v_max_f32_e32 v8, v136, v137
	v_max_f32_e32 v9, v34, v35
	v_pk_mul_f32 v[42:43], v[18:19], v[24:25] op_sel_hi:[1,0]
	v_pk_mul_f32 v[50:51], v[10:11], v[24:25] op_sel_hi:[1,0]
	v_max3_f32 v8, v140, v141, v8
	v_max3_f32 v9, v138, v139, v9
	s_mov_b32 s2, 0xff61b1e6
	v_pk_mul_f32 v[36:37], v[16:17], v[24:25] op_sel_hi:[1,0]
	v_max3_f32 v8, v8, s2, v9
	v_max_f32_e32 v9, v42, v43
	v_max_f32_e32 v10, v50, v51
	v_max3_f32 v9, v36, v37, v9
	v_max3_f32 v10, v48, v49, v10
	v_max3_f32 v8, v8, v9, v10
	v_mov_b32_e32 v9, v8
	s_nop 1
	v_permlane16_swap_b32_e32 v8, v9
	s_waitcnt lgkmcnt(0)
	v_max_f32_e32 v9, v9, v9
	v_max_f32_e32 v8, v8, v9
	v_mov_b32_e32 v9, v8
	s_nop 1
	v_permlane32_swap_b32_e32 v8, v9
	s_and_saveexec_b64 s[2:3], vcc
	s_cbranch_execz .LBB0_760
	s_lshl_b32 s6, s48, 10
	s_waitcnt lgkmcnt(0)
	v_max_f32_e32 v9, v9, v9
	v_max_f32_e32 v8, v8, v8
	s_add_i32 s6, s5, s6
	v_max_f32_e32 v8, v8, v9
	v_lshl_add_u32 v9, v201, 4, s6
	ds_write_b32 v9, v8 offset:2560
.LBB0_760:
	s_or_b64 exec, exec, s[2:3]
	v_mul_f32_e32 v10, 0x3db8aa3b, v117
	v_pk_mul_f32 v[132:133], v[22:23], v[10:11] op_sel_hi:[1,0]
	v_pk_mul_f32 v[18:19], v[14:15], v[10:11] op_sel_hi:[1,0]
	v_pk_mul_f32 v[134:135], v[20:21], v[10:11] op_sel_hi:[1,0]
	v_pk_mul_f32 v[12:13], v[12:13], v[10:11] op_sel_hi:[1,0]
	s_waitcnt lgkmcnt(0)
	v_pk_mul_f32 v[8:9], v[6:7], v[10:11] op_sel_hi:[1,0]
	v_pk_mul_f32 v[16:17], v[4:5], v[10:11] op_sel_hi:[1,0]
	v_pk_mul_f32 v[14:15], v[2:3], v[10:11] op_sel_hi:[1,0]
	v_pk_mul_f32 v[10:11], v[0:1], v[10:11] op_sel_hi:[1,0]
	v_max_f32_e32 v0, v132, v133
	v_max_f32_e32 v1, v18, v19
	v_max3_f32 v0, v134, v135, v0
	v_max3_f32 v1, v12, v13, v1
	s_mov_b32 s2, 0xff61b1e6
	v_max3_f32 v0, v0, s2, v1
	v_max_f32_e32 v1, v8, v9
	v_max_f32_e32 v2, v14, v15
	v_max3_f32 v1, v16, v17, v1
	v_max3_f32 v2, v10, v11, v2
	v_max3_f32 v0, v0, v1, v2
	v_mov_b32_e32 v1, v0
	s_nop 1
	v_permlane16_swap_b32_e32 v0, v1
	s_waitcnt lgkmcnt(0)
	v_max_f32_e32 v1, v1, v1
	v_max_f32_e32 v0, v0, v1
	v_mov_b32_e32 v1, v0
	s_nop 1
	v_permlane32_swap_b32_e32 v0, v1
	s_and_saveexec_b64 s[2:3], vcc
	s_cbranch_execz .LBB0_762
	s_lshl_b32 s6, s48, 10
	s_waitcnt lgkmcnt(0)
	v_max_f32_e32 v1, v1, v1
	v_max_f32_e32 v0, v0, v0
	s_add_i32 s6, s5, s6
	v_max_f32_e32 v0, v0, v1
	v_lshl_add_u32 v1, v201, 4, s6
	ds_write_b32 v1, v0 offset:2816
.LBB0_762:
	s_or_b64 exec, exec, s[2:3]
	v_or_b32_e32 v6, s4, v200
	s_waitcnt lgkmcnt(0)
	s_barrier
	v_lshl_add_u32 v0, v6, 2, 0
	ds_read_b128 v[2:5], v0
	s_waitcnt lgkmcnt(0)
	v_max_f32_e32 v1, v5, v5
	v_max_f32_e32 v4, v4, v4
	v_max_f32_e32 v1, v4, v1
	v_max3_f32 v1, v2, v3, v1
	v_sub_f32_e32 v2, v188, v1
	v_exp_f32_e32 v116, v2
	v_sub_f32_e32 v2, v189, v1
	v_sub_f32_e32 v4, v120, v1
	v_exp_f32_e32 v117, v2
	v_sub_f32_e32 v2, v184, v1
	v_exp_f32_e32 v120, v4
	v_sub_f32_e32 v4, v121, v1
	v_sub_f32_e32 v5, v124, v1
	v_exp_f32_e32 v118, v2
	v_sub_f32_e32 v2, v185, v1
	v_exp_f32_e32 v121, v4
	v_sub_f32_e32 v4, v122, v1
	v_exp_f32_e32 v124, v5
	v_sub_f32_e32 v5, v125, v1
	v_exp_f32_e32 v119, v2
	v_exp_f32_e32 v122, v4
	v_sub_f32_e32 v4, v123, v1
	v_exp_f32_e32 v125, v5
	v_sub_f32_e32 v5, v126, v1
	v_exp_f32_e32 v123, v4
	v_exp_f32_e32 v126, v5
	v_sub_f32_e32 v5, v127, v1
	v_exp_f32_e32 v127, v5
	v_sub_f32_e32 v5, v128, v1
	v_exp_f32_e32 v128, v5
	v_sub_f32_e32 v5, v129, v1
	v_add_f32_e32 v2, v116, v117
	v_add_f32_e32 v3, v118, v119
	v_exp_f32_e32 v129, v5
	v_sub_f32_e32 v5, v130, v1
	v_sub_f32_e32 v1, v131, v1
	v_add_f32_e32 v2, v2, v3
	v_add_f32_e32 v3, v120, v121
	v_add_f32_e32 v4, v122, v123
	v_exp_f32_e32 v130, v5
	v_exp_f32_e32 v131, v1
	v_add_f32_e32 v2, 0, v2
	v_add_f32_e32 v3, v3, v4
	v_add_f32_e32 v2, v3, v2
	v_add_f32_e32 v3, v124, v125
	v_add_f32_e32 v4, v126, v127
	v_add_f32_e32 v1, v3, v4
	v_add_f32_e32 v1, v1, v2
	v_add_f32_e32 v2, v128, v129
	v_add_f32_e32 v3, v130, v131
	v_add_f32_e32 v2, v2, v3
	v_add_f32_e32 v1, v2, v1
	v_mov_b32_e32 v2, v1
	s_nop 1
	v_permlane16_swap_b32_e32 v1, v2
	v_lshl_add_u32 v184, v6, 2, s5
	s_waitcnt lgkmcnt(0)
	v_add_f32_e32 v1, v1, v2
	v_mov_b32_e32 v2, v1
	s_nop 1
	v_permlane32_swap_b32_e32 v1, v2
	s_and_saveexec_b64 s[2:3], vcc
	s_cbranch_execz .LBB0_764
	s_waitcnt lgkmcnt(0)
	v_add_f32_e32 v1, v1, v2
	ds_write_b32 v184, v1 offset:4096
.LBB0_764:
	s_or_b64 exec, exec, s[2:3]
	s_waitcnt lgkmcnt(0)
	ds_read_b128 v[2:5], v0 offset:256
	s_waitcnt lgkmcnt(0)
	v_max_f32_e32 v1, v5, v5
	v_max_f32_e32 v4, v4, v4
	v_max_f32_e32 v1, v4, v1
	v_max3_f32 v1, v2, v3, v1
	v_sub_f32_e32 v4, v186, v1
	v_exp_f32_e32 v96, v4
	v_sub_f32_e32 v4, v104, v1
	v_sub_f32_e32 v2, v190, v1
	v_exp_f32_e32 v94, v4
	v_sub_f32_e32 v4, v105, v1
	v_sub_f32_e32 v5, v180, v1
	v_sub_f32_e32 v3, v191, v1
	v_exp_f32_e32 v88, v2
	v_sub_f32_e32 v2, v187, v1
	v_exp_f32_e32 v95, v4
	v_sub_f32_e32 v4, v182, v1
	v_exp_f32_e32 v92, v5
	v_sub_f32_e32 v5, v181, v1
	v_exp_f32_e32 v89, v3
	v_exp_f32_e32 v97, v2
	v_exp_f32_e32 v104, v4
	v_sub_f32_e32 v4, v183, v1
	v_exp_f32_e32 v93, v5
	v_sub_f32_e32 v5, v110, v1
	v_exp_f32_e32 v105, v4
	v_exp_f32_e32 v102, v5
	v_sub_f32_e32 v5, v111, v1
	v_exp_f32_e32 v103, v5
	v_sub_f32_e32 v5, v108, v1
	v_exp_f32_e32 v108, v5
	v_sub_f32_e32 v5, v109, v1
	v_add_f32_e32 v2, v88, v89
	v_add_f32_e32 v3, v96, v97
	v_exp_f32_e32 v109, v5
	v_sub_f32_e32 v5, v90, v1
	v_sub_f32_e32 v1, v91, v1
	v_add_f32_e32 v2, v2, v3
	v_add_f32_e32 v3, v94, v95
	v_add_f32_e32 v4, v104, v105
	v_exp_f32_e32 v110, v5
	v_exp_f32_e32 v111, v1
	v_add_f32_e32 v2, 0, v2
	v_add_f32_e32 v3, v3, v4
	v_add_f32_e32 v2, v3, v2
	v_add_f32_e32 v3, v92, v93
	v_add_f32_e32 v4, v102, v103
	v_add_f32_e32 v1, v3, v4
	v_add_f32_e32 v1, v1, v2
	v_add_f32_e32 v2, v108, v109
	v_add_f32_e32 v3, v110, v111
	v_add_f32_e32 v2, v2, v3
	v_add_f32_e32 v1, v2, v1
	v_mov_b32_e32 v2, v1
	s_nop 1
	v_permlane16_swap_b32_e32 v1, v2
	s_waitcnt lgkmcnt(0)
	v_add_f32_e32 v1, v1, v2
	v_mov_b32_e32 v2, v1
	s_nop 1
	v_permlane32_swap_b32_e32 v1, v2
	s_and_saveexec_b64 s[2:3], vcc
	s_cbranch_execz .LBB0_766
	s_waitcnt lgkmcnt(0)
	v_add_f32_e32 v1, v1, v2
	ds_write_b32 v184, v1 offset:4352
.LBB0_766:
	s_or_b64 exec, exec, s[2:3]
	s_waitcnt lgkmcnt(0)
	ds_read_b128 v[2:5], v0 offset:512
	s_waitcnt lgkmcnt(0)
	v_max_f32_e32 v1, v5, v5
	v_max_f32_e32 v4, v4, v4
	v_max_f32_e32 v1, v4, v1
	v_max3_f32 v1, v2, v3, v1
	v_sub_f32_e32 v4, v174, v1
	v_exp_f32_e32 v86, v4
	v_sub_f32_e32 v4, v176, v1
	v_sub_f32_e32 v2, v178, v1
	v_exp_f32_e32 v90, v4
	v_sub_f32_e32 v4, v177, v1
	v_sub_f32_e32 v5, v100, v1
	v_sub_f32_e32 v3, v179, v1
	v_exp_f32_e32 v84, v2
	v_sub_f32_e32 v2, v175, v1
	v_exp_f32_e32 v91, v4
	v_sub_f32_e32 v4, v98, v1
	v_exp_f32_e32 v100, v5
	v_sub_f32_e32 v5, v101, v1
	v_exp_f32_e32 v85, v3
	v_exp_f32_e32 v87, v2
	v_exp_f32_e32 v98, v4
	v_sub_f32_e32 v4, v99, v1
	v_exp_f32_e32 v101, v5
	v_sub_f32_e32 v5, v106, v1
	v_exp_f32_e32 v99, v4
	v_exp_f32_e32 v106, v5
	v_sub_f32_e32 v5, v107, v1
	v_exp_f32_e32 v107, v5
	v_sub_f32_e32 v5, v112, v1
	v_exp_f32_e32 v112, v5
	v_sub_f32_e32 v5, v113, v1
	v_add_f32_e32 v2, v84, v85
	v_add_f32_e32 v3, v86, v87
	v_exp_f32_e32 v113, v5
	v_sub_f32_e32 v5, v114, v1
	v_sub_f32_e32 v1, v115, v1
	v_add_f32_e32 v2, v2, v3
	v_add_f32_e32 v3, v90, v91
	v_add_f32_e32 v4, v98, v99
	v_exp_f32_e32 v114, v5
	v_exp_f32_e32 v115, v1
	v_add_f32_e32 v2, 0, v2
	v_add_f32_e32 v3, v3, v4
	v_add_f32_e32 v2, v3, v2
	v_add_f32_e32 v3, v100, v101
	v_add_f32_e32 v4, v106, v107
	v_add_f32_e32 v1, v3, v4
	v_add_f32_e32 v1, v1, v2
	v_add_f32_e32 v2, v112, v113
	v_add_f32_e32 v3, v114, v115
	v_add_f32_e32 v2, v2, v3
	v_add_f32_e32 v1, v2, v1
	v_mov_b32_e32 v2, v1
	s_nop 1
	v_permlane16_swap_b32_e32 v1, v2
	s_waitcnt lgkmcnt(0)
	v_add_f32_e32 v1, v1, v2
	v_mov_b32_e32 v2, v1
	s_nop 1
	v_permlane32_swap_b32_e32 v1, v2
	s_and_saveexec_b64 s[2:3], vcc
	s_cbranch_execz .LBB0_768
	s_waitcnt lgkmcnt(0)
	v_add_f32_e32 v1, v1, v2
	ds_write_b32 v184, v1 offset:4608
.LBB0_768:
	s_or_b64 exec, exec, s[2:3]
	s_waitcnt lgkmcnt(0)
	ds_read_b128 v[2:5], v0 offset:768
	s_waitcnt lgkmcnt(0)
	v_max_f32_e32 v1, v5, v5
	v_max_f32_e32 v4, v4, v4
	v_max_f32_e32 v1, v4, v1
	v_max3_f32 v1, v2, v3, v1
	v_sub_f32_e32 v4, v168, v1
	v_exp_f32_e32 v64, v4
	v_sub_f32_e32 v4, v170, v1
	v_sub_f32_e32 v2, v172, v1
	v_exp_f32_e32 v62, v4
	v_sub_f32_e32 v4, v171, v1
	v_sub_f32_e32 v5, v166, v1
	v_sub_f32_e32 v3, v173, v1
	v_exp_f32_e32 v56, v2
	v_sub_f32_e32 v2, v169, v1
	v_exp_f32_e32 v63, v4
	v_sub_f32_e32 v4, v72, v1
	v_exp_f32_e32 v60, v5
	v_sub_f32_e32 v5, v167, v1
	v_exp_f32_e32 v57, v3
	v_exp_f32_e32 v65, v2
	v_exp_f32_e32 v72, v4
	v_sub_f32_e32 v4, v73, v1
	v_exp_f32_e32 v61, v5
	v_sub_f32_e32 v5, v70, v1
	v_exp_f32_e32 v73, v4
	v_exp_f32_e32 v70, v5
	v_sub_f32_e32 v5, v71, v1
	v_exp_f32_e32 v71, v5
	v_sub_f32_e32 v5, v76, v1
	v_exp_f32_e32 v76, v5
	v_sub_f32_e32 v5, v77, v1
	v_add_f32_e32 v2, v56, v57
	v_add_f32_e32 v3, v64, v65
	v_exp_f32_e32 v77, v5
	v_sub_f32_e32 v5, v78, v1
	v_sub_f32_e32 v1, v79, v1
	v_add_f32_e32 v2, v2, v3
	v_add_f32_e32 v3, v62, v63
	v_add_f32_e32 v4, v72, v73
	v_exp_f32_e32 v78, v5
	v_exp_f32_e32 v79, v1
	v_add_f32_e32 v2, 0, v2
	v_add_f32_e32 v3, v3, v4
	v_add_f32_e32 v2, v3, v2
	v_add_f32_e32 v3, v60, v61
	v_add_f32_e32 v4, v70, v71
	v_add_f32_e32 v1, v3, v4
	v_add_f32_e32 v1, v1, v2
	v_add_f32_e32 v2, v76, v77
	v_add_f32_e32 v3, v78, v79
	v_add_f32_e32 v2, v2, v3
	v_add_f32_e32 v1, v2, v1
	v_mov_b32_e32 v2, v1
	s_nop 1
	v_permlane16_swap_b32_e32 v1, v2
	s_waitcnt lgkmcnt(0)
	v_add_f32_e32 v1, v1, v2
	v_mov_b32_e32 v2, v1
	s_nop 1
	v_permlane32_swap_b32_e32 v1, v2
	s_and_saveexec_b64 s[2:3], vcc
	s_cbranch_execz .LBB0_770
	s_waitcnt lgkmcnt(0)
	v_add_f32_e32 v1, v1, v2
	ds_write_b32 v184, v1 offset:4864
.LBB0_770:
	s_or_b64 exec, exec, s[2:3]
	s_waitcnt lgkmcnt(0)
	ds_read_b128 v[2:5], v0 offset:2048
	s_waitcnt lgkmcnt(0)
	v_max_f32_e32 v1, v5, v5
	v_max_f32_e32 v4, v4, v4
	v_max_f32_e32 v1, v4, v1
	v_max3_f32 v1, v2, v3, v1
	v_sub_f32_e32 v4, v162, v1
	v_exp_f32_e32 v54, v4
	v_sub_f32_e32 v4, v58, v1
	v_sub_f32_e32 v2, v164, v1
	v_exp_f32_e32 v58, v4
	v_sub_f32_e32 v4, v59, v1
	v_sub_f32_e32 v5, v68, v1
	v_sub_f32_e32 v3, v165, v1
	v_exp_f32_e32 v52, v2
	v_sub_f32_e32 v2, v163, v1
	v_exp_f32_e32 v59, v4
	v_sub_f32_e32 v4, v66, v1
	v_exp_f32_e32 v68, v5
	v_sub_f32_e32 v5, v69, v1
	v_exp_f32_e32 v53, v3
	v_exp_f32_e32 v55, v2
	v_exp_f32_e32 v66, v4
	v_sub_f32_e32 v4, v67, v1
	v_exp_f32_e32 v69, v5
	v_sub_f32_e32 v5, v74, v1
	v_exp_f32_e32 v67, v4
	v_exp_f32_e32 v74, v5
	v_sub_f32_e32 v5, v75, v1
	v_exp_f32_e32 v75, v5
	v_sub_f32_e32 v5, v80, v1
	v_exp_f32_e32 v80, v5
	v_sub_f32_e32 v5, v81, v1
	v_add_f32_e32 v2, v52, v53
	v_add_f32_e32 v3, v54, v55
	v_exp_f32_e32 v81, v5
	v_sub_f32_e32 v5, v82, v1
	v_sub_f32_e32 v1, v83, v1
	v_add_f32_e32 v2, v2, v3
	v_add_f32_e32 v3, v58, v59
	v_add_f32_e32 v4, v66, v67
	v_exp_f32_e32 v82, v5
	v_exp_f32_e32 v83, v1
	v_add_f32_e32 v2, 0, v2
	v_add_f32_e32 v3, v3, v4
	v_add_f32_e32 v2, v3, v2
	v_add_f32_e32 v3, v68, v69
	v_add_f32_e32 v4, v74, v75
	v_add_f32_e32 v1, v3, v4
	v_add_f32_e32 v1, v1, v2
	v_add_f32_e32 v2, v80, v81
	v_add_f32_e32 v3, v82, v83
	v_add_f32_e32 v2, v2, v3
	v_add_f32_e32 v1, v2, v1
	v_mov_b32_e32 v2, v1
	s_nop 1
	v_permlane16_swap_b32_e32 v1, v2
	s_waitcnt lgkmcnt(0)
	v_add_f32_e32 v1, v1, v2
	v_mov_b32_e32 v2, v1
	s_nop 1
	v_permlane32_swap_b32_e32 v1, v2
	s_and_saveexec_b64 s[2:3], vcc
	s_cbranch_execz .LBB0_772
	s_waitcnt lgkmcnt(0)
	v_add_f32_e32 v1, v1, v2
	ds_write_b32 v184, v1 offset:6144
.LBB0_772:
	s_or_b64 exec, exec, s[2:3]
	s_waitcnt lgkmcnt(0)
	ds_read_b128 v[2:5], v0 offset:2304
	s_waitcnt lgkmcnt(0)
	v_max_f32_e32 v1, v5, v5
	v_max_f32_e32 v4, v4, v4
	v_max_f32_e32 v1, v4, v1
	v_max3_f32 v1, v2, v3, v1
	v_sub_f32_e32 v4, v156, v1
	v_exp_f32_e32 v32, v4
	v_sub_f32_e32 v4, v158, v1
	v_sub_f32_e32 v2, v160, v1
	v_exp_f32_e32 v30, v4
	v_sub_f32_e32 v4, v159, v1
	v_sub_f32_e32 v5, v142, v1
	v_sub_f32_e32 v3, v161, v1
	v_exp_f32_e32 v24, v2
	v_sub_f32_e32 v2, v157, v1
	v_exp_f32_e32 v31, v4
	v_sub_f32_e32 v4, v40, v1
	v_exp_f32_e32 v28, v5
	v_sub_f32_e32 v5, v143, v1
	v_exp_f32_e32 v25, v3
	v_exp_f32_e32 v33, v2
	v_exp_f32_e32 v40, v4
	v_sub_f32_e32 v4, v41, v1
	v_exp_f32_e32 v29, v5
	v_sub_f32_e32 v5, v46, v1
	v_exp_f32_e32 v41, v4
	v_exp_f32_e32 v38, v5
	v_sub_f32_e32 v5, v47, v1
	v_exp_f32_e32 v39, v5
	v_sub_f32_e32 v5, v44, v1
	v_exp_f32_e32 v44, v5
	v_sub_f32_e32 v5, v45, v1
	v_add_f32_e32 v2, v24, v25
	v_add_f32_e32 v3, v32, v33
	v_exp_f32_e32 v45, v5
	v_sub_f32_e32 v5, v26, v1
	v_sub_f32_e32 v1, v27, v1
	v_add_f32_e32 v2, v2, v3
	v_add_f32_e32 v3, v30, v31
	v_add_f32_e32 v4, v40, v41
	v_exp_f32_e32 v46, v5
	v_exp_f32_e32 v47, v1
	v_add_f32_e32 v2, 0, v2
	v_add_f32_e32 v3, v3, v4
	v_add_f32_e32 v2, v3, v2
	v_add_f32_e32 v3, v28, v29
	v_add_f32_e32 v4, v38, v39
	v_add_f32_e32 v1, v3, v4
	v_add_f32_e32 v1, v1, v2
	v_add_f32_e32 v2, v44, v45
	v_add_f32_e32 v3, v46, v47
	v_add_f32_e32 v2, v2, v3
	v_add_f32_e32 v1, v2, v1
	v_mov_b32_e32 v2, v1
	s_nop 1
	v_permlane16_swap_b32_e32 v1, v2
	s_waitcnt lgkmcnt(0)
	v_add_f32_e32 v1, v1, v2
	v_mov_b32_e32 v2, v1
	s_nop 1
	v_permlane32_swap_b32_e32 v1, v2
	s_and_saveexec_b64 s[2:3], vcc
	s_cbranch_execz .LBB0_774
	s_waitcnt lgkmcnt(0)
	v_add_f32_e32 v1, v1, v2
	ds_write_b32 v184, v1 offset:6400
.LBB0_774:
	s_or_b64 exec, exec, s[2:3]
	s_waitcnt lgkmcnt(0)
	ds_read_b128 v[2:5], v0 offset:2560
	s_waitcnt lgkmcnt(0)
	v_max_f32_e32 v1, v5, v5
	v_max_f32_e32 v4, v4, v4
	v_max_f32_e32 v1, v4, v1
	v_max3_f32 v1, v2, v3, v1
	v_sub_f32_e32 v4, v136, v1
	v_exp_f32_e32 v22, v4
	v_sub_f32_e32 v4, v138, v1
	v_sub_f32_e32 v2, v140, v1
	v_exp_f32_e32 v26, v4
	v_sub_f32_e32 v4, v139, v1
	v_sub_f32_e32 v5, v36, v1
	v_sub_f32_e32 v3, v141, v1
	v_exp_f32_e32 v20, v2
	v_sub_f32_e32 v2, v137, v1
	v_exp_f32_e32 v27, v4
	v_sub_f32_e32 v4, v34, v1
	v_exp_f32_e32 v36, v5
	v_sub_f32_e32 v5, v37, v1
	v_exp_f32_e32 v21, v3
	v_exp_f32_e32 v23, v2
	v_exp_f32_e32 v34, v4
	v_sub_f32_e32 v4, v35, v1
	v_exp_f32_e32 v37, v5
	v_sub_f32_e32 v5, v42, v1
	v_exp_f32_e32 v35, v4
	v_exp_f32_e32 v42, v5
	v_sub_f32_e32 v5, v43, v1
	v_exp_f32_e32 v43, v5
	v_sub_f32_e32 v5, v48, v1
	v_exp_f32_e32 v48, v5
	v_sub_f32_e32 v5, v49, v1
	v_add_f32_e32 v2, v20, v21
	v_add_f32_e32 v3, v22, v23
	v_exp_f32_e32 v49, v5
	v_sub_f32_e32 v5, v50, v1
	v_sub_f32_e32 v1, v51, v1
	v_add_f32_e32 v2, v2, v3
	v_add_f32_e32 v3, v26, v27
	v_add_f32_e32 v4, v34, v35
	v_exp_f32_e32 v50, v5
	v_exp_f32_e32 v51, v1
	v_add_f32_e32 v2, 0, v2
	v_add_f32_e32 v3, v3, v4
	v_add_f32_e32 v2, v3, v2
	v_add_f32_e32 v3, v36, v37
	v_add_f32_e32 v4, v42, v43
	v_add_f32_e32 v1, v3, v4
	v_add_f32_e32 v1, v1, v2
	v_add_f32_e32 v2, v48, v49
	v_add_f32_e32 v3, v50, v51
	v_add_f32_e32 v2, v2, v3
	v_add_f32_e32 v1, v2, v1
	v_mov_b32_e32 v2, v1
	s_nop 1
	v_permlane16_swap_b32_e32 v1, v2
	s_waitcnt lgkmcnt(0)
	v_add_f32_e32 v1, v1, v2
	v_mov_b32_e32 v2, v1
	s_nop 1
	v_permlane32_swap_b32_e32 v1, v2
	s_and_saveexec_b64 s[2:3], vcc
	s_cbranch_execz .LBB0_776
	s_waitcnt lgkmcnt(0)
	v_add_f32_e32 v1, v1, v2
	ds_write_b32 v184, v1 offset:6656
.LBB0_776:
	s_or_b64 exec, exec, s[2:3]
	s_waitcnt lgkmcnt(0)
	ds_read_b128 v[0:3], v0 offset:2816
	s_waitcnt lgkmcnt(0)
	v_max_f32_e32 v3, v3, v3
	v_max_f32_e32 v2, v2, v2
	v_max_f32_e32 v2, v2, v3
	v_max3_f32 v136, v0, v1, v2
	v_sub_f32_e32 v2, v132, v136
	v_sub_f32_e32 v0, v134, v136
	v_sub_f32_e32 v1, v135, v136
	v_exp_f32_e32 v6, v2
	v_sub_f32_e32 v2, v133, v136
	v_exp_f32_e32 v0, v0
	v_exp_f32_e32 v1, v1
	v_exp_f32_e32 v7, v2
	v_sub_f32_e32 v4, v12, v136
	v_sub_f32_e32 v5, v13, v136
	v_add_f32_e32 v2, v0, v1
	v_add_f32_e32 v3, v6, v7
	v_sub_f32_e32 v12, v18, v136
	v_sub_f32_e32 v13, v19, v136
	v_exp_f32_e32 v4, v4
	v_exp_f32_e32 v5, v5
	v_exp_f32_e32 v12, v12
	v_exp_f32_e32 v13, v13
	v_add_f32_e32 v2, v2, v3
	v_add_f32_e32 v18, 0, v2
	v_sub_f32_e32 v2, v16, v136
	v_sub_f32_e32 v3, v17, v136
	v_sub_f32_e32 v8, v8, v136
	v_sub_f32_e32 v9, v9, v136
	v_exp_f32_e32 v2, v2
	v_exp_f32_e32 v3, v3
	v_exp_f32_e32 v8, v8
	v_exp_f32_e32 v9, v9
	v_sub_f32_e32 v10, v10, v136
	v_sub_f32_e32 v11, v11, v136
	v_sub_f32_e32 v14, v14, v136
	v_sub_f32_e32 v15, v15, v136
	v_add_f32_e32 v19, v4, v5
	v_add_f32_e32 v132, v12, v13
	v_exp_f32_e32 v10, v10
	v_exp_f32_e32 v11, v11
	v_exp_f32_e32 v14, v14
	v_exp_f32_e32 v15, v15
	v_add_f32_e32 v16, v19, v132
	v_add_f32_e32 v16, v16, v18
	v_add_f32_e32 v17, v2, v3
	v_add_f32_e32 v18, v8, v9
	v_add_f32_e32 v17, v17, v18
	v_add_f32_e32 v16, v17, v16
	v_add_f32_e32 v17, v10, v11
	v_add_f32_e32 v18, v14, v15
	v_add_f32_e32 v17, v17, v18
	v_add_f32_e32 v16, v17, v16
	v_mov_b32_e32 v17, v16
	s_nop 1
	v_permlane16_swap_b32_e32 v16, v17
	s_waitcnt lgkmcnt(0)
	v_add_f32_e32 v16, v16, v17
	v_mov_b32_e32 v17, v16
	s_nop 1
	v_permlane32_swap_b32_e32 v16, v17
	s_and_saveexec_b64 s[2:3], vcc
	s_cbranch_execz .LBB0_778
	s_waitcnt lgkmcnt(0)
	v_add_f32_e32 v16, v16, v17
	ds_write_b32 v184, v16 offset:6912

.LBB0_1202:
	v_and_b32_e32 v147, 64, v197
	v_xor_b32_e32 v146, 16, v197
	v_add_u32_e32 v147, 64, v147
	s_bfe_u32 s3, s52, 0x10006
	v_cmp_lt_i32_e32 vcc, v146, v147
	s_lshl_b32 s2, s68, 2
	s_add_i32 s5, s2, 0
	v_cndmask_b32_e32 v146, v197, v146, vcc
	s_lshl_b32 s2, s3, 10
	v_lshlrev_b32_e32 v166, 2, v146
	v_xor_b32_e32 v146, 32, v197
	s_add_i32 s2, s2, s92
	v_cmp_lt_i32_e32 vcc, v146, v147
	s_add_i32 s2, s2, 0
	v_add_u32_e32 v167, s2, v167
	v_cndmask_b32_e32 v146, v197, v146, vcc
	s_lshl_b32 s2, s68, 13
	v_and_b32_e32 v144, 63, v165
	v_lshlrev_b32_e32 v165, 2, v146
	v_lshlrev_b64 v[146:147], 11, v[158:159]
	s_and_b32 s2, s2, 0x4000
	v_lshl_add_u64 v[146:147], s[60:61], 0, v[146:147]
	s_or_b32 s4, s2, 0x10000
	v_lshl_add_u64 v[160:161], v[156:157], 1, v[146:147]
	v_add_u32_e32 v146, s4, v167
	ds_read_b128 v[168:171], v146
	s_add_i32 s5, s5, 0x20000
	v_cmp_gt_u32_e32 vcc, 16, v144
	s_waitcnt lgkmcnt(0)
	v_lshlrev_b32_e32 v146, 16, v168
	v_and_b32_e32 v147, 0xffff0000, v168
	v_lshlrev_b32_e32 v154, 16, v169
	v_and_b32_e32 v155, 0xffff0000, v169
	v_pk_fma_f32 v[138:139], v[138:139], 0.5, v[154:155] op_sel_hi:[1,0,1]
	v_pk_fma_f32 v[136:137], v[136:137], 0.5, v[146:147] op_sel_hi:[1,0,1]
	v_lshlrev_b32_e32 v146, 16, v170
	v_and_b32_e32 v147, 0xffff0000, v170
	v_lshlrev_b32_e32 v154, 16, v171
	v_and_b32_e32 v155, 0xffff0000, v171
	v_pk_fma_f32 v[154:155], v[134:135], 0.5, v[154:155] op_sel_hi:[1,0,1]
	v_pk_fma_f32 v[146:147], v[132:133], 0.5, v[146:147] op_sel_hi:[1,0,1]
	v_cvt_pk_bf16_f32 v132, v136, v137
	v_cvt_pk_bf16_f32 v133, v138, v139
	v_cvt_pk_bf16_f32 v134, v146, v147
	v_cvt_pk_bf16_f32 v135, v154, v155
	global_store_dwordx4 v[160:161], v[132:135], off
	s_nop 1
	v_mul_f32_e32 v132, v137, v137
	v_mul_f32_e32 v133, v139, v139
	v_fmac_f32_e32 v132, v136, v136
	v_fmac_f32_e32 v133, v138, v138
	v_add_f32_e32 v132, v132, v133
	v_mul_f32_e32 v133, v147, v147
	v_mul_f32_e32 v134, v155, v155
	v_fmac_f32_e32 v133, v146, v146
	v_fmac_f32_e32 v134, v154, v154
	v_add_f32_e32 v133, v133, v134
	v_add_f32_e32 v138, v132, v133
	v_add_u32_e32 v132, s2, v167
	ds_read_b128 v[132:135], v132
	s_waitcnt lgkmcnt(0)
	v_lshlrev_b32_e32 v136, 16, v132
	v_and_b32_e32 v137, 0xffff0000, v132
	v_lshlrev_b32_e32 v132, 16, v133
	v_and_b32_e32 v133, 0xffff0000, v133
	v_pk_fma_f32 v[126:127], v[126:127], 0.5, v[132:133] op_sel_hi:[1,0,1]
	v_lshlrev_b32_e32 v132, 16, v134
	v_and_b32_e32 v133, 0xffff0000, v134
	v_lshlrev_b32_e32 v134, 16, v135
	v_and_b32_e32 v135, 0xffff0000, v135
	v_pk_fma_f32 v[124:125], v[124:125], 0.5, v[136:137] op_sel_hi:[1,0,1]
	v_pk_fma_f32 v[134:135], v[122:123], 0.5, v[134:135] op_sel_hi:[1,0,1]
	v_pk_fma_f32 v[132:133], v[120:121], 0.5, v[132:133] op_sel_hi:[1,0,1]
	v_cvt_pk_bf16_f32 v120, v124, v125
	v_cvt_pk_bf16_f32 v121, v126, v127
	v_cvt_pk_bf16_f32 v122, v132, v133
	v_cvt_pk_bf16_f32 v123, v134, v135
	global_store_dwordx4 v[160:161], v[120:123], off offset:256
	s_nop 1
	v_mul_f32_e32 v120, v125, v125
	v_mul_f32_e32 v121, v127, v127
	v_fmac_f32_e32 v120, v124, v124
	v_fmac_f32_e32 v121, v126, v126
	v_add_f32_e32 v120, v120, v121
	v_mul_f32_e32 v121, v133, v133
	v_mul_f32_e32 v122, v135, v135
	v_fmac_f32_e32 v121, v132, v132
	v_fmac_f32_e32 v122, v134, v134
	v_add_f32_e32 v121, v121, v122
	v_add_f32_e32 v120, v120, v121
	v_add_f32_e32 v120, v138, v120
	v_mov_b32_e32 v121, v120
	s_nop 1
	v_permlane16_swap_b32_e32 v120, v121
	v_lshl_add_u32 v122, v164, 4, s5
	s_waitcnt lgkmcnt(0)
	v_add_f32_e32 v120, v120, v121
	v_mov_b32_e32 v121, v120
	s_nop 1
	v_permlane32_swap_b32_e32 v120, v121
	s_and_saveexec_b64 s[18:19], vcc
	s_cbranch_execz .LBB0_1204
	s_waitcnt lgkmcnt(0)
	v_add_f32_e32 v120, v120, v121
	ds_write_b32 v122, v120
.LBB0_1204:
	s_or_b64 exec, exec, s[18:19]
	s_or_b32 s5, s65, 16
	v_or_b32_e32 v123, s5, v162
	s_lshr_b32 s5, s5, 3
	s_or_b32 s5, s5, s3
	v_lshlrev_b32_e32 v124, 6, v123
	s_movk_i32 s8, 0x3c0
	s_lshl_b32 s5, s5, 10
	v_lshlrev_b32_e32 v123, 2, v123
	v_and_or_b32 v124, v124, s8, v163
	v_and_b32_e32 v123, 32, v123
	s_add_i32 s5, s5, 0
	v_xad_u32 v123, v124, v123, s5
	v_add_u32_e32 v124, s4, v123
	ds_read_b128 v[124:127], v124
	v_or_b32_e32 v120, 16, v158
	s_waitcnt lgkmcnt(0)
	v_ashrrev_i32_e32 v121, 31, v120
	v_lshlrev_b64 v[120:121], 11, v[120:121]
	v_lshl_add_u64 v[120:121], s[60:61], 0, v[120:121]
	v_lshlrev_b32_e32 v132, 16, v124
	v_and_b32_e32 v133, 0xffff0000, v124
	v_lshlrev_b32_e32 v124, 16, v125
	v_and_b32_e32 v125, 0xffff0000, v125
	v_pk_fma_f32 v[118:119], v[118:119], 0.5, v[124:125] op_sel_hi:[1,0,1]
	v_lshlrev_b32_e32 v124, 16, v126
	v_and_b32_e32 v125, 0xffff0000, v126
	v_lshlrev_b32_e32 v126, 16, v127
	v_and_b32_e32 v127, 0xffff0000, v127
	v_pk_fma_f32 v[116:117], v[116:117], 0.5, v[132:133] op_sel_hi:[1,0,1]
	v_pk_fma_f32 v[126:127], v[114:115], 0.5, v[126:127] op_sel_hi:[1,0,1]
	v_pk_fma_f32 v[124:125], v[112:113], 0.5, v[124:125] op_sel_hi:[1,0,1]
	v_lshl_add_u64 v[120:121], v[156:157], 1, v[120:121]
	v_cvt_pk_bf16_f32 v112, v116, v117
	v_cvt_pk_bf16_f32 v113, v118, v119
	v_cvt_pk_bf16_f32 v114, v124, v125
	v_cvt_pk_bf16_f32 v115, v126, v127
	global_store_dwordx4 v[120:121], v[112:115], off
	s_nop 1
	v_mul_f32_e32 v112, v117, v117
	v_mul_f32_e32 v113, v119, v119
	v_fmac_f32_e32 v112, v116, v116
	v_fmac_f32_e32 v113, v118, v118
	v_add_f32_e32 v112, v112, v113
	v_mul_f32_e32 v113, v125, v125
	v_mul_f32_e32 v114, v127, v127
	v_fmac_f32_e32 v113, v124, v124
	v_fmac_f32_e32 v114, v126, v126
	v_add_f32_e32 v113, v113, v114
	v_add_f32_e32 v118, v112, v113
	v_add_u32_e32 v112, s2, v123
	ds_read_b128 v[112:115], v112
	s_waitcnt lgkmcnt(0)
	v_lshlrev_b32_e32 v116, 16, v112
	v_and_b32_e32 v117, 0xffff0000, v112
	v_lshlrev_b32_e32 v112, 16, v113
	v_and_b32_e32 v113, 0xffff0000, v113
	v_pk_fma_f32 v[106:107], v[106:107], 0.5, v[112:113] op_sel_hi:[1,0,1]
	v_lshlrev_b32_e32 v112, 16, v114
	v_and_b32_e32 v113, 0xffff0000, v114
	v_lshlrev_b32_e32 v114, 16, v115
	v_and_b32_e32 v115, 0xffff0000, v115
	v_pk_fma_f32 v[104:105], v[104:105], 0.5, v[116:117] op_sel_hi:[1,0,1]
	v_pk_fma_f32 v[114:115], v[102:103], 0.5, v[114:115] op_sel_hi:[1,0,1]
	v_pk_fma_f32 v[112:113], v[100:101], 0.5, v[112:113] op_sel_hi:[1,0,1]
	v_cvt_pk_bf16_f32 v100, v104, v105
	v_cvt_pk_bf16_f32 v101, v106, v107
	v_cvt_pk_bf16_f32 v102, v112, v113
	v_cvt_pk_bf16_f32 v103, v114, v115
	global_store_dwordx4 v[120:121], v[100:103], off offset:256
	s_nop 1
	v_mul_f32_e32 v100, v105, v105
	v_mul_f32_e32 v101, v107, v107
	v_fmac_f32_e32 v100, v104, v104
	v_fmac_f32_e32 v101, v106, v106
	v_add_f32_e32 v100, v100, v101
	v_mul_f32_e32 v101, v113, v113
	v_mul_f32_e32 v102, v115, v115
	v_fmac_f32_e32 v101, v112, v112
	v_fmac_f32_e32 v102, v114, v114
	v_add_f32_e32 v101, v101, v102
	v_add_f32_e32 v100, v100, v101
	v_add_f32_e32 v100, v118, v100
	v_mov_b32_e32 v101, v100
	s_nop 1
	v_permlane16_swap_b32_e32 v100, v101
	s_waitcnt lgkmcnt(0)
	v_add_f32_e32 v100, v100, v101
	v_mov_b32_e32 v101, v100
	s_nop 1
	v_permlane32_swap_b32_e32 v100, v101
	s_and_saveexec_b64 s[18:19], vcc
	s_cbranch_execz .LBB0_1206
	s_waitcnt lgkmcnt(0)
	v_add_f32_e32 v100, v100, v101
	ds_write_b32 v122, v100 offset:256
.LBB0_1206:
	s_or_b64 exec, exec, s[18:19]
	s_or_b32 s5, s65, 32
	v_or_b32_e32 v102, s5, v162
	s_lshr_b32 s5, s5, 3
	s_or_b32 s5, s5, s3
	v_lshlrev_b32_e32 v103, 6, v102
	s_lshl_b32 s5, s5, 10
	v_lshlrev_b32_e32 v102, 2, v102
	v_and_or_b32 v103, v103, s8, v163
	v_and_b32_e32 v102, 32, v102
	s_add_i32 s5, s5, 0
	v_xad_u32 v102, v103, v102, s5
	v_add_u32_e32 v103, s4, v102
	ds_read_b128 v[104:107], v103
	v_or_b32_e32 v100, 32, v158
	s_waitcnt lgkmcnt(0)
	v_ashrrev_i32_e32 v101, 31, v100
	v_lshlrev_b64 v[100:101], 11, v[100:101]
	v_lshl_add_u64 v[100:101], s[60:61], 0, v[100:101]
	v_lshlrev_b32_e32 v112, 16, v104
	v_and_b32_e32 v113, 0xffff0000, v104
	v_lshlrev_b32_e32 v104, 16, v105
	v_and_b32_e32 v105, 0xffff0000, v105
	v_pk_fma_f32 v[98:99], v[98:99], 0.5, v[104:105] op_sel_hi:[1,0,1]
	v_lshlrev_b32_e32 v104, 16, v106
	v_and_b32_e32 v105, 0xffff0000, v106
	v_lshlrev_b32_e32 v106, 16, v107
	v_and_b32_e32 v107, 0xffff0000, v107
	v_pk_fma_f32 v[96:97], v[96:97], 0.5, v[112:113] op_sel_hi:[1,0,1]
	v_pk_fma_f32 v[106:107], v[94:95], 0.5, v[106:107] op_sel_hi:[1,0,1]
	v_pk_fma_f32 v[104:105], v[92:93], 0.5, v[104:105] op_sel_hi:[1,0,1]
	v_lshl_add_u64 v[100:101], v[156:157], 1, v[100:101]
	v_cvt_pk_bf16_f32 v92, v96, v97
	v_cvt_pk_bf16_f32 v93, v98, v99
	v_cvt_pk_bf16_f32 v94, v104, v105
	v_cvt_pk_bf16_f32 v95, v106, v107
	global_store_dwordx4 v[100:101], v[92:95], off
	s_nop 1
	v_mul_f32_e32 v92, v97, v97
	v_mul_f32_e32 v93, v99, v99
	v_fmac_f32_e32 v92, v96, v96
	v_fmac_f32_e32 v93, v98, v98
	v_add_f32_e32 v92, v92, v93
	v_mul_f32_e32 v93, v105, v105
	v_mul_f32_e32 v94, v107, v107
	v_fmac_f32_e32 v93, v104, v104
	v_fmac_f32_e32 v94, v106, v106
	v_add_f32_e32 v93, v93, v94
	v_add_f32_e32 v98, v92, v93
	v_add_u32_e32 v92, s2, v102
	ds_read_b128 v[92:95], v92
	s_waitcnt lgkmcnt(0)
	v_lshlrev_b32_e32 v96, 16, v92
	v_and_b32_e32 v97, 0xffff0000, v92
	v_lshlrev_b32_e32 v92, 16, v93
	v_and_b32_e32 v93, 0xffff0000, v93
	v_pk_fma_f32 v[86:87], v[86:87], 0.5, v[92:93] op_sel_hi:[1,0,1]
	v_lshlrev_b32_e32 v92, 16, v94
	v_and_b32_e32 v93, 0xffff0000, v94
	v_lshlrev_b32_e32 v94, 16, v95
	v_and_b32_e32 v95, 0xffff0000, v95
	v_pk_fma_f32 v[84:85], v[84:85], 0.5, v[96:97] op_sel_hi:[1,0,1]
	v_pk_fma_f32 v[94:95], v[82:83], 0.5, v[94:95] op_sel_hi:[1,0,1]
	v_pk_fma_f32 v[92:93], v[80:81], 0.5, v[92:93] op_sel_hi:[1,0,1]
	v_cvt_pk_bf16_f32 v80, v84, v85
	v_cvt_pk_bf16_f32 v81, v86, v87
	v_cvt_pk_bf16_f32 v82, v92, v93
	v_cvt_pk_bf16_f32 v83, v94, v95
	global_store_dwordx4 v[100:101], v[80:83], off offset:256
	s_nop 1
	v_mul_f32_e32 v80, v85, v85
	v_mul_f32_e32 v81, v87, v87
	v_fmac_f32_e32 v80, v84, v84
	v_fmac_f32_e32 v81, v86, v86
	v_add_f32_e32 v80, v80, v81
	v_mul_f32_e32 v81, v93, v93
	v_mul_f32_e32 v82, v95, v95
	v_fmac_f32_e32 v81, v92, v92
	v_fmac_f32_e32 v82, v94, v94
	v_add_f32_e32 v81, v81, v82
	v_add_f32_e32 v80, v80, v81
	v_add_f32_e32 v80, v98, v80
	v_mov_b32_e32 v81, v80
	s_nop 1
	v_permlane16_swap_b32_e32 v80, v81
	s_waitcnt lgkmcnt(0)
	v_add_f32_e32 v80, v80, v81
	v_mov_b32_e32 v81, v80
	s_nop 1
	v_permlane32_swap_b32_e32 v80, v81
	s_and_saveexec_b64 s[18:19], vcc
	s_cbranch_execz .LBB0_1208
	s_waitcnt lgkmcnt(0)
	v_add_f32_e32 v80, v80, v81
	ds_write_b32 v122, v80 offset:512
.LBB0_1208:
	s_or_b64 exec, exec, s[18:19]
	s_or_b32 s5, s65, 48
	v_or_b32_e32 v82, s5, v162
	s_lshr_b32 s5, s5, 3
	s_or_b32 s3, s5, s3
	v_lshlrev_b32_e32 v83, 6, v82
	s_movk_i32 s5, 0x3c0
	s_lshl_b32 s3, s3, 10
	v_lshlrev_b32_e32 v82, 2, v82
	v_and_or_b32 v83, v83, s5, v163
	v_and_b32_e32 v82, 32, v82
	s_add_i32 s3, s3, 0
	v_xad_u32 v82, v83, v82, s3
	v_add_u32_e32 v83, s4, v82
	ds_read_b128 v[84:87], v83
	v_or_b32_e32 v80, 48, v158
	s_waitcnt lgkmcnt(0)
	v_ashrrev_i32_e32 v81, 31, v80
	v_lshlrev_b64 v[80:81], 11, v[80:81]
	v_lshl_add_u64 v[80:81], s[60:61], 0, v[80:81]
	v_lshlrev_b32_e32 v92, 16, v84
	v_and_b32_e32 v93, 0xffff0000, v84
	v_lshlrev_b32_e32 v84, 16, v85
	v_and_b32_e32 v85, 0xffff0000, v85
	v_pk_fma_f32 v[78:79], v[78:79], 0.5, v[84:85] op_sel_hi:[1,0,1]
	v_lshlrev_b32_e32 v84, 16, v86
	v_and_b32_e32 v85, 0xffff0000, v86
	v_lshlrev_b32_e32 v86, 16, v87
	v_and_b32_e32 v87, 0xffff0000, v87
	v_pk_fma_f32 v[76:77], v[76:77], 0.5, v[92:93] op_sel_hi:[1,0,1]
	v_pk_fma_f32 v[86:87], v[74:75], 0.5, v[86:87] op_sel_hi:[1,0,1]
	v_pk_fma_f32 v[84:85], v[72:73], 0.5, v[84:85] op_sel_hi:[1,0,1]
	v_lshl_add_u64 v[80:81], v[156:157], 1, v[80:81]
	v_cvt_pk_bf16_f32 v72, v76, v77
	v_cvt_pk_bf16_f32 v73, v78, v79
	v_cvt_pk_bf16_f32 v74, v84, v85
	v_cvt_pk_bf16_f32 v75, v86, v87
	global_store_dwordx4 v[80:81], v[72:75], off
	s_nop 1
	v_mul_f32_e32 v72, v77, v77
	v_mul_f32_e32 v73, v79, v79
	v_fmac_f32_e32 v72, v76, v76
	v_fmac_f32_e32 v73, v78, v78
	v_add_f32_e32 v72, v72, v73
	v_mul_f32_e32 v73, v85, v85
	v_mul_f32_e32 v74, v87, v87
	v_fmac_f32_e32 v73, v84, v84
	v_fmac_f32_e32 v74, v86, v86
	v_add_f32_e32 v73, v73, v74
	v_add_f32_e32 v78, v72, v73
	v_add_u32_e32 v72, s2, v82
	ds_read_b128 v[72:75], v72
	s_waitcnt lgkmcnt(0)
	v_lshlrev_b32_e32 v76, 16, v72
	v_and_b32_e32 v77, 0xffff0000, v72
	v_lshlrev_b32_e32 v72, 16, v73
	v_and_b32_e32 v73, 0xffff0000, v73
	v_pk_fma_f32 v[70:71], v[70:71], 0.5, v[72:73] op_sel_hi:[1,0,1]
	v_lshlrev_b32_e32 v72, 16, v74
	v_and_b32_e32 v73, 0xffff0000, v74
	v_lshlrev_b32_e32 v74, 16, v75
	v_and_b32_e32 v75, 0xffff0000, v75
	v_pk_fma_f32 v[68:69], v[68:69], 0.5, v[76:77] op_sel_hi:[1,0,1]
	v_pk_fma_f32 v[74:75], v[66:67], 0.5, v[74:75] op_sel_hi:[1,0,1]
	v_pk_fma_f32 v[72:73], v[64:65], 0.5, v[72:73] op_sel_hi:[1,0,1]
	v_cvt_pk_bf16_f32 v64, v68, v69
	v_cvt_pk_bf16_f32 v65, v70, v71
	v_cvt_pk_bf16_f32 v66, v72, v73
	v_cvt_pk_bf16_f32 v67, v74, v75
	global_store_dwordx4 v[80:81], v[64:67], off offset:256
	s_nop 1
	v_mul_f32_e32 v64, v69, v69
	v_mul_f32_e32 v65, v71, v71
	v_fmac_f32_e32 v64, v68, v68
	v_fmac_f32_e32 v65, v70, v70
	v_add_f32_e32 v64, v64, v65
	v_mul_f32_e32 v65, v73, v73
	v_mul_f32_e32 v66, v75, v75
	v_fmac_f32_e32 v65, v72, v72
	v_fmac_f32_e32 v66, v74, v74
	v_add_f32_e32 v65, v65, v66
	v_add_f32_e32 v64, v64, v65
	v_add_f32_e32 v64, v78, v64
	v_mov_b32_e32 v65, v64
	s_nop 1
	v_permlane16_swap_b32_e32 v64, v65
	s_waitcnt lgkmcnt(0)
	v_add_f32_e32 v64, v64, v65
	v_mov_b32_e32 v65, v64
	s_nop 1
	v_permlane32_swap_b32_e32 v64, v65
	s_and_saveexec_b64 s[18:19], vcc
	s_cbranch_execz .LBB0_1210
	s_waitcnt lgkmcnt(0)
	v_add_f32_e32 v64, v64, v65
	ds_write_b32 v122, v64 offset:768
.LBB0_1210:
	s_or_b64 exec, exec, s[18:19]
	s_or_b32 s2, s2, 0x18000
	v_add_u32_e32 v68, s2, v167
	ds_read_b128 v[68:71], v68
	s_waitcnt lgkmcnt(0)
	v_lshlrev_b64 v[64:65], 11, v[158:159]
	v_lshl_add_u64 v[64:65], s[60:61], 0, v[64:65]
	v_lshl_add_u64 v[64:65], v[156:157], 1, v[64:65]
	s_mov_b32 s3, 0x40000
	v_lshlrev_b32_e32 v72, 16, v68
	v_and_b32_e32 v73, 0xffff0000, v68
	v_lshlrev_b32_e32 v68, 16, v69
	v_and_b32_e32 v69, 0xffff0000, v69
	v_pk_fma_f32 v[62:63], v[62:63], 0.5, v[68:69] op_sel_hi:[1,0,1]
	v_lshlrev_b32_e32 v68, 16, v70
	v_and_b32_e32 v69, 0xffff0000, v70
	v_lshlrev_b32_e32 v70, 16, v71
	v_and_b32_e32 v71, 0xffff0000, v71
	v_pk_fma_f32 v[60:61], v[60:61], 0.5, v[72:73] op_sel_hi:[1,0,1]
	v_pk_fma_f32 v[70:71], v[58:59], 0.5, v[70:71] op_sel_hi:[1,0,1]
	v_pk_fma_f32 v[68:69], v[56:57], 0.5, v[68:69] op_sel_hi:[1,0,1]
	v_add_co_u32_e64 v72, s[38:39], s3, v64
	v_cvt_pk_bf16_f32 v56, v60, v61
	v_cvt_pk_bf16_f32 v57, v62, v63
	v_cvt_pk_bf16_f32 v58, v68, v69
	v_cvt_pk_bf16_f32 v59, v70, v71
	v_addc_co_u32_e64 v73, s[38:39], 0, v65, s[38:39]
	global_store_dwordx4 v[72:73], v[56:59], off
	v_lshl_add_u64 v[66:67], v[64:65], 0, s[62:63]
	s_nop 0
	v_mul_f32_e32 v56, v61, v61
	v_mul_f32_e32 v57, v63, v63
	v_fmac_f32_e32 v56, v60, v60
	v_fmac_f32_e32 v57, v62, v62
	v_add_f32_e32 v56, v56, v57
	v_mul_f32_e32 v57, v69, v69
	v_mul_f32_e32 v58, v71, v71
	v_fmac_f32_e32 v57, v68, v68
	v_fmac_f32_e32 v58, v70, v70
	v_add_f32_e32 v57, v57, v58
	v_add_f32_e32 v60, v56, v57
	ds_read_b128 v[56:59], v167 offset:32768
	s_waitcnt vmcnt(0) lgkmcnt(0)
	v_cndmask_b32_e64 v61, v59, v143, s[36:37]
	v_cndmask_b32_e64 v59, v57, v141, s[36:37]
	v_cndmask_b32_e64 v57, v56, v140, s[36:37]
	v_cndmask_b32_e64 v62, v58, v142, s[36:37]
	v_lshlrev_b32_e32 v56, 16, v57
	v_and_b32_e32 v57, 0xffff0000, v57
	v_lshlrev_b32_e32 v58, 16, v59
	v_and_b32_e32 v59, 0xffff0000, v59
	v_pk_fma_f32 v[54:55], v[54:55], 0.5, v[58:59] op_sel_hi:[1,0,1]
	v_pk_fma_f32 v[52:53], v[52:53], 0.5, v[56:57] op_sel_hi:[1,0,1]
	v_lshlrev_b32_e32 v56, 16, v62
	v_and_b32_e32 v57, 0xffff0000, v62
	v_lshlrev_b32_e32 v58, 16, v61
	v_and_b32_e32 v59, 0xffff0000, v61
	v_pk_fma_f32 v[58:59], v[50:51], 0.5, v[58:59] op_sel_hi:[1,0,1]
	v_pk_fma_f32 v[56:57], v[48:49], 0.5, v[56:57] op_sel_hi:[1,0,1]
	v_cvt_pk_bf16_f32 v48, v52, v53
	v_cvt_pk_bf16_f32 v49, v54, v55
	v_cvt_pk_bf16_f32 v50, v56, v57
	v_cvt_pk_bf16_f32 v51, v58, v59
	global_store_dwordx4 v[66:67], v[48:51], off offset:256
	s_nop 1
	v_mul_f32_e32 v48, v53, v53
	v_mul_f32_e32 v49, v55, v55
	v_fmac_f32_e32 v48, v52, v52
	v_fmac_f32_e32 v49, v54, v54
	v_add_f32_e32 v48, v48, v49
	v_mul_f32_e32 v49, v57, v57
	v_mul_f32_e32 v50, v59, v59
	v_fmac_f32_e32 v49, v56, v56
	v_fmac_f32_e32 v50, v58, v58
	v_add_f32_e32 v49, v49, v50
	v_add_f32_e32 v48, v48, v49
	v_add_f32_e32 v48, v60, v48
	v_mov_b32_e32 v49, v48
	s_nop 1
	v_permlane16_swap_b32_e32 v48, v49
	s_waitcnt lgkmcnt(0)
	v_add_f32_e32 v48, v48, v49
	v_mov_b32_e32 v49, v48
	s_nop 1
	v_permlane32_swap_b32_e32 v48, v49
	s_and_saveexec_b64 s[18:19], vcc
	s_cbranch_execz .LBB0_1212
	s_waitcnt lgkmcnt(0)
	v_add_f32_e32 v48, v48, v49
	ds_write_b32 v122, v48 offset:2048
.LBB0_1212:
	s_or_b64 exec, exec, s[18:19]
	v_add_u32_e32 v50, s2, v123
	ds_read_b128 v[50:53], v50
	s_mov_b32 s3, 0x48000
	s_waitcnt lgkmcnt(0)
	v_lshl_add_u64 v[48:49], v[64:65], 0, s[76:77]
	s_waitcnt lgkmcnt(0)
	v_lshlrev_b32_e32 v54, 16, v50
	v_and_b32_e32 v55, 0xffff0000, v50
	v_lshlrev_b32_e32 v50, 16, v51
	v_and_b32_e32 v51, 0xffff0000, v51
	v_pk_fma_f32 v[46:47], v[46:47], 0.5, v[50:51] op_sel_hi:[1,0,1]
	v_lshlrev_b32_e32 v50, 16, v52
	v_and_b32_e32 v51, 0xffff0000, v52
	v_lshlrev_b32_e32 v52, 16, v53
	v_and_b32_e32 v53, 0xffff0000, v53
	v_pk_fma_f32 v[44:45], v[44:45], 0.5, v[54:55] op_sel_hi:[1,0,1]
	v_pk_fma_f32 v[52:53], v[42:43], 0.5, v[52:53] op_sel_hi:[1,0,1]
	v_pk_fma_f32 v[50:51], v[40:41], 0.5, v[50:51] op_sel_hi:[1,0,1]
	v_add_co_u32_e64 v54, s[38:39], s3, v64
	v_cvt_pk_bf16_f32 v40, v44, v45
	v_cvt_pk_bf16_f32 v41, v46, v47
	v_cvt_pk_bf16_f32 v42, v50, v51
	v_cvt_pk_bf16_f32 v43, v52, v53
	v_addc_co_u32_e64 v55, s[38:39], 0, v65, s[38:39]
	global_store_dwordx4 v[54:55], v[40:43], off
	s_nop 1
	v_mul_f32_e32 v40, v45, v45
	v_mul_f32_e32 v41, v47, v47
	v_fmac_f32_e32 v40, v44, v44
	v_fmac_f32_e32 v41, v46, v46
	v_add_f32_e32 v40, v40, v41
	v_mul_f32_e32 v41, v51, v51
	v_mul_f32_e32 v42, v53, v53
	v_fmac_f32_e32 v41, v50, v50
	v_fmac_f32_e32 v42, v52, v52
	v_add_f32_e32 v41, v41, v42
	v_add_f32_e32 v44, v40, v41
	ds_read_b128 v[40:43], v123 offset:32768
	s_waitcnt lgkmcnt(0)
	v_cndmask_b32_e64 v45, v43, v131, s[36:37]
	v_cndmask_b32_e64 v43, v41, v129, s[36:37]
	v_cndmask_b32_e64 v41, v40, v128, s[36:37]
	v_cndmask_b32_e64 v46, v42, v130, s[36:37]
	v_lshlrev_b32_e32 v40, 16, v41
	v_and_b32_e32 v41, 0xffff0000, v41
	v_lshlrev_b32_e32 v42, 16, v43
	v_and_b32_e32 v43, 0xffff0000, v43
	v_pk_fma_f32 v[38:39], v[38:39], 0.5, v[42:43] op_sel_hi:[1,0,1]
	v_pk_fma_f32 v[36:37], v[36:37], 0.5, v[40:41] op_sel_hi:[1,0,1]
	v_lshlrev_b32_e32 v40, 16, v46
	v_and_b32_e32 v41, 0xffff0000, v46
	v_lshlrev_b32_e32 v42, 16, v45
	v_and_b32_e32 v43, 0xffff0000, v45
	v_pk_fma_f32 v[42:43], v[34:35], 0.5, v[42:43] op_sel_hi:[1,0,1]
	v_pk_fma_f32 v[40:41], v[32:33], 0.5, v[40:41] op_sel_hi:[1,0,1]
	v_cvt_pk_bf16_f32 v32, v36, v37
	v_cvt_pk_bf16_f32 v33, v38, v39
	v_cvt_pk_bf16_f32 v34, v40, v41
	v_cvt_pk_bf16_f32 v35, v42, v43
	global_store_dwordx4 v[48:49], v[32:35], off offset:256
	s_nop 1
	v_mul_f32_e32 v32, v37, v37
	v_mul_f32_e32 v33, v39, v39
	v_fmac_f32_e32 v32, v36, v36
	v_fmac_f32_e32 v33, v38, v38
	v_add_f32_e32 v32, v32, v33
	v_mul_f32_e32 v33, v41, v41
	v_mul_f32_e32 v34, v43, v43
	v_fmac_f32_e32 v33, v40, v40
	v_fmac_f32_e32 v34, v42, v42
	v_add_f32_e32 v33, v33, v34
	v_add_f32_e32 v32, v32, v33
	v_add_f32_e32 v32, v44, v32
	v_mov_b32_e32 v33, v32
	s_nop 1
	v_permlane16_swap_b32_e32 v32, v33
	s_waitcnt lgkmcnt(0)
	v_add_f32_e32 v32, v32, v33
	v_mov_b32_e32 v33, v32
	s_nop 1
	v_permlane32_swap_b32_e32 v32, v33
	s_and_saveexec_b64 s[18:19], vcc
	s_cbranch_execz .LBB0_1214
	s_waitcnt lgkmcnt(0)
	v_add_f32_e32 v32, v32, v33
	ds_write_b32 v122, v32 offset:2304
.LBB0_1214:
	s_or_b64 exec, exec, s[18:19]
	v_add_u32_e32 v36, s2, v102
	ds_read_b128 v[36:39], v36
	s_waitcnt lgkmcnt(0)
	v_lshlrev_b64 v[32:33], 11, v[158:159]
	v_lshl_add_u64 v[32:33], s[60:61], 0, v[32:33]
	v_lshl_add_u64 v[32:33], v[156:157], 1, v[32:33]
	s_mov_b32 s3, 0x50000
	s_waitcnt lgkmcnt(0)
	v_lshlrev_b32_e32 v40, 16, v36
	v_and_b32_e32 v41, 0xffff0000, v36
	v_lshlrev_b32_e32 v36, 16, v37
	v_and_b32_e32 v37, 0xffff0000, v37
	v_pk_fma_f32 v[30:31], v[30:31], 0.5, v[36:37] op_sel_hi:[1,0,1]
	v_lshlrev_b32_e32 v36, 16, v38
	v_and_b32_e32 v37, 0xffff0000, v38
	v_lshlrev_b32_e32 v38, 16, v39
	v_and_b32_e32 v39, 0xffff0000, v39
	v_pk_fma_f32 v[28:29], v[28:29], 0.5, v[40:41] op_sel_hi:[1,0,1]
	v_pk_fma_f32 v[38:39], v[26:27], 0.5, v[38:39] op_sel_hi:[1,0,1]
	v_pk_fma_f32 v[36:37], v[24:25], 0.5, v[36:37] op_sel_hi:[1,0,1]
	v_add_co_u32_e64 v40, s[38:39], s3, v32
	v_cvt_pk_bf16_f32 v24, v28, v29
	v_cvt_pk_bf16_f32 v25, v30, v31
	v_cvt_pk_bf16_f32 v26, v36, v37
	v_cvt_pk_bf16_f32 v27, v38, v39
	v_addc_co_u32_e64 v41, s[38:39], 0, v33, s[38:39]
	global_store_dwordx4 v[40:41], v[24:27], off
	v_lshl_add_u64 v[34:35], v[32:33], 0, s[78:79]
	s_nop 0
	v_mul_f32_e32 v24, v29, v29
	v_mul_f32_e32 v25, v31, v31
	v_fmac_f32_e32 v24, v28, v28
	v_fmac_f32_e32 v25, v30, v30
	v_add_f32_e32 v24, v24, v25
	v_mul_f32_e32 v25, v37, v37
	v_mul_f32_e32 v26, v39, v39
	v_fmac_f32_e32 v25, v36, v36
	v_fmac_f32_e32 v26, v38, v38
	v_add_f32_e32 v25, v25, v26
	v_add_f32_e32 v28, v24, v25
	ds_read_b128 v[24:27], v102 offset:32768
	s_waitcnt lgkmcnt(0)
	v_cndmask_b32_e64 v29, v27, v111, s[36:37]
	v_cndmask_b32_e64 v27, v25, v109, s[36:37]
	v_cndmask_b32_e64 v25, v24, v108, s[36:37]
	v_cndmask_b32_e64 v30, v26, v110, s[36:37]
	v_lshlrev_b32_e32 v24, 16, v25
	v_and_b32_e32 v25, 0xffff0000, v25
	v_lshlrev_b32_e32 v26, 16, v27
	v_and_b32_e32 v27, 0xffff0000, v27
	v_pk_fma_f32 v[14:15], v[14:15], 0.5, v[26:27] op_sel_hi:[1,0,1]
	v_pk_fma_f32 v[12:13], v[12:13], 0.5, v[24:25] op_sel_hi:[1,0,1]
	v_lshlrev_b32_e32 v24, 16, v30
	v_and_b32_e32 v25, 0xffff0000, v30
	v_lshlrev_b32_e32 v26, 16, v29
	v_and_b32_e32 v27, 0xffff0000, v29
	v_pk_fma_f32 v[26:27], v[10:11], 0.5, v[26:27] op_sel_hi:[1,0,1]
	v_pk_fma_f32 v[24:25], v[8:9], 0.5, v[24:25] op_sel_hi:[1,0,1]
	v_cvt_pk_bf16_f32 v8, v12, v13
	v_cvt_pk_bf16_f32 v9, v14, v15
	v_cvt_pk_bf16_f32 v10, v24, v25
	v_cvt_pk_bf16_f32 v11, v26, v27
	global_store_dwordx4 v[34:35], v[8:11], off offset:256
	s_nop 1
	v_mul_f32_e32 v8, v13, v13
	v_mul_f32_e32 v9, v15, v15
	v_fmac_f32_e32 v8, v12, v12
	v_fmac_f32_e32 v9, v14, v14
	v_add_f32_e32 v8, v8, v9
	v_mul_f32_e32 v9, v25, v25
	v_mul_f32_e32 v10, v27, v27
	v_fmac_f32_e32 v9, v24, v24
	v_fmac_f32_e32 v10, v26, v26
	v_add_f32_e32 v9, v9, v10
	v_add_f32_e32 v8, v8, v9
	v_add_f32_e32 v8, v28, v8
	v_mov_b32_e32 v9, v8
	s_nop 1
	v_permlane16_swap_b32_e32 v8, v9
	s_waitcnt lgkmcnt(0)
	v_add_f32_e32 v8, v8, v9
	v_mov_b32_e32 v9, v8
	s_nop 1
	v_permlane32_swap_b32_e32 v8, v9
	s_and_saveexec_b64 s[18:19], vcc
	s_cbranch_execz .LBB0_1216
	s_waitcnt lgkmcnt(0)
	v_add_f32_e32 v8, v8, v9
	ds_write_b32 v122, v8 offset:2560
.LBB0_1216:
	s_or_b64 exec, exec, s[18:19]
	v_add_u32_e32 v8, s2, v82
	s_waitcnt lgkmcnt(0)
	ds_read_b128 v[8:11], v8
	ds_read_b128 v[12:15], v82 offset:32768
	v_lshl_add_u64 v[24:25], v[32:33], 0, s[80:81]
	s_waitcnt lgkmcnt(0)
	v_lshlrev_b32_e32 v26, 16, v8
	v_and_b32_e32 v27, 0xffff0000, v8
	v_lshlrev_b32_e32 v8, 16, v9
	v_and_b32_e32 v9, 0xffff0000, v9
	v_pk_fma_f32 v[6:7], v[6:7], 0.5, v[8:9] op_sel_hi:[1,0,1]
	v_pk_fma_f32 v[4:5], v[4:5], 0.5, v[26:27] op_sel_hi:[1,0,1]
	v_lshlrev_b32_e32 v8, 16, v10
	v_and_b32_e32 v9, 0xffff0000, v10
	v_pk_fma_f32 v[8:9], v[0:1], 0.5, v[8:9] op_sel_hi:[1,0,1]
	v_cvt_pk_bf16_f32 v0, v4, v5
	v_mul_f32_e32 v5, v5, v5
	v_lshlrev_b32_e32 v10, 16, v11
	v_and_b32_e32 v11, 0xffff0000, v11
	v_fmac_f32_e32 v5, v4, v4
	v_mul_f32_e32 v4, v7, v7
	v_pk_fma_f32 v[10:11], v[2:3], 0.5, v[10:11] op_sel_hi:[1,0,1]
	v_fmac_f32_e32 v4, v6, v6
	v_cvt_pk_bf16_f32 v1, v6, v7
	v_add_f32_e32 v4, v5, v4
	v_mul_f32_e32 v5, v9, v9
	v_mul_f32_e32 v6, v11, v11
	v_fmac_f32_e32 v5, v8, v8
	v_fmac_f32_e32 v6, v10, v10
	v_add_f32_e32 v5, v5, v6
	v_add_f32_e32 v26, v4, v5
	s_waitcnt lgkmcnt(0)
	v_cndmask_b32_e64 v7, v13, v89, s[36:37]
	v_cndmask_b32_e64 v5, v12, v88, s[36:37]
	v_lshlrev_b32_e32 v4, 16, v5
	v_and_b32_e32 v5, 0xffff0000, v5
	v_lshlrev_b32_e32 v6, 16, v7
	v_and_b32_e32 v7, 0xffff0000, v7
	v_cvt_pk_bf16_f32 v2, v8, v9
	v_cvt_pk_bf16_f32 v3, v10, v11
	v_cndmask_b32_e64 v11, v15, v91, s[36:37]
	v_cndmask_b32_e64 v9, v14, v90, s[36:37]
	v_pk_fma_f32 v[6:7], v[22:23], 0.5, v[6:7] op_sel_hi:[1,0,1]
	v_pk_fma_f32 v[4:5], v[20:21], 0.5, v[4:5] op_sel_hi:[1,0,1]
	v_lshlrev_b32_e32 v8, 16, v9
	v_and_b32_e32 v9, 0xffff0000, v9
	v_lshlrev_b32_e32 v10, 16, v11
	v_and_b32_e32 v11, 0xffff0000, v11
	v_mul_f32_e32 v12, v5, v5
	v_mul_f32_e32 v13, v7, v7
	v_pk_fma_f32 v[10:11], v[18:19], 0.5, v[10:11] op_sel_hi:[1,0,1]
	v_pk_fma_f32 v[8:9], v[16:17], 0.5, v[8:9] op_sel_hi:[1,0,1]
	v_fmac_f32_e32 v12, v4, v4
	v_fmac_f32_e32 v13, v6, v6
	v_add_f32_e32 v12, v12, v13
	v_mul_f32_e32 v13, v9, v9
	v_mul_f32_e32 v14, v11, v11
	v_fmac_f32_e32 v13, v8, v8
	v_fmac_f32_e32 v14, v10, v10
	v_add_f32_e32 v13, v13, v14
	v_add_f32_e32 v12, v12, v13
	v_add_f32_e32 v14, v26, v12
	v_mov_b32_e32 v15, v14
	s_nop 1
	v_permlane16_swap_b32_e32 v14, v15
	v_add_co_u32_e64 v12, s[36:37], s55, v32
	s_nop 1
	v_addc_co_u32_e64 v13, s[36:37], 0, v33, s[36:37]
	global_store_dwordx4 v[12:13], v[0:3], off
	s_waitcnt lgkmcnt(0)
	s_nop 0
	v_add_f32_e32 v0, v14, v15
	v_mov_b32_e32 v1, v0
	s_nop 1
	v_permlane32_swap_b32_e32 v0, v1
	v_cvt_pk_bf16_f32 v2, v4, v5
	v_cvt_pk_bf16_f32 v3, v6, v7
	v_cvt_pk_bf16_f32 v4, v8, v9
	v_cvt_pk_bf16_f32 v5, v10, v11
	global_store_dwordx4 v[24:25], v[2:5], off offset:256
	s_and_saveexec_b64 s[18:19], vcc
	s_cbranch_execz .LBB0_1218
	s_waitcnt lgkmcnt(0)
	v_add_f32_e32 v0, v0, v1
	ds_write_b32 v122, v0 offset:2816

.LBB0_1246:
	v_bfe_u32 v144, v142, 4, 2
	v_lshlrev_b32_e32 v128, 3, v144
	s_lshl_b32 s68, s12, 8
	v_lshl_or_b32 v128, s69, 5, v128
	v_and_b32_e32 v129, 64, v197
	v_and_b32_e32 v163, 63, v142
	v_or_b32_e32 v142, s68, v128
	v_xor_b32_e32 v128, 16, v197
	v_add_u32_e32 v129, 64, v129
	v_cmp_lt_i32_e32 vcc, v128, v129
	s_lshl_b32 s0, s23, 8
	s_add_i32 s2, s0, s15
	v_cndmask_b32_e32 v128, v197, v128, vcc
	v_lshlrev_b32_e32 v160, 2, v128
	v_xor_b32_e32 v128, 32, v197
	v_or_b32_e32 v140, s2, v164
	v_cmp_lt_i32_e32 vcc, v128, v129
	v_ashrrev_i32_e32 v141, 31, v140
	v_ashrrev_i32_e32 v143, 31, v142
	v_cndmask_b32_e32 v128, v197, v128, vcc
	v_lshlrev_b32_e32 v161, 2, v128
	v_lshlrev_b64 v[128:129], 11, v[140:141]
	v_lshl_add_u64 v[128:129], s[60:61], 0, v[128:129]
	v_lshl_add_u64 v[132:133], v[142:143], 1, v[128:129]
	s_barrier
	global_load_dwordx4 v[128:131], v[132:133], off
	s_lshl_b32 s2, s69, 2
	s_add_i32 s2, s2, 0
	v_cmp_gt_u32_e64 s[36:37], 16, v163
	v_lshl_add_u32 v165, v162, 4, s2
	s_waitcnt vmcnt(0)
	v_lshlrev_b32_e32 v134, 16, v128
	v_and_b32_e32 v135, 0xffff0000, v128
	v_lshlrev_b32_e32 v128, 16, v129
	v_and_b32_e32 v129, 0xffff0000, v129
	v_pk_fma_f32 v[126:127], v[126:127], 0.5, v[128:129] op_sel_hi:[1,0,1]
	v_pk_fma_f32 v[124:125], v[124:125], 0.5, v[134:135] op_sel_hi:[1,0,1]
	v_lshlrev_b32_e32 v128, 16, v130
	v_and_b32_e32 v129, 0xffff0000, v130
	v_lshlrev_b32_e32 v130, 16, v131
	v_and_b32_e32 v131, 0xffff0000, v131
	v_pk_fma_f32 v[120:121], v[120:121], 0.5, v[128:129] op_sel_hi:[1,0,1]
	v_mul_f32_e32 v128, v125, v125
	v_mul_f32_e32 v129, v127, v127
	v_pk_fma_f32 v[122:123], v[122:123], 0.5, v[130:131] op_sel_hi:[1,0,1]
	v_fmac_f32_e32 v128, v124, v124
	v_fmac_f32_e32 v129, v126, v126
	v_add_f32_e32 v128, v128, v129
	v_mul_f32_e32 v129, v121, v121
	v_mul_f32_e32 v130, v123, v123
	v_fmac_f32_e32 v129, v120, v120
	v_fmac_f32_e32 v130, v122, v122
	v_add_f32_e32 v129, v129, v130
	v_add_f32_e32 v134, v128, v129
	global_load_dwordx4 v[128:131], v[132:133], off offset:256
	s_waitcnt vmcnt(0)
	v_lshlrev_b32_e32 v132, 16, v128
	v_and_b32_e32 v133, 0xffff0000, v128
	v_lshlrev_b32_e32 v128, 16, v129
	v_and_b32_e32 v129, 0xffff0000, v129
	v_pk_fma_f32 v[118:119], v[118:119], 0.5, v[128:129] op_sel_hi:[1,0,1]
	v_pk_fma_f32 v[116:117], v[116:117], 0.5, v[132:133] op_sel_hi:[1,0,1]
	v_lshlrev_b32_e32 v128, 16, v130
	v_and_b32_e32 v129, 0xffff0000, v130
	v_lshlrev_b32_e32 v130, 16, v131
	v_and_b32_e32 v131, 0xffff0000, v131
	v_pk_fma_f32 v[112:113], v[112:113], 0.5, v[128:129] op_sel_hi:[1,0,1]
	v_mul_f32_e32 v128, v117, v117
	v_mul_f32_e32 v129, v119, v119
	v_pk_fma_f32 v[114:115], v[114:115], 0.5, v[130:131] op_sel_hi:[1,0,1]
	v_fmac_f32_e32 v128, v116, v116
	v_fmac_f32_e32 v129, v118, v118
	v_add_f32_e32 v128, v128, v129
	v_mul_f32_e32 v129, v113, v113
	v_mul_f32_e32 v130, v115, v115
	v_fmac_f32_e32 v129, v112, v112
	v_fmac_f32_e32 v130, v114, v114
	v_add_f32_e32 v129, v129, v130
	v_add_f32_e32 v128, v128, v129
	v_add_f32_e32 v128, v134, v128
	v_mov_b32_e32 v129, v128
	s_nop 1
	v_permlane16_swap_b32_e32 v128, v129
	s_waitcnt lgkmcnt(0)
	v_add_f32_e32 v128, v128, v129
	v_mov_b32_e32 v129, v128
	s_nop 1
	v_permlane32_swap_b32_e32 v128, v129
	s_and_saveexec_b64 s[18:19], s[36:37]
	s_movk_i32 s33, 0xe000
	s_cbranch_execz .LBB0_1248
	s_waitcnt lgkmcnt(0)
	v_add_f32_e32 v128, v128, v129
	ds_write_b32 v165, v128
.LBB0_1248:
	s_or_b64 exec, exec, s[18:19]
	v_or_b32_e32 v128, 16, v140
	s_waitcnt lgkmcnt(0)
	v_ashrrev_i32_e32 v129, 31, v128
	v_lshlrev_b64 v[128:129], 11, v[128:129]
	v_lshl_add_u64 v[128:129], s[60:61], 0, v[128:129]
	v_lshl_add_u64 v[132:133], v[142:143], 1, v[128:129]
	global_load_dwordx4 v[128:131], v[132:133], off
	s_waitcnt vmcnt(0)
	v_lshlrev_b32_e32 v134, 16, v128
	v_and_b32_e32 v135, 0xffff0000, v128
	v_lshlrev_b32_e32 v128, 16, v129
	v_and_b32_e32 v129, 0xffff0000, v129
	v_pk_fma_f32 v[110:111], v[110:111], 0.5, v[128:129] op_sel_hi:[1,0,1]
	v_pk_fma_f32 v[108:109], v[108:109], 0.5, v[134:135] op_sel_hi:[1,0,1]
	v_lshlrev_b32_e32 v128, 16, v130
	v_and_b32_e32 v129, 0xffff0000, v130
	v_lshlrev_b32_e32 v130, 16, v131
	v_and_b32_e32 v131, 0xffff0000, v131
	v_pk_fma_f32 v[104:105], v[104:105], 0.5, v[128:129] op_sel_hi:[1,0,1]
	v_mul_f32_e32 v128, v109, v109
	v_mul_f32_e32 v129, v111, v111
	v_pk_fma_f32 v[106:107], v[106:107], 0.5, v[130:131] op_sel_hi:[1,0,1]
	v_fmac_f32_e32 v128, v108, v108
	v_fmac_f32_e32 v129, v110, v110
	v_add_f32_e32 v128, v128, v129
	v_mul_f32_e32 v129, v105, v105
	v_mul_f32_e32 v130, v107, v107
	v_fmac_f32_e32 v129, v104, v104
	v_fmac_f32_e32 v130, v106, v106
	v_add_f32_e32 v129, v129, v130
	v_add_f32_e32 v134, v128, v129
	global_load_dwordx4 v[128:131], v[132:133], off offset:256
	s_waitcnt vmcnt(0)
	v_lshlrev_b32_e32 v132, 16, v128
	v_and_b32_e32 v133, 0xffff0000, v128
	v_lshlrev_b32_e32 v128, 16, v129
	v_and_b32_e32 v129, 0xffff0000, v129
	v_pk_fma_f32 v[102:103], v[102:103], 0.5, v[128:129] op_sel_hi:[1,0,1]
	v_pk_fma_f32 v[100:101], v[100:101], 0.5, v[132:133] op_sel_hi:[1,0,1]
	v_lshlrev_b32_e32 v132, 16, v130
	v_and_b32_e32 v133, 0xffff0000, v130
	v_lshlrev_b32_e32 v128, 16, v131
	v_and_b32_e32 v129, 0xffff0000, v131
	v_pk_fma_f32 v[130:131], v[96:97], 0.5, v[132:133] op_sel_hi:[1,0,1]
	v_mul_f32_e32 v96, v101, v101
	v_mul_f32_e32 v97, v103, v103
	v_pk_fma_f32 v[128:129], v[98:99], 0.5, v[128:129] op_sel_hi:[1,0,1]
	v_fmac_f32_e32 v96, v100, v100
	v_fmac_f32_e32 v97, v102, v102
	v_add_f32_e32 v96, v96, v97
	v_mul_f32_e32 v97, v131, v131
	v_mul_f32_e32 v98, v129, v129
	v_fmac_f32_e32 v97, v130, v130
	v_fmac_f32_e32 v98, v128, v128
	v_add_f32_e32 v97, v97, v98
	v_add_f32_e32 v96, v96, v97
	v_add_f32_e32 v96, v134, v96
	v_mov_b32_e32 v97, v96
	s_nop 1
	v_permlane16_swap_b32_e32 v96, v97
	s_waitcnt lgkmcnt(0)
	v_add_f32_e32 v96, v96, v97
	v_mov_b32_e32 v97, v96
	s_nop 1
	v_permlane32_swap_b32_e32 v96, v97
	s_and_saveexec_b64 s[18:19], s[36:37]
	s_movk_i32 s23, 0xf000
	s_cbranch_execz .LBB0_1250
	s_waitcnt lgkmcnt(0)
	v_add_f32_e32 v96, v96, v97
	ds_write_b32 v165, v96 offset:256
.LBB0_1250:
	s_or_b64 exec, exec, s[18:19]
	v_or_b32_e32 v96, 32, v140
	s_waitcnt lgkmcnt(0)
	v_ashrrev_i32_e32 v97, 31, v96
	v_lshlrev_b64 v[96:97], 11, v[96:97]
	v_lshl_add_u64 v[96:97], s[60:61], 0, v[96:97]
	v_lshl_add_u64 v[132:133], v[142:143], 1, v[96:97]
	global_load_dwordx4 v[96:99], v[132:133], off
	s_waitcnt vmcnt(0)
	v_lshlrev_b32_e32 v134, 16, v96
	v_and_b32_e32 v135, 0xffff0000, v96
	v_lshlrev_b32_e32 v96, 16, v97
	v_and_b32_e32 v97, 0xffff0000, v97
	v_pk_fma_f32 v[94:95], v[94:95], 0.5, v[96:97] op_sel_hi:[1,0,1]
	v_pk_fma_f32 v[92:93], v[92:93], 0.5, v[134:135] op_sel_hi:[1,0,1]
	v_lshlrev_b32_e32 v96, 16, v98
	v_and_b32_e32 v97, 0xffff0000, v98
	v_lshlrev_b32_e32 v98, 16, v99
	v_and_b32_e32 v99, 0xffff0000, v99
	v_pk_fma_f32 v[88:89], v[88:89], 0.5, v[96:97] op_sel_hi:[1,0,1]
	v_mul_f32_e32 v96, v93, v93
	v_mul_f32_e32 v97, v95, v95
	v_pk_fma_f32 v[90:91], v[90:91], 0.5, v[98:99] op_sel_hi:[1,0,1]
	v_fmac_f32_e32 v96, v92, v92
	v_fmac_f32_e32 v97, v94, v94
	v_add_f32_e32 v96, v96, v97
	v_mul_f32_e32 v97, v89, v89
	v_mul_f32_e32 v98, v91, v91
	v_fmac_f32_e32 v97, v88, v88
	v_fmac_f32_e32 v98, v90, v90
	v_add_f32_e32 v97, v97, v98
	v_add_f32_e32 v146, v96, v97
	global_load_dwordx4 v[96:99], v[132:133], off offset:256
	s_waitcnt vmcnt(0)
	v_lshlrev_b32_e32 v134, 16, v96
	v_and_b32_e32 v135, 0xffff0000, v96
	v_lshlrev_b32_e32 v96, 16, v97
	v_and_b32_e32 v97, 0xffff0000, v97
	v_pk_fma_f32 v[132:133], v[86:87], 0.5, v[96:97] op_sel_hi:[1,0,1]
	v_pk_fma_f32 v[134:135], v[84:85], 0.5, v[134:135] op_sel_hi:[1,0,1]
	v_lshlrev_b32_e32 v84, 16, v98
	v_and_b32_e32 v85, 0xffff0000, v98
	v_lshlrev_b32_e32 v86, 16, v99
	v_and_b32_e32 v87, 0xffff0000, v99
	v_pk_fma_f32 v[138:139], v[80:81], 0.5, v[84:85] op_sel_hi:[1,0,1]
	v_mul_f32_e32 v80, v135, v135
	v_mul_f32_e32 v81, v133, v133
	v_pk_fma_f32 v[136:137], v[82:83], 0.5, v[86:87] op_sel_hi:[1,0,1]
	v_fmac_f32_e32 v80, v134, v134
	v_fmac_f32_e32 v81, v132, v132
	v_add_f32_e32 v80, v80, v81
	v_mul_f32_e32 v81, v139, v139
	v_mul_f32_e32 v82, v137, v137
	v_fmac_f32_e32 v81, v138, v138
	v_fmac_f32_e32 v82, v136, v136
	v_add_f32_e32 v81, v81, v82
	v_add_f32_e32 v80, v80, v81
	v_add_f32_e32 v80, v146, v80
	v_mov_b32_e32 v81, v80
	s_nop 1
	v_permlane16_swap_b32_e32 v80, v81
	s_waitcnt lgkmcnt(0)
	v_add_f32_e32 v80, v80, v81
	v_mov_b32_e32 v81, v80
	s_nop 1
	v_permlane32_swap_b32_e32 v80, v81
	s_and_saveexec_b64 s[18:19], s[36:37]
	s_cbranch_execz .LBB0_1252
	s_waitcnt lgkmcnt(0)
	v_add_f32_e32 v80, v80, v81
	ds_write_b32 v165, v80 offset:512
.LBB0_1252:
	s_or_b64 exec, exec, s[18:19]
	v_or_b32_e32 v80, 48, v140
	s_waitcnt lgkmcnt(0)
	v_ashrrev_i32_e32 v81, 31, v80
	v_lshlrev_b64 v[80:81], 11, v[80:81]
	v_lshl_add_u64 v[80:81], s[60:61], 0, v[80:81]
	v_lshl_add_u64 v[84:85], v[142:143], 1, v[80:81]
	global_load_dwordx4 v[80:83], v[84:85], off
	s_waitcnt vmcnt(0)
	v_lshlrev_b32_e32 v86, 16, v80
	v_and_b32_e32 v87, 0xffff0000, v80
	v_lshlrev_b32_e32 v80, 16, v81
	v_and_b32_e32 v81, 0xffff0000, v81
	v_pk_fma_f32 v[78:79], v[78:79], 0.5, v[80:81] op_sel_hi:[1,0,1]
	v_pk_fma_f32 v[76:77], v[76:77], 0.5, v[86:87] op_sel_hi:[1,0,1]
	v_lshlrev_b32_e32 v80, 16, v82
	v_and_b32_e32 v81, 0xffff0000, v82
	v_lshlrev_b32_e32 v82, 16, v83
	v_and_b32_e32 v83, 0xffff0000, v83
	v_pk_fma_f32 v[72:73], v[72:73], 0.5, v[80:81] op_sel_hi:[1,0,1]
	v_mul_f32_e32 v80, v77, v77
	v_mul_f32_e32 v81, v79, v79
	v_pk_fma_f32 v[74:75], v[74:75], 0.5, v[82:83] op_sel_hi:[1,0,1]
	v_fmac_f32_e32 v80, v76, v76
	v_fmac_f32_e32 v81, v78, v78
	v_add_f32_e32 v80, v80, v81
	v_mul_f32_e32 v81, v73, v73
	v_mul_f32_e32 v82, v75, v75
	v_fmac_f32_e32 v81, v72, v72
	v_fmac_f32_e32 v82, v74, v74
	v_add_f32_e32 v81, v81, v82
	v_add_f32_e32 v86, v80, v81
	global_load_dwordx4 v[80:83], v[84:85], off offset:256
	s_waitcnt vmcnt(0)
	v_lshlrev_b32_e32 v84, 16, v80
	v_and_b32_e32 v85, 0xffff0000, v80
	v_lshlrev_b32_e32 v80, 16, v81
	v_and_b32_e32 v81, 0xffff0000, v81
	v_pk_fma_f32 v[70:71], v[70:71], 0.5, v[80:81] op_sel_hi:[1,0,1]
	v_pk_fma_f32 v[68:69], v[68:69], 0.5, v[84:85] op_sel_hi:[1,0,1]
	v_lshlrev_b32_e32 v80, 16, v82
	v_and_b32_e32 v81, 0xffff0000, v82
	v_lshlrev_b32_e32 v82, 16, v83
	v_and_b32_e32 v83, 0xffff0000, v83
	v_pk_fma_f32 v[64:65], v[64:65], 0.5, v[80:81] op_sel_hi:[1,0,1]
	v_mul_f32_e32 v80, v69, v69
	v_mul_f32_e32 v81, v71, v71
	v_pk_fma_f32 v[66:67], v[66:67], 0.5, v[82:83] op_sel_hi:[1,0,1]
	v_fmac_f32_e32 v80, v68, v68
	v_fmac_f32_e32 v81, v70, v70
	v_add_f32_e32 v80, v80, v81
	v_mul_f32_e32 v81, v65, v65
	v_mul_f32_e32 v82, v67, v67
	v_fmac_f32_e32 v81, v64, v64
	v_fmac_f32_e32 v82, v66, v66
	v_add_f32_e32 v81, v81, v82
	v_add_f32_e32 v80, v80, v81
	v_add_f32_e32 v80, v86, v80
	v_mov_b32_e32 v81, v80
	s_nop 1
	v_permlane16_swap_b32_e32 v80, v81
	s_waitcnt lgkmcnt(0)
	v_add_f32_e32 v80, v80, v81
	v_mov_b32_e32 v81, v80
	s_nop 1
	v_permlane32_swap_b32_e32 v80, v81
	s_and_saveexec_b64 s[18:19], s[36:37]
	s_cbranch_execz .LBB0_1254
	s_waitcnt lgkmcnt(0)
	v_add_f32_e32 v80, v80, v81
	ds_write_b32 v165, v80 offset:768
.LBB0_1254:
	s_or_b64 exec, exec, s[18:19]
	s_waitcnt lgkmcnt(0)
	v_lshlrev_b64 v[80:81], 11, v[140:141]
	v_lshl_add_u64 v[80:81], s[60:61], 0, v[80:81]
	v_lshl_add_u64 v[80:81], v[142:143], 1, v[80:81]
	v_add_co_u32_e32 v82, vcc, 0x40000, v80
	v_lshl_add_u64 v[86:87], v[80:81], 0, s[62:63]
	s_nop 0
	v_addc_co_u32_e32 v83, vcc, 0, v81, vcc
	global_load_dwordx4 v[82:85], v[82:83], off
	s_waitcnt vmcnt(0)
	v_lshlrev_b32_e32 v96, 16, v82
	v_and_b32_e32 v97, 0xffff0000, v82
	v_lshlrev_b32_e32 v82, 16, v83
	v_and_b32_e32 v83, 0xffff0000, v83
	v_pk_fma_f32 v[62:63], v[62:63], 0.5, v[82:83] op_sel_hi:[1,0,1]
	v_pk_fma_f32 v[60:61], v[60:61], 0.5, v[96:97] op_sel_hi:[1,0,1]
	v_lshlrev_b32_e32 v82, 16, v84
	v_and_b32_e32 v83, 0xffff0000, v84
	v_lshlrev_b32_e32 v84, 16, v85
	v_and_b32_e32 v85, 0xffff0000, v85
	v_pk_fma_f32 v[56:57], v[56:57], 0.5, v[82:83] op_sel_hi:[1,0,1]
	v_mul_f32_e32 v82, v61, v61
	v_mul_f32_e32 v83, v63, v63
	v_pk_fma_f32 v[58:59], v[58:59], 0.5, v[84:85] op_sel_hi:[1,0,1]
	v_fmac_f32_e32 v82, v60, v60
	v_fmac_f32_e32 v83, v62, v62
	v_add_f32_e32 v82, v82, v83
	v_mul_f32_e32 v83, v57, v57
	v_mul_f32_e32 v84, v59, v59
	v_fmac_f32_e32 v83, v56, v56
	v_fmac_f32_e32 v84, v58, v58
	v_add_f32_e32 v83, v83, v84
	v_add_f32_e32 v96, v82, v83
	global_load_dwordx4 v[82:85], v[86:87], off offset:256
	s_waitcnt vmcnt(0)
	v_lshlrev_b32_e32 v86, 16, v82
	v_and_b32_e32 v87, 0xffff0000, v82
	v_lshlrev_b32_e32 v82, 16, v83
	v_and_b32_e32 v83, 0xffff0000, v83
	v_pk_fma_f32 v[54:55], v[54:55], 0.5, v[82:83] op_sel_hi:[1,0,1]
	v_pk_fma_f32 v[52:53], v[52:53], 0.5, v[86:87] op_sel_hi:[1,0,1]
	v_lshlrev_b32_e32 v82, 16, v84
	v_and_b32_e32 v83, 0xffff0000, v84
	v_lshlrev_b32_e32 v84, 16, v85
	v_and_b32_e32 v85, 0xffff0000, v85
	v_pk_fma_f32 v[48:49], v[48:49], 0.5, v[82:83] op_sel_hi:[1,0,1]
	v_mul_f32_e32 v82, v53, v53
	v_mul_f32_e32 v83, v55, v55
	v_pk_fma_f32 v[50:51], v[50:51], 0.5, v[84:85] op_sel_hi:[1,0,1]
	v_fmac_f32_e32 v82, v52, v52
	v_fmac_f32_e32 v83, v54, v54
	v_add_f32_e32 v82, v82, v83
	v_mul_f32_e32 v83, v49, v49
	v_mul_f32_e32 v84, v51, v51
	v_fmac_f32_e32 v83, v48, v48
	v_fmac_f32_e32 v84, v50, v50
	v_add_f32_e32 v83, v83, v84
	v_add_f32_e32 v82, v82, v83
	v_add_f32_e32 v82, v96, v82
	v_mov_b32_e32 v83, v82
	s_nop 1
	v_permlane16_swap_b32_e32 v82, v83
	s_waitcnt lgkmcnt(0)
	v_add_f32_e32 v82, v82, v83
	v_mov_b32_e32 v83, v82
	s_nop 1
	v_permlane32_swap_b32_e32 v82, v83
	s_and_saveexec_b64 s[18:19], s[36:37]
	s_cbranch_execz .LBB0_1256
	s_waitcnt lgkmcnt(0)
	v_add_f32_e32 v82, v82, v83
	ds_write_b32 v165, v82 offset:2048
.LBB0_1256:
	s_or_b64 exec, exec, s[18:19]
	v_lshl_add_u64 v[84:85], v[80:81], 0, s[76:77]
	v_add_co_u32_e32 v80, vcc, 0x48000, v80
	s_nop 1
	v_addc_co_u32_e32 v81, vcc, 0, v81, vcc
	s_waitcnt lgkmcnt(0)
	global_load_dwordx4 v[80:83], v[80:81], off
	s_waitcnt vmcnt(0)
	v_lshlrev_b32_e32 v86, 16, v80
	v_and_b32_e32 v87, 0xffff0000, v80
	v_lshlrev_b32_e32 v80, 16, v81
	v_and_b32_e32 v81, 0xffff0000, v81
	v_pk_fma_f32 v[46:47], v[46:47], 0.5, v[80:81] op_sel_hi:[1,0,1]
	v_pk_fma_f32 v[44:45], v[44:45], 0.5, v[86:87] op_sel_hi:[1,0,1]
	v_lshlrev_b32_e32 v80, 16, v82
	v_and_b32_e32 v81, 0xffff0000, v82
	v_lshlrev_b32_e32 v82, 16, v83
	v_and_b32_e32 v83, 0xffff0000, v83
	v_pk_fma_f32 v[40:41], v[40:41], 0.5, v[80:81] op_sel_hi:[1,0,1]
	v_mul_f32_e32 v80, v45, v45
	v_mul_f32_e32 v81, v47, v47
	v_pk_fma_f32 v[42:43], v[42:43], 0.5, v[82:83] op_sel_hi:[1,0,1]
	v_fmac_f32_e32 v80, v44, v44
	v_fmac_f32_e32 v81, v46, v46
	v_add_f32_e32 v80, v80, v81
	v_mul_f32_e32 v81, v41, v41
	v_mul_f32_e32 v82, v43, v43
	v_fmac_f32_e32 v81, v40, v40
	v_fmac_f32_e32 v82, v42, v42
	v_add_f32_e32 v81, v81, v82
	v_add_f32_e32 v98, v80, v81
	global_load_dwordx4 v[80:83], v[84:85], off offset:256
	s_waitcnt vmcnt(0)
	v_lshlrev_b32_e32 v84, 16, v80
	v_and_b32_e32 v85, 0xffff0000, v80
	v_lshlrev_b32_e32 v80, 16, v81
	v_and_b32_e32 v81, 0xffff0000, v81
	v_pk_fma_f32 v[38:39], v[38:39], 0.5, v[80:81] op_sel_hi:[1,0,1]
	v_pk_fma_f32 v[36:37], v[36:37], 0.5, v[84:85] op_sel_hi:[1,0,1]
	v_lshlrev_b32_e32 v80, 16, v82
	v_and_b32_e32 v81, 0xffff0000, v82
	v_lshlrev_b32_e32 v82, 16, v83
	v_and_b32_e32 v83, 0xffff0000, v83
	v_pk_fma_f32 v[96:97], v[32:33], 0.5, v[80:81] op_sel_hi:[1,0,1]
	v_mul_f32_e32 v32, v37, v37
	v_mul_f32_e32 v33, v39, v39
	v_pk_fma_f32 v[86:87], v[34:35], 0.5, v[82:83] op_sel_hi:[1,0,1]
	v_fmac_f32_e32 v32, v36, v36
	v_fmac_f32_e32 v33, v38, v38
	v_add_f32_e32 v32, v32, v33
	v_mul_f32_e32 v33, v97, v97
	v_mul_f32_e32 v34, v87, v87
	v_fmac_f32_e32 v33, v96, v96
	v_fmac_f32_e32 v34, v86, v86
	v_add_f32_e32 v33, v33, v34
	v_add_f32_e32 v32, v32, v33
	v_add_f32_e32 v32, v98, v32
	v_mov_b32_e32 v33, v32
	s_nop 1
	v_permlane16_swap_b32_e32 v32, v33
	s_waitcnt lgkmcnt(0)
	v_add_f32_e32 v32, v32, v33
	v_mov_b32_e32 v33, v32
	s_nop 1
	v_permlane32_swap_b32_e32 v32, v33
	s_and_saveexec_b64 s[18:19], s[36:37]
	s_cbranch_execz .LBB0_1258
	s_waitcnt lgkmcnt(0)
	v_add_f32_e32 v32, v32, v33
	ds_write_b32 v165, v32 offset:2304
.LBB0_1258:
	s_or_b64 exec, exec, s[18:19]
	s_waitcnt lgkmcnt(0)
	v_lshlrev_b64 v[32:33], 11, v[140:141]
	v_lshl_add_u64 v[32:33], s[60:61], 0, v[32:33]
	v_lshl_add_u64 v[84:85], v[142:143], 1, v[32:33]
	v_add_co_u32_e32 v32, vcc, 0x50000, v84
	v_lshl_add_u64 v[98:99], v[84:85], 0, s[78:79]
	s_nop 0
	v_addc_co_u32_e32 v33, vcc, 0, v85, vcc
	global_load_dwordx4 v[32:35], v[32:33], off
	s_waitcnt vmcnt(0)
	v_lshlrev_b32_e32 v80, 16, v32
	v_and_b32_e32 v81, 0xffff0000, v32
	v_lshlrev_b32_e32 v32, 16, v33
	v_and_b32_e32 v33, 0xffff0000, v33
	v_pk_fma_f32 v[32:33], v[30:31], 0.5, v[32:33] op_sel_hi:[1,0,1]
	v_pk_fma_f32 v[80:81], v[28:29], 0.5, v[80:81] op_sel_hi:[1,0,1]
	v_lshlrev_b32_e32 v28, 16, v34
	v_and_b32_e32 v29, 0xffff0000, v34
	v_lshlrev_b32_e32 v30, 16, v35
	v_and_b32_e32 v31, 0xffff0000, v35
	v_pk_fma_f32 v[82:83], v[24:25], 0.5, v[28:29] op_sel_hi:[1,0,1]
	v_mul_f32_e32 v24, v81, v81
	v_mul_f32_e32 v25, v33, v33
	v_pk_fma_f32 v[34:35], v[26:27], 0.5, v[30:31] op_sel_hi:[1,0,1]
	v_fmac_f32_e32 v24, v80, v80
	v_fmac_f32_e32 v25, v32, v32
	v_add_f32_e32 v24, v24, v25
	v_mul_f32_e32 v25, v83, v83
	v_mul_f32_e32 v26, v35, v35
	v_fmac_f32_e32 v25, v82, v82
	v_fmac_f32_e32 v26, v34, v34
	v_add_f32_e32 v25, v25, v26
	v_add_f32_e32 v30, v24, v25
	global_load_dwordx4 v[24:27], v[98:99], off offset:256
	s_waitcnt vmcnt(0)
	v_lshlrev_b32_e32 v28, 16, v24
	v_and_b32_e32 v29, 0xffff0000, v24
	v_lshlrev_b32_e32 v24, 16, v25
	v_and_b32_e32 v25, 0xffff0000, v25
	v_pk_fma_f32 v[140:141], v[22:23], 0.5, v[24:25] op_sel_hi:[1,0,1]
	v_pk_fma_f32 v[142:143], v[20:21], 0.5, v[28:29] op_sel_hi:[1,0,1]
	v_lshlrev_b32_e32 v20, 16, v26
	v_and_b32_e32 v21, 0xffff0000, v26
	v_lshlrev_b32_e32 v22, 16, v27
	v_and_b32_e32 v23, 0xffff0000, v27
	v_pk_fma_f32 v[158:159], v[16:17], 0.5, v[20:21] op_sel_hi:[1,0,1]
	v_mul_f32_e32 v16, v143, v143
	v_mul_f32_e32 v17, v141, v141
	v_pk_fma_f32 v[156:157], v[18:19], 0.5, v[22:23] op_sel_hi:[1,0,1]
	v_fmac_f32_e32 v16, v142, v142
	v_fmac_f32_e32 v17, v140, v140
	v_add_f32_e32 v16, v16, v17
	v_mul_f32_e32 v17, v159, v159
	v_mul_f32_e32 v18, v157, v157
	v_fmac_f32_e32 v17, v158, v158
	v_fmac_f32_e32 v18, v156, v156
	v_add_f32_e32 v17, v17, v18
	v_add_f32_e32 v16, v16, v17
	v_add_f32_e32 v16, v30, v16
	v_mov_b32_e32 v17, v16
	s_nop 1
	v_permlane16_swap_b32_e32 v16, v17
	s_waitcnt lgkmcnt(0)
	v_add_f32_e32 v16, v16, v17
	v_mov_b32_e32 v17, v16
	s_nop 1
	v_permlane32_swap_b32_e32 v16, v17
	s_and_saveexec_b64 s[18:19], s[36:37]
	s_cbranch_execz .LBB0_1260
	s_waitcnt lgkmcnt(0)
	v_add_f32_e32 v16, v16, v17
	ds_write_b32 v165, v16 offset:2560
.LBB0_1260:
	s_or_b64 exec, exec, s[18:19]
	v_add_co_u32_e32 v16, vcc, 0x58000, v84
	v_lshl_add_u64 v[28:29], v[84:85], 0, s[80:81]
	s_waitcnt lgkmcnt(0)
	v_addc_co_u32_e32 v17, vcc, 0, v85, vcc
	global_load_dwordx4 v[16:19], v[16:17], off
	s_waitcnt vmcnt(0)
	v_lshlrev_b32_e32 v20, 16, v16
	v_and_b32_e32 v21, 0xffff0000, v16
	v_lshlrev_b32_e32 v16, 16, v17
	v_and_b32_e32 v17, 0xffff0000, v17
	v_pk_fma_f32 v[24:25], v[14:15], 0.5, v[16:17] op_sel_hi:[1,0,1]
	v_pk_fma_f32 v[26:27], v[12:13], 0.5, v[20:21] op_sel_hi:[1,0,1]
	v_lshlrev_b32_e32 v12, 16, v18
	v_and_b32_e32 v13, 0xffff0000, v18
	v_lshlrev_b32_e32 v14, 16, v19
	v_and_b32_e32 v15, 0xffff0000, v19
	v_pk_fma_f32 v[22:23], v[8:9], 0.5, v[12:13] op_sel_hi:[1,0,1]
	v_mul_f32_e32 v8, v27, v27
	v_mul_f32_e32 v9, v25, v25
	v_pk_fma_f32 v[20:21], v[10:11], 0.5, v[14:15] op_sel_hi:[1,0,1]
	v_fmac_f32_e32 v8, v26, v26
	v_fmac_f32_e32 v9, v24, v24
	v_add_f32_e32 v8, v8, v9
	v_mul_f32_e32 v9, v23, v23
	v_mul_f32_e32 v10, v21, v21
	v_fmac_f32_e32 v9, v22, v22
	v_fmac_f32_e32 v10, v20, v20
	v_add_f32_e32 v9, v9, v10
	v_add_f32_e32 v14, v8, v9
	global_load_dwordx4 v[8:11], v[28:29], off offset:256
	s_waitcnt vmcnt(0)
	v_lshlrev_b32_e32 v12, 16, v8
	v_and_b32_e32 v13, 0xffff0000, v8
	v_lshlrev_b32_e32 v8, 16, v9
	v_and_b32_e32 v9, 0xffff0000, v9
	v_pk_fma_f32 v[28:29], v[6:7], 0.5, v[8:9] op_sel_hi:[1,0,1]
	v_pk_fma_f32 v[30:31], v[4:5], 0.5, v[12:13] op_sel_hi:[1,0,1]
	v_lshlrev_b32_e32 v4, 16, v10
	v_and_b32_e32 v5, 0xffff0000, v10
	v_lshlrev_b32_e32 v6, 16, v11
	v_and_b32_e32 v7, 0xffff0000, v11
	v_pk_fma_f32 v[98:99], v[0:1], 0.5, v[4:5] op_sel_hi:[1,0,1]
	v_mul_f32_e32 v0, v31, v31
	v_mul_f32_e32 v1, v29, v29
	v_pk_fma_f32 v[84:85], v[2:3], 0.5, v[6:7] op_sel_hi:[1,0,1]
	v_fmac_f32_e32 v0, v30, v30
	v_fmac_f32_e32 v1, v28, v28
	v_add_f32_e32 v0, v0, v1
	v_mul_f32_e32 v1, v99, v99
	v_mul_f32_e32 v2, v85, v85
	v_fmac_f32_e32 v1, v98, v98
	v_fmac_f32_e32 v2, v84, v84
	v_add_f32_e32 v1, v1, v2
	v_add_f32_e32 v0, v0, v1
	v_add_f32_e32 v0, v14, v0
	v_mov_b32_e32 v1, v0
	s_nop 1
	v_permlane16_swap_b32_e32 v0, v1
	s_waitcnt lgkmcnt(0)
	v_add_f32_e32 v0, v0, v1
	v_mov_b32_e32 v1, v0
	s_nop 1
	v_permlane32_swap_b32_e32 v0, v1
	s_and_saveexec_b64 s[18:19], s[36:37]
	s_cbranch_execz .LBB0_1262
	s_waitcnt lgkmcnt(0)
	v_add_f32_e32 v0, v0, v1
	ds_write_b32 v165, v0 offset:2816
